# v34 + GEMM K loops without per-section s_setprio flips (both wave halves at priority 0)
# baseline (speedup 1.0000x reference)
; #define PG8_STAGE(bufoff, gbase, voff) do { _Pragma("unroll") for (int _i = 0; _i < 2; ++_i) \
;         __builtin_amdgcn_global_load_lds((const unsigned*)((const char*)(gbase) + (voff)[_i]), (LAS unsigned*)(lds + (bufoff) + ldsw + _i * 8192), 16, 0, 0); } while (0)
; #define PG8_LDA(dst, b, h) do { _Pragma("unroll") for (int m = 0; m < 4; ++m) _Pragma("unroll") for (int k = 0; k < 2; ++k) dst[m][k] = *(const LAS bf16x8*)(lds + PG8_SA(b, h) + aoff + m * 2048 + k * 1024); } while (0)
; #define PG8_LDB(dst, b, h) do { _Pragma("unroll") for (int n = 0; n < 2; ++n) _Pragma("unroll") for (int k = 0; k < 2; ++k) dst[n][k] = *(const LAS bf16x8*)(lds + PG8_SB(b, h) + boff + n * 2048 + k * 1024); } while (0)
; #define PG8_MMA(ai, bj, At, Bt) do { __builtin_amdgcn_s_setprio(1); _Pragma("unroll") for (int m = 0; m < 4; ++m) _Pragma("unroll") for (int n = 0; n < 2; ++n) _Pragma("unroll") for (int k = 0; k < 2; ++k) \
;         acc[ai][bj][m][n] = __builtin_amdgcn_mfma_f32_16x16x32_bf16(Bt[n][k], At[m][k], acc[ai][bj][m][n], 0, 0, 0); __builtin_amdgcn_s_setprio(0); } while (0)
; #define PG8_WAIT_V(n) asm volatile("s_waitcnt vmcnt(" #n ")" ::: "memory")
; #define PG8_WAIT_L(n) asm volatile("s_waitcnt lgkmcnt(" #n ")" ::: "memory")
; #define PG8_BAR __builtin_amdgcn_s_barrier()
; #define PG8_SCHED __builtin_amdgcn_sched_barrier(0)
; template <class Epi>
; __device__ __forceinline__ void gemm_phase(LAS unsigned char* lds, const Gemm g, const StaticOrder& S, const Epi& E, int wave_s) {
;     ...
;             PG8_WAIT_V(8); PG8_WAIT_L(0); PG8_BAR; PG8_MMA(0, 0, At, B0); PG8_MMA(0, 1, At, B1); PG8_BAR; PG8_SCHED;
;             PG8_LDA(At, 0, 1); PG8_STAGE(PG8_SB(0, 0), b2, voffB); PG8_STAGE(PG8_SB(0, 1), b2 + hstepB, voffB); PG8_STAGE(PG8_SA(0, 0), a2, voffA);
;             PG8_WAIT_V(8); PG8_WAIT_L(0); PG8_BAR; PG8_MMA(1, 0, At, B0); PG8_MMA(1, 1, At, B1); PG8_BAR; PG8_SCHED;
;             PG8_LDB(B0, 1, 0); PG8_LDB(B1, 1, 1); PG8_SCHED; PG8_LDA(At, 1, 0); PG8_STAGE(PG8_SA(0, 1), a2 + hstepA, voffA);
;             PG8_WAIT_V(8); PG8_WAIT_L(0); PG8_BAR; PG8_MMA(0, 0, At, B0); PG8_MMA(0, 1, At, B1); PG8_BAR; PG8_SCHED;
.Lpp_lead_5:
	s_waitcnt lgkmcnt(4)
	s_barrier
	s_waitcnt lgkmcnt(4)
	v_mfma_f32_16x16x32_bf16 v[126:129], v[150:153], v[190:193], v[126:129]
	v_mfma_f32_16x16x32_bf16 v[122:125], v[158:161], v[190:193], v[122:125]
	v_mfma_f32_16x16x32_bf16 v[118:121], v[150:153], v[198:201], v[118:121]
	v_mfma_f32_16x16x32_bf16 v[114:117], v[158:161], v[198:201], v[114:117]
	v_mfma_f32_16x16x32_bf16 v[110:113], v[150:153], v[206:209], v[110:113]
	v_mfma_f32_16x16x32_bf16 v[106:109], v[158:161], v[206:209], v[106:109]
	v_mfma_f32_16x16x32_bf16 v[102:105], v[150:153], v[214:217], v[102:105]
	v_mfma_f32_16x16x32_bf16 v[98:101], v[158:161], v[214:217], v[98:101]
	v_mfma_f32_16x16x32_bf16 v[126:129], v[154:157], v[194:197], v[126:129]
	v_mfma_f32_16x16x32_bf16 v[122:125], v[162:165], v[194:197], v[122:125]
	v_mfma_f32_16x16x32_bf16 v[118:121], v[154:157], v[202:205], v[118:121]
	v_mfma_f32_16x16x32_bf16 v[114:117], v[162:165], v[202:205], v[114:117]
	v_mfma_f32_16x16x32_bf16 v[110:113], v[154:157], v[210:213], v[110:113]
	v_mfma_f32_16x16x32_bf16 v[106:109], v[162:165], v[210:213], v[106:109]
	v_mfma_f32_16x16x32_bf16 v[102:105], v[154:157], v[218:221], v[102:105]
	v_mfma_f32_16x16x32_bf16 v[98:101], v[162:165], v[218:221], v[98:101]
	s_waitcnt lgkmcnt(0)
	v_mfma_f32_16x16x32_bf16 v[62:65], v[166:169], v[190:193], v[62:65]
	v_mfma_f32_16x16x32_bf16 v[58:61], v[182:185], v[190:193], v[58:61]
	v_mfma_f32_16x16x32_bf16 v[54:57], v[166:169], v[198:201], v[54:57]
	v_mfma_f32_16x16x32_bf16 v[50:53], v[182:185], v[198:201], v[50:53]
	v_mfma_f32_16x16x32_bf16 v[46:49], v[166:169], v[206:209], v[46:49]
	v_mfma_f32_16x16x32_bf16 v[42:45], v[182:185], v[206:209], v[42:45]
	v_mfma_f32_16x16x32_bf16 v[38:41], v[166:169], v[214:217], v[38:41]
	v_mfma_f32_16x16x32_bf16 v[34:37], v[182:185], v[214:217], v[34:37]
	v_mfma_f32_16x16x32_bf16 v[62:65], v[178:181], v[194:197], v[62:65]
	v_mfma_f32_16x16x32_bf16 v[58:61], v[186:189], v[194:197], v[58:61]
	v_mfma_f32_16x16x32_bf16 v[54:57], v[178:181], v[202:205], v[54:57]
	v_mfma_f32_16x16x32_bf16 v[50:53], v[186:189], v[202:205], v[50:53]
	v_mfma_f32_16x16x32_bf16 v[46:49], v[178:181], v[210:213], v[46:49]
	v_mfma_f32_16x16x32_bf16 v[42:45], v[186:189], v[210:213], v[42:45]
	v_mfma_f32_16x16x32_bf16 v[38:41], v[178:181], v[218:221], v[38:41]
	v_mfma_f32_16x16x32_bf16 v[34:37], v[186:189], v[218:221], v[34:37]
	s_barrier
	s_add_i32 s49, s49, s18
	v_lshl_add_u64 v[170:171], s[26:27], 0, v[134:135]
	s_mov_b32 m0, s49
	ds_read_b128 v[190:193], v149 offset:16384
	ds_read_b128 v[194:197], v149 offset:17408
	ds_read_b128 v[198:201], v149 offset:18432
	ds_read_b128 v[202:205], v149 offset:19456
	ds_read_b128 v[206:209], v149 offset:20480
	ds_read_b128 v[210:213], v149 offset:21504
	ds_read_b128 v[214:217], v149 offset:22528
	ds_read_b128 v[218:221], v149 offset:23552
	global_load_lds_dwordx4 v[170:171], off
	s_add_i32 m0, s49, 0x2000
	s_add_u32 s50, s26, 0x40000
	v_lshl_add_u64 v[172:173], s[26:27], 0, v[130:131]
	s_addc_u32 s51, s27, 0
	s_add_i32 s49, s52, s18
	global_load_lds_dwordx4 v[172:173], off
	v_lshl_add_u64 v[174:175], s[50:51], 0, v[134:135]
	s_mov_b32 m0, s49
	v_lshl_add_u64 v[176:177], s[30:31], 0, v[132:133]
	global_load_lds_dwordx4 v[174:175], off
	v_lshl_add_u64 v[174:175], s[50:51], 0, v[130:131]
	s_add_i32 m0, s49, 0x2000
	s_nop 0
	global_load_lds_dwordx4 v[174:175], off
	v_lshl_add_u64 v[174:175], s[30:31], 0, v[136:137]
	s_mov_b32 m0, s20
	s_nop 0
	global_load_lds_dwordx4 v[174:175], off
	s_mov_b32 m0, s25
	s_nop 0
	global_load_lds_dwordx4 v[176:177], off
	s_waitcnt vmcnt(8)
	s_waitcnt lgkmcnt(0)
	s_barrier
	s_waitcnt lgkmcnt(0)
	v_mfma_f32_16x16x32_bf16 v[94:97], v[150:153], v[190:193], v[94:97]
	v_mfma_f32_16x16x32_bf16 v[90:93], v[158:161], v[190:193], v[90:93]
	v_mfma_f32_16x16x32_bf16 v[86:89], v[150:153], v[198:201], v[86:89]
	v_mfma_f32_16x16x32_bf16 v[82:85], v[158:161], v[198:201], v[82:85]
	v_mfma_f32_16x16x32_bf16 v[78:81], v[150:153], v[206:209], v[78:81]
	v_mfma_f32_16x16x32_bf16 v[74:77], v[158:161], v[206:209], v[74:77]
	v_mfma_f32_16x16x32_bf16 v[70:73], v[150:153], v[214:217], v[70:73]
	v_mfma_f32_16x16x32_bf16 v[66:69], v[158:161], v[214:217], v[66:69]
	v_mfma_f32_16x16x32_bf16 v[94:97], v[154:157], v[194:197], v[94:97]
	v_mfma_f32_16x16x32_bf16 v[90:93], v[162:165], v[194:197], v[90:93]
	v_mfma_f32_16x16x32_bf16 v[86:89], v[154:157], v[202:205], v[86:89]
	v_mfma_f32_16x16x32_bf16 v[82:85], v[162:165], v[202:205], v[82:85]
	v_mfma_f32_16x16x32_bf16 v[78:81], v[154:157], v[210:213], v[78:81]
	v_mfma_f32_16x16x32_bf16 v[74:77], v[162:165], v[210:213], v[74:77]
	v_mfma_f32_16x16x32_bf16 v[70:73], v[154:157], v[218:221], v[70:73]
	v_mfma_f32_16x16x32_bf16 v[66:69], v[162:165], v[218:221], v[66:69]
	v_mfma_f32_16x16x32_bf16 v[30:33], v[166:169], v[190:193], v[30:33]
	v_mfma_f32_16x16x32_bf16 v[26:29], v[182:185], v[190:193], v[26:29]
	v_mfma_f32_16x16x32_bf16 v[22:25], v[166:169], v[198:201], v[22:25]
	v_mfma_f32_16x16x32_bf16 v[18:21], v[182:185], v[198:201], v[18:21]
	v_mfma_f32_16x16x32_bf16 v[14:17], v[166:169], v[206:209], v[14:17]
	v_mfma_f32_16x16x32_bf16 v[8:11], v[182:185], v[206:209], v[8:11]
	v_mfma_f32_16x16x32_bf16 v[4:7], v[166:169], v[214:217], v[4:7]
	v_mfma_f32_16x16x32_bf16 v[0:3], v[182:185], v[214:217], v[0:3]
	v_mfma_f32_16x16x32_bf16 v[30:33], v[178:181], v[194:197], v[30:33]
	v_mfma_f32_16x16x32_bf16 v[26:29], v[186:189], v[194:197], v[26:29]
	v_mfma_f32_16x16x32_bf16 v[22:25], v[178:181], v[202:205], v[22:25]
	v_mfma_f32_16x16x32_bf16 v[18:21], v[186:189], v[202:205], v[18:21]
	v_mfma_f32_16x16x32_bf16 v[14:17], v[178:181], v[210:213], v[14:17]
	v_mfma_f32_16x16x32_bf16 v[8:11], v[186:189], v[210:213], v[8:11]
	v_mfma_f32_16x16x32_bf16 v[4:7], v[178:181], v[218:221], v[4:7]
	v_mfma_f32_16x16x32_bf16 v[0:3], v[186:189], v[218:221], v[0:3]
	s_barrier
	s_add_i32 s49, 0, 0x18000
	v_add_u32_e32 v12, s49, v148
	s_add_i32 s50, 0, 0x1c000
	ds_read_b128 v[150:153], v12
	ds_read_b128 v[154:157], v12 offset:1024
	ds_read_b128 v[158:161], v12 offset:2048
	ds_read_b128 v[162:165], v12 offset:3072
	v_add_u32_e32 v12, s50, v148
	ds_read_b128 v[190:193], v149 offset:32768
	ds_read_b128 v[194:197], v149 offset:33792
	ds_read_b128 v[198:201], v149 offset:34816
	ds_read_b128 v[202:205], v149 offset:35840
	ds_read_b128 v[206:209], v149 offset:36864
	ds_read_b128 v[210:213], v149 offset:37888
	ds_read_b128 v[214:217], v149 offset:38912
	ds_read_b128 v[218:221], v149 offset:39936
	ds_read_b128 v[166:169], v12
	ds_read_b128 v[178:181], v12 offset:1024
	ds_read_b128 v[182:185], v12 offset:2048
	ds_read_b128 v[186:189], v12 offset:3072
	s_add_u32 s30, s30, 0x40000
	s_addc_u32 s31, s31, 0
	s_mov_b32 m0, s29
	v_lshl_add_u64 v[222:223], s[30:31], 0, v[136:137]
	global_load_lds_dwordx4 v[222:223], off
	v_lshl_add_u64 v[222:223], s[30:31], 0, v[132:133]
	s_mov_b32 m0, s35
	s_nop 0
	global_load_lds_dwordx4 v[222:223], off
	s_waitcnt vmcnt(8)
	s_cmp_lg_u64 s[8:9], 0
	s_cbranch_scc1 .Lpp_lead_6
	s_waitcnt lgkmcnt(0)
; #define PG8_STAGE(bufoff, gbase, voff) do { _Pragma("unroll") for (int _i = 0; _i < 2; ++_i) \
;         __builtin_amdgcn_global_load_lds((const unsigned*)((const char*)(gbase) + (voff)[_i]), (LAS unsigned*)(lds + (bufoff) + ldsw + _i * 8192), 16, 0, 0); } while (0)
; #define PG8_LDA(dst, b, h) do { _Pragma("unroll") for (int m = 0; m < 4; ++m) _Pragma("unroll") for (int k = 0; k < 2; ++k) dst[m][k] = *(const LAS bf16x8*)(lds + PG8_SA(b, h) + aoff + m * 2048 + k * 1024); } while (0)
; #define PG8_MMA(ai, bj, At, Bt) do { __builtin_amdgcn_s_setprio(1); _Pragma("unroll") for (int m = 0; m < 4; ++m) _Pragma("unroll") for (int n = 0; n < 2; ++n) _Pragma("unroll") for (int k = 0; k < 2; ++k) \
;         acc[ai][bj][m][n] = __builtin_amdgcn_mfma_f32_16x16x32_bf16(Bt[n][k], At[m][k], acc[ai][bj][m][n], 0, 0, 0); __builtin_amdgcn_s_setprio(0); } while (0)
; #define PG8_WAIT_V(n) asm volatile("s_waitcnt vmcnt(" #n ")" ::: "memory")
; #define PG8_WAIT_L(n) asm volatile("s_waitcnt lgkmcnt(" #n ")" ::: "memory")
; #define PG8_BAR __builtin_amdgcn_s_barrier()
; #define PG8_SCHED __builtin_amdgcn_sched_barrier(0)
; template <class Epi>
; __device__ __forceinline__ void gemm_phase(LAS unsigned char* lds, const Gemm g, const StaticOrder& S, const Epi& E, int wave_s) {
;     ...
;             PG8_WAIT_V(8); PG8_WAIT_L(0); PG8_BAR; PG8_MMA(0, 0, At, B0); PG8_MMA(0, 1, At, B1); PG8_BAR; PG8_SCHED;
;             PG8_LDA(At, 1, 1); PG8_STAGE(PG8_SB(1, 0), b3, voffB); PG8_STAGE(PG8_SB(1, 1), b3 + hstepB, voffB); PG8_STAGE(PG8_SA(1, 0), a3, voffA);
;             PG8_WAIT_V(8); PG8_WAIT_L(0); PG8_BAR; PG8_MMA(1, 0, At, B0); PG8_MMA(1, 1, At, B1); PG8_BAR; PG8_SCHED;
;         }
;         if (wr == 0) PG8_BAR;
.Lpp_lead_6:
	s_waitcnt lgkmcnt(4)
	s_barrier
	s_waitcnt lgkmcnt(4)
	v_mfma_f32_16x16x32_bf16 v[126:129], v[150:153], v[190:193], v[126:129]
	v_mfma_f32_16x16x32_bf16 v[122:125], v[158:161], v[190:193], v[122:125]
	v_mfma_f32_16x16x32_bf16 v[118:121], v[150:153], v[198:201], v[118:121]
	v_mfma_f32_16x16x32_bf16 v[114:117], v[158:161], v[198:201], v[114:117]
	v_mfma_f32_16x16x32_bf16 v[110:113], v[150:153], v[206:209], v[110:113]
	v_mfma_f32_16x16x32_bf16 v[106:109], v[158:161], v[206:209], v[106:109]
	v_mfma_f32_16x16x32_bf16 v[102:105], v[150:153], v[214:217], v[102:105]
	v_mfma_f32_16x16x32_bf16 v[98:101], v[158:161], v[214:217], v[98:101]
	v_mfma_f32_16x16x32_bf16 v[126:129], v[154:157], v[194:197], v[126:129]
	v_mfma_f32_16x16x32_bf16 v[122:125], v[162:165], v[194:197], v[122:125]
	v_mfma_f32_16x16x32_bf16 v[118:121], v[154:157], v[202:205], v[118:121]
	v_mfma_f32_16x16x32_bf16 v[114:117], v[162:165], v[202:205], v[114:117]
	v_mfma_f32_16x16x32_bf16 v[110:113], v[154:157], v[210:213], v[110:113]
	v_mfma_f32_16x16x32_bf16 v[106:109], v[162:165], v[210:213], v[106:109]
	v_mfma_f32_16x16x32_bf16 v[102:105], v[154:157], v[218:221], v[102:105]
	v_mfma_f32_16x16x32_bf16 v[98:101], v[162:165], v[218:221], v[98:101]
	s_waitcnt lgkmcnt(0)
	v_mfma_f32_16x16x32_bf16 v[62:65], v[166:169], v[190:193], v[62:65]
	v_mfma_f32_16x16x32_bf16 v[58:61], v[182:185], v[190:193], v[58:61]
	v_mfma_f32_16x16x32_bf16 v[54:57], v[166:169], v[198:201], v[54:57]
	v_mfma_f32_16x16x32_bf16 v[50:53], v[182:185], v[198:201], v[50:53]
	v_mfma_f32_16x16x32_bf16 v[46:49], v[166:169], v[206:209], v[46:49]
	v_mfma_f32_16x16x32_bf16 v[42:45], v[182:185], v[206:209], v[42:45]
	v_mfma_f32_16x16x32_bf16 v[38:41], v[166:169], v[214:217], v[38:41]
	v_mfma_f32_16x16x32_bf16 v[34:37], v[182:185], v[214:217], v[34:37]
	v_mfma_f32_16x16x32_bf16 v[62:65], v[178:181], v[194:197], v[62:65]
	v_mfma_f32_16x16x32_bf16 v[58:61], v[186:189], v[194:197], v[58:61]
	v_mfma_f32_16x16x32_bf16 v[54:57], v[178:181], v[202:205], v[54:57]
	v_mfma_f32_16x16x32_bf16 v[50:53], v[186:189], v[202:205], v[50:53]
	v_mfma_f32_16x16x32_bf16 v[46:49], v[178:181], v[210:213], v[46:49]
	v_mfma_f32_16x16x32_bf16 v[42:45], v[186:189], v[210:213], v[42:45]
	v_mfma_f32_16x16x32_bf16 v[38:41], v[178:181], v[218:221], v[38:41]
	v_mfma_f32_16x16x32_bf16 v[34:37], v[186:189], v[218:221], v[34:37]
	s_barrier
	s_add_i32 s30, s49, s18
	v_lshl_add_u64 v[170:171], v[170:171], 0, s[84:85]
	s_mov_b32 m0, s30
	ds_read_b128 v[190:193], v149 offset:49152
	ds_read_b128 v[194:197], v149 offset:50176
	ds_read_b128 v[198:201], v149 offset:51200
	ds_read_b128 v[202:205], v149 offset:52224
	ds_read_b128 v[206:209], v149 offset:53248
	ds_read_b128 v[210:213], v149 offset:54272
	ds_read_b128 v[214:217], v149 offset:55296
	ds_read_b128 v[218:221], v149 offset:56320
	global_load_lds_dwordx4 v[170:171], off
	s_add_i32 m0, s30, 0x2000
	s_add_u32 s26, s26, 0x40080
	v_lshl_add_u64 v[170:171], v[172:173], 0, s[84:85]
	s_addc_u32 s27, s27, 0
	s_add_i32 s30, s50, s18
	global_load_lds_dwordx4 v[170:171], off
	v_lshl_add_u64 v[170:171], s[26:27], 0, v[134:135]
	s_mov_b32 m0, s30
	s_nop 0
	global_load_lds_dwordx4 v[170:171], off
	v_lshl_add_u64 v[170:171], s[26:27], 0, v[130:131]
	s_add_i32 m0, s30, 0x2000
	s_nop 0
	global_load_lds_dwordx4 v[170:171], off
	v_lshl_add_u64 v[170:171], v[174:175], 0, s[84:85]
	s_mov_b32 m0, s37
	s_nop 0
	global_load_lds_dwordx4 v[170:171], off
	v_lshl_add_u64 v[170:171], v[176:177], 0, s[84:85]
	s_mov_b32 m0, s40
	s_nop 0
	global_load_lds_dwordx4 v[170:171], off
	s_waitcnt vmcnt(8)
	s_waitcnt lgkmcnt(0)
	s_barrier
	s_waitcnt lgkmcnt(0)
	v_mfma_f32_16x16x32_bf16 v[94:97], v[150:153], v[190:193], v[94:97]
	v_mfma_f32_16x16x32_bf16 v[90:93], v[158:161], v[190:193], v[90:93]
	v_mfma_f32_16x16x32_bf16 v[86:89], v[150:153], v[198:201], v[86:89]
	v_mfma_f32_16x16x32_bf16 v[82:85], v[158:161], v[198:201], v[82:85]
	v_mfma_f32_16x16x32_bf16 v[78:81], v[150:153], v[206:209], v[78:81]
	v_mfma_f32_16x16x32_bf16 v[74:77], v[158:161], v[206:209], v[74:77]
	v_mfma_f32_16x16x32_bf16 v[70:73], v[150:153], v[214:217], v[70:73]
	v_mfma_f32_16x16x32_bf16 v[66:69], v[158:161], v[214:217], v[66:69]
	v_mfma_f32_16x16x32_bf16 v[94:97], v[154:157], v[194:197], v[94:97]
	v_mfma_f32_16x16x32_bf16 v[90:93], v[162:165], v[194:197], v[90:93]
	v_mfma_f32_16x16x32_bf16 v[86:89], v[154:157], v[202:205], v[86:89]
	v_mfma_f32_16x16x32_bf16 v[82:85], v[162:165], v[202:205], v[82:85]
	v_mfma_f32_16x16x32_bf16 v[78:81], v[154:157], v[210:213], v[78:81]
	v_mfma_f32_16x16x32_bf16 v[74:77], v[162:165], v[210:213], v[74:77]
	v_mfma_f32_16x16x32_bf16 v[70:73], v[154:157], v[218:221], v[70:73]
	v_mfma_f32_16x16x32_bf16 v[66:69], v[162:165], v[218:221], v[66:69]
	v_mfma_f32_16x16x32_bf16 v[30:33], v[166:169], v[190:193], v[30:33]
	v_mfma_f32_16x16x32_bf16 v[26:29], v[182:185], v[190:193], v[26:29]
	v_mfma_f32_16x16x32_bf16 v[22:25], v[166:169], v[198:201], v[22:25]
	v_mfma_f32_16x16x32_bf16 v[18:21], v[182:185], v[198:201], v[18:21]
	v_mfma_f32_16x16x32_bf16 v[14:17], v[166:169], v[206:209], v[14:17]
	v_mfma_f32_16x16x32_bf16 v[8:11], v[182:185], v[206:209], v[8:11]
	v_mfma_f32_16x16x32_bf16 v[4:7], v[166:169], v[214:217], v[4:7]
	v_mfma_f32_16x16x32_bf16 v[0:3], v[182:185], v[214:217], v[0:3]
	v_mfma_f32_16x16x32_bf16 v[30:33], v[178:181], v[194:197], v[30:33]
	v_mfma_f32_16x16x32_bf16 v[26:29], v[186:189], v[194:197], v[26:29]
	v_mfma_f32_16x16x32_bf16 v[22:25], v[178:181], v[202:205], v[22:25]
	v_mfma_f32_16x16x32_bf16 v[18:21], v[186:189], v[202:205], v[18:21]
	v_mfma_f32_16x16x32_bf16 v[14:17], v[178:181], v[210:213], v[14:17]
	v_mfma_f32_16x16x32_bf16 v[8:11], v[186:189], v[210:213], v[8:11]
	v_mfma_f32_16x16x32_bf16 v[4:7], v[178:181], v[218:221], v[4:7]
	v_mfma_f32_16x16x32_bf16 v[0:3], v[186:189], v[218:221], v[0:3]
	s_barrier
	s_add_i32 s48, s48, 2
	s_add_u32 s4, s4, 0x100
	s_addc_u32 s5, s5, 0
	s_add_u32 s46, s46, 0x100
	s_addc_u32 s47, s47, 0
	s_cmp_gt_u32 s48, 13
	s_cbranch_scc0 .LBB0_215
	s_and_b64 vcc, exec, s[8:9]
	s_cbranch_vccz .LBB0_218
	s_barrier

; #define PG8_STAGE(bufoff, gbase, voff) do { _Pragma("unroll") for (int _i = 0; _i < 2; ++_i) \
;         __builtin_amdgcn_global_load_lds((const unsigned*)((const char*)(gbase) + (voff)[_i]), (LAS unsigned*)(lds + (bufoff) + ldsw + _i * 8192), 16, 0, 0); } while (0)
; #define PG8_LDA(dst, b, h) do { _Pragma("unroll") for (int m = 0; m < 4; ++m) _Pragma("unroll") for (int k = 0; k < 2; ++k) dst[m][k] = *(const LAS bf16x8*)(lds + PG8_SA(b, h) + aoff + m * 2048 + k * 1024); } while (0)
; #define PG8_LDB(dst, b, h) do { _Pragma("unroll") for (int n = 0; n < 2; ++n) _Pragma("unroll") for (int k = 0; k < 2; ++k) dst[n][k] = *(const LAS bf16x8*)(lds + PG8_SB(b, h) + boff + n * 2048 + k * 1024); } while (0)
; #define PG8_MMA(ai, bj, At, Bt) do { __builtin_amdgcn_s_setprio(1); _Pragma("unroll") for (int m = 0; m < 4; ++m) _Pragma("unroll") for (int n = 0; n < 2; ++n) _Pragma("unroll") for (int k = 0; k < 2; ++k) \
;         acc[ai][bj][m][n] = __builtin_amdgcn_mfma_f32_16x16x32_bf16(Bt[n][k], At[m][k], acc[ai][bj][m][n], 0, 0, 0); __builtin_amdgcn_s_setprio(0); } while (0)
; #define PG8_WAIT_V(n) asm volatile("s_waitcnt vmcnt(" #n ")" ::: "memory")
; #define PG8_WAIT_L(n) asm volatile("s_waitcnt lgkmcnt(" #n ")" ::: "memory")
; #define PG8_BAR __builtin_amdgcn_s_barrier()
; #define PG8_SCHED __builtin_amdgcn_sched_barrier(0)
; template <class Epi>
; __device__ __forceinline__ void gemm_phase(LAS unsigned char* lds, const Gemm g, const StaticOrder& S, const Epi& E, int wave_s) {
;     ...
;             PG8_WAIT_V(8); PG8_WAIT_L(0); PG8_BAR; PG8_MMA(0, 0, At, B0); PG8_MMA(0, 1, At, B1); PG8_BAR; PG8_SCHED;
;             PG8_LDA(At, 0, 1); PG8_STAGE(PG8_SB(0, 0), b2, voffB); PG8_STAGE(PG8_SB(0, 1), b2 + hstepB, voffB); PG8_STAGE(PG8_SA(0, 0), a2, voffA);
;             PG8_WAIT_V(8); PG8_WAIT_L(0); PG8_BAR; PG8_MMA(1, 0, At, B0); PG8_MMA(1, 1, At, B1); PG8_BAR; PG8_SCHED;
;             PG8_LDB(B0, 1, 0); PG8_LDB(B1, 1, 1); PG8_SCHED; PG8_LDA(At, 1, 0); PG8_STAGE(PG8_SA(0, 1), a2 + hstepA, voffA);
;             PG8_WAIT_V(8); PG8_WAIT_L(0); PG8_BAR; PG8_MMA(0, 0, At, B0); PG8_MMA(0, 1, At, B1); PG8_BAR; PG8_SCHED;
.Lpp_lead_7:
	s_waitcnt lgkmcnt(4)
	s_barrier
	s_waitcnt lgkmcnt(4)
	v_mfma_f32_16x16x32_bf16 v[126:129], v[130:133], v[188:191], v[126:129]
	v_mfma_f32_16x16x32_bf16 v[122:125], v[138:141], v[188:191], v[122:125]
	v_mfma_f32_16x16x32_bf16 v[118:121], v[130:133], v[196:199], v[118:121]
	v_mfma_f32_16x16x32_bf16 v[114:117], v[138:141], v[196:199], v[114:117]
	v_mfma_f32_16x16x32_bf16 v[110:113], v[130:133], v[204:207], v[110:113]
	v_mfma_f32_16x16x32_bf16 v[106:109], v[138:141], v[204:207], v[106:109]
	v_mfma_f32_16x16x32_bf16 v[102:105], v[130:133], v[212:215], v[102:105]
	v_mfma_f32_16x16x32_bf16 v[98:101], v[138:141], v[212:215], v[98:101]
	v_mfma_f32_16x16x32_bf16 v[126:129], v[134:137], v[192:195], v[126:129]
	v_mfma_f32_16x16x32_bf16 v[122:125], v[142:145], v[192:195], v[122:125]
	v_mfma_f32_16x16x32_bf16 v[118:121], v[134:137], v[200:203], v[118:121]
	v_mfma_f32_16x16x32_bf16 v[114:117], v[142:145], v[200:203], v[114:117]
	v_mfma_f32_16x16x32_bf16 v[110:113], v[134:137], v[208:211], v[110:113]
	v_mfma_f32_16x16x32_bf16 v[106:109], v[142:145], v[208:211], v[106:109]
	v_mfma_f32_16x16x32_bf16 v[102:105], v[134:137], v[216:219], v[102:105]
	v_mfma_f32_16x16x32_bf16 v[98:101], v[142:145], v[216:219], v[98:101]
	s_waitcnt lgkmcnt(0)
	v_mfma_f32_16x16x32_bf16 v[62:65], v[146:149], v[188:191], v[62:65]
	v_mfma_f32_16x16x32_bf16 v[58:61], v[168:171], v[188:191], v[58:61]
	v_mfma_f32_16x16x32_bf16 v[54:57], v[146:149], v[196:199], v[54:57]
	v_mfma_f32_16x16x32_bf16 v[50:53], v[168:171], v[196:199], v[50:53]
	v_mfma_f32_16x16x32_bf16 v[46:49], v[146:149], v[204:207], v[46:49]
	v_mfma_f32_16x16x32_bf16 v[42:45], v[168:171], v[204:207], v[42:45]
	v_mfma_f32_16x16x32_bf16 v[38:41], v[146:149], v[212:215], v[38:41]
	v_mfma_f32_16x16x32_bf16 v[34:37], v[168:171], v[212:215], v[34:37]
	v_mfma_f32_16x16x32_bf16 v[62:65], v[150:153], v[192:195], v[62:65]
	v_mfma_f32_16x16x32_bf16 v[58:61], v[184:187], v[192:195], v[58:61]
	v_mfma_f32_16x16x32_bf16 v[54:57], v[150:153], v[200:203], v[54:57]
	v_mfma_f32_16x16x32_bf16 v[50:53], v[184:187], v[200:203], v[50:53]
	v_mfma_f32_16x16x32_bf16 v[46:49], v[150:153], v[208:211], v[46:49]
	v_mfma_f32_16x16x32_bf16 v[42:45], v[184:187], v[208:211], v[42:45]
	v_mfma_f32_16x16x32_bf16 v[38:41], v[150:153], v[216:219], v[38:41]
	v_mfma_f32_16x16x32_bf16 v[34:37], v[184:187], v[216:219], v[34:37]
	s_barrier
	s_add_i32 s22, s51, s25
	v_lshl_add_u64 v[172:173], s[26:27], 0, v[158:159]
	s_mov_b32 m0, s22
	ds_read_b128 v[188:191], v167 offset:16384
	ds_read_b128 v[192:195], v167 offset:17408
	ds_read_b128 v[196:199], v167 offset:18432
	ds_read_b128 v[200:203], v167 offset:19456
	ds_read_b128 v[204:207], v167 offset:20480
	ds_read_b128 v[208:211], v167 offset:21504
	ds_read_b128 v[212:215], v167 offset:22528
	ds_read_b128 v[216:219], v167 offset:23552
	global_load_lds_dwordx4 v[172:173], off
	s_add_i32 m0, s22, 0x2000
	s_add_u32 s22, s26, 0x18000
	v_lshl_add_u64 v[174:175], s[26:27], 0, v[154:155]
	s_addc_u32 s23, s27, 0
	s_add_i32 s51, s52, s25
	global_load_lds_dwordx4 v[174:175], off
	v_lshl_add_u64 v[176:177], s[22:23], 0, v[158:159]
	s_mov_b32 m0, s51
	v_lshl_add_u64 v[220:221], s[30:31], 0, v[156:157]
	global_load_lds_dwordx4 v[176:177], off
	v_lshl_add_u64 v[176:177], s[22:23], 0, v[154:155]
	s_add_i32 m0, s51, 0x2000
	s_nop 0
	global_load_lds_dwordx4 v[176:177], off
	v_lshl_add_u64 v[176:177], s[30:31], 0, v[160:161]
	s_mov_b32 m0, s29
	s_nop 0
	global_load_lds_dwordx4 v[176:177], off
	s_mov_b32 m0, s35
	s_nop 0
	global_load_lds_dwordx4 v[220:221], off
	s_waitcnt vmcnt(8)
	s_waitcnt lgkmcnt(0)
	s_barrier
	s_waitcnt lgkmcnt(0)
	v_mfma_f32_16x16x32_bf16 v[94:97], v[130:133], v[188:191], v[94:97]
	v_mfma_f32_16x16x32_bf16 v[90:93], v[138:141], v[188:191], v[90:93]
	v_mfma_f32_16x16x32_bf16 v[86:89], v[130:133], v[196:199], v[86:89]
	v_mfma_f32_16x16x32_bf16 v[82:85], v[138:141], v[196:199], v[82:85]
	v_mfma_f32_16x16x32_bf16 v[78:81], v[130:133], v[204:207], v[78:81]
	v_mfma_f32_16x16x32_bf16 v[74:77], v[138:141], v[204:207], v[74:77]
	v_mfma_f32_16x16x32_bf16 v[70:73], v[130:133], v[212:215], v[70:73]
	v_mfma_f32_16x16x32_bf16 v[66:69], v[138:141], v[212:215], v[66:69]
	v_mfma_f32_16x16x32_bf16 v[94:97], v[134:137], v[192:195], v[94:97]
	v_mfma_f32_16x16x32_bf16 v[90:93], v[142:145], v[192:195], v[90:93]
	v_mfma_f32_16x16x32_bf16 v[86:89], v[134:137], v[200:203], v[86:89]
	v_mfma_f32_16x16x32_bf16 v[82:85], v[142:145], v[200:203], v[82:85]
	v_mfma_f32_16x16x32_bf16 v[78:81], v[134:137], v[208:211], v[78:81]
	v_mfma_f32_16x16x32_bf16 v[74:77], v[142:145], v[208:211], v[74:77]
	v_mfma_f32_16x16x32_bf16 v[70:73], v[134:137], v[216:219], v[70:73]
	v_mfma_f32_16x16x32_bf16 v[66:69], v[142:145], v[216:219], v[66:69]
	v_mfma_f32_16x16x32_bf16 v[30:33], v[146:149], v[188:191], v[30:33]
	v_mfma_f32_16x16x32_bf16 v[26:29], v[168:171], v[188:191], v[26:29]
	v_mfma_f32_16x16x32_bf16 v[22:25], v[146:149], v[196:199], v[22:25]
	v_mfma_f32_16x16x32_bf16 v[18:21], v[168:171], v[196:199], v[18:21]
	v_mfma_f32_16x16x32_bf16 v[14:17], v[146:149], v[204:207], v[14:17]
	v_mfma_f32_16x16x32_bf16 v[8:11], v[168:171], v[204:207], v[8:11]
	v_mfma_f32_16x16x32_bf16 v[4:7], v[146:149], v[212:215], v[4:7]
	v_mfma_f32_16x16x32_bf16 v[0:3], v[168:171], v[212:215], v[0:3]
	v_mfma_f32_16x16x32_bf16 v[30:33], v[150:153], v[192:195], v[30:33]
	v_mfma_f32_16x16x32_bf16 v[26:29], v[184:187], v[192:195], v[26:29]
	v_mfma_f32_16x16x32_bf16 v[22:25], v[150:153], v[200:203], v[22:25]
	v_mfma_f32_16x16x32_bf16 v[18:21], v[184:187], v[200:203], v[18:21]
	v_mfma_f32_16x16x32_bf16 v[14:17], v[150:153], v[208:211], v[14:17]
	v_mfma_f32_16x16x32_bf16 v[8:11], v[184:187], v[208:211], v[8:11]
	v_mfma_f32_16x16x32_bf16 v[4:7], v[150:153], v[216:219], v[4:7]
	v_mfma_f32_16x16x32_bf16 v[0:3], v[184:187], v[216:219], v[0:3]
	s_barrier
	s_add_i32 s51, 0, 0x18000
	v_add_u32_e32 v12, s51, v166
	s_add_i32 s52, 0, 0x1c000
	ds_read_b128 v[130:133], v12
	ds_read_b128 v[134:137], v12 offset:1024
	ds_read_b128 v[138:141], v12 offset:2048
	ds_read_b128 v[142:145], v12 offset:3072
	v_add_u32_e32 v12, s52, v166
	ds_read_b128 v[188:191], v167 offset:32768
	ds_read_b128 v[192:195], v167 offset:33792
	ds_read_b128 v[196:199], v167 offset:34816
	ds_read_b128 v[200:203], v167 offset:35840
	ds_read_b128 v[204:207], v167 offset:36864
	ds_read_b128 v[208:211], v167 offset:37888
	ds_read_b128 v[212:215], v167 offset:38912
	ds_read_b128 v[216:219], v167 offset:39936
	ds_read_b128 v[146:149], v12
	ds_read_b128 v[150:153], v12 offset:1024
	ds_read_b128 v[168:171], v12 offset:2048
	ds_read_b128 v[184:187], v12 offset:3072
	s_add_u32 s22, s30, 0xc0000
	s_addc_u32 s23, s31, 0
	s_mov_b32 m0, s36
	v_lshl_add_u64 v[222:223], s[22:23], 0, v[160:161]
	global_load_lds_dwordx4 v[222:223], off
	v_lshl_add_u64 v[222:223], s[22:23], 0, v[156:157]
	s_mov_b32 m0, s37
	s_nop 0
	global_load_lds_dwordx4 v[222:223], off
	s_waitcnt vmcnt(8)
	s_cmp_lg_u64 s[10:11], 0
	s_cbranch_scc1 .Lpp_lead_8
	s_waitcnt lgkmcnt(0)
; #define PG8_STAGE(bufoff, gbase, voff) do { _Pragma("unroll") for (int _i = 0; _i < 2; ++_i) \
;         __builtin_amdgcn_global_load_lds((const unsigned*)((const char*)(gbase) + (voff)[_i]), (LAS unsigned*)(lds + (bufoff) + ldsw + _i * 8192), 16, 0, 0); } while (0)
; #define PG8_LDA(dst, b, h) do { _Pragma("unroll") for (int m = 0; m < 4; ++m) _Pragma("unroll") for (int k = 0; k < 2; ++k) dst[m][k] = *(const LAS bf16x8*)(lds + PG8_SA(b, h) + aoff + m * 2048 + k * 1024); } while (0)
; #define PG8_LDB(dst, b, h) do { _Pragma("unroll") for (int n = 0; n < 2; ++n) _Pragma("unroll") for (int k = 0; k < 2; ++k) dst[n][k] = *(const LAS bf16x8*)(lds + PG8_SB(b, h) + boff + n * 2048 + k * 1024); } while (0)
; #define PG8_MMA(ai, bj, At, Bt) do { __builtin_amdgcn_s_setprio(1); _Pragma("unroll") for (int m = 0; m < 4; ++m) _Pragma("unroll") for (int n = 0; n < 2; ++n) _Pragma("unroll") for (int k = 0; k < 2; ++k) \
;         acc[ai][bj][m][n] = __builtin_amdgcn_mfma_f32_16x16x32_bf16(Bt[n][k], At[m][k], acc[ai][bj][m][n], 0, 0, 0); __builtin_amdgcn_s_setprio(0); } while (0)
; #define PG8_WAIT_V(n) asm volatile("s_waitcnt vmcnt(" #n ")" ::: "memory")
; #define PG8_WAIT_L(n) asm volatile("s_waitcnt lgkmcnt(" #n ")" ::: "memory")
; #define PG8_BAR __builtin_amdgcn_s_barrier()
; #define PG8_SCHED __builtin_amdgcn_sched_barrier(0)
; template <class Epi>
; __device__ __forceinline__ void gemm_phase(LAS unsigned char* lds, const Gemm g, const StaticOrder& S, const Epi& E, int wave_s) {
;     ...
;             PG8_LDB(B0, 1, 0); PG8_LDB(B1, 1, 1); PG8_SCHED; PG8_LDA(At, 1, 0); PG8_STAGE(PG8_SA(0, 1), a2 + hstepA, voffA);
;             PG8_WAIT_V(8); PG8_WAIT_L(0); PG8_BAR; PG8_MMA(0, 0, At, B0); PG8_MMA(0, 1, At, B1); PG8_BAR; PG8_SCHED;
;             PG8_LDA(At, 1, 1); PG8_STAGE(PG8_SB(1, 0), b3, voffB); PG8_STAGE(PG8_SB(1, 1), b3 + hstepB, voffB); PG8_STAGE(PG8_SA(1, 0), a3, voffA);
;             PG8_WAIT_V(8); PG8_WAIT_L(0); PG8_BAR; PG8_MMA(1, 0, At, B0); PG8_MMA(1, 1, At, B1); PG8_BAR; PG8_SCHED;
;         }
;         if (wr == 0) PG8_BAR;
.Lpp_lead_8:
	s_waitcnt lgkmcnt(4)
	s_barrier
	s_waitcnt lgkmcnt(4)
	v_mfma_f32_16x16x32_bf16 v[126:129], v[130:133], v[188:191], v[126:129]
	v_mfma_f32_16x16x32_bf16 v[122:125], v[138:141], v[188:191], v[122:125]
	v_mfma_f32_16x16x32_bf16 v[118:121], v[130:133], v[196:199], v[118:121]
	v_mfma_f32_16x16x32_bf16 v[114:117], v[138:141], v[196:199], v[114:117]
	v_mfma_f32_16x16x32_bf16 v[110:113], v[130:133], v[204:207], v[110:113]
	v_mfma_f32_16x16x32_bf16 v[106:109], v[138:141], v[204:207], v[106:109]
	v_mfma_f32_16x16x32_bf16 v[102:105], v[130:133], v[212:215], v[102:105]
	v_mfma_f32_16x16x32_bf16 v[98:101], v[138:141], v[212:215], v[98:101]
	v_mfma_f32_16x16x32_bf16 v[126:129], v[134:137], v[192:195], v[126:129]
	v_mfma_f32_16x16x32_bf16 v[122:125], v[142:145], v[192:195], v[122:125]
	v_mfma_f32_16x16x32_bf16 v[118:121], v[134:137], v[200:203], v[118:121]
	v_mfma_f32_16x16x32_bf16 v[114:117], v[142:145], v[200:203], v[114:117]
	v_mfma_f32_16x16x32_bf16 v[110:113], v[134:137], v[208:211], v[110:113]
	v_mfma_f32_16x16x32_bf16 v[106:109], v[142:145], v[208:211], v[106:109]
	v_mfma_f32_16x16x32_bf16 v[102:105], v[134:137], v[216:219], v[102:105]
	v_mfma_f32_16x16x32_bf16 v[98:101], v[142:145], v[216:219], v[98:101]
	s_waitcnt lgkmcnt(0)
	v_mfma_f32_16x16x32_bf16 v[62:65], v[146:149], v[188:191], v[62:65]
	v_mfma_f32_16x16x32_bf16 v[58:61], v[168:171], v[188:191], v[58:61]
	v_mfma_f32_16x16x32_bf16 v[54:57], v[146:149], v[196:199], v[54:57]
	v_mfma_f32_16x16x32_bf16 v[50:53], v[168:171], v[196:199], v[50:53]
	v_mfma_f32_16x16x32_bf16 v[46:49], v[146:149], v[204:207], v[46:49]
	v_mfma_f32_16x16x32_bf16 v[42:45], v[168:171], v[204:207], v[42:45]
	v_mfma_f32_16x16x32_bf16 v[38:41], v[146:149], v[212:215], v[38:41]
	v_mfma_f32_16x16x32_bf16 v[34:37], v[168:171], v[212:215], v[34:37]
	v_mfma_f32_16x16x32_bf16 v[62:65], v[150:153], v[192:195], v[62:65]
	v_mfma_f32_16x16x32_bf16 v[58:61], v[184:187], v[192:195], v[58:61]
	v_mfma_f32_16x16x32_bf16 v[54:57], v[150:153], v[200:203], v[54:57]
	v_mfma_f32_16x16x32_bf16 v[50:53], v[184:187], v[200:203], v[50:53]
	v_mfma_f32_16x16x32_bf16 v[46:49], v[150:153], v[208:211], v[46:49]
	v_mfma_f32_16x16x32_bf16 v[42:45], v[184:187], v[208:211], v[42:45]
	v_mfma_f32_16x16x32_bf16 v[38:41], v[150:153], v[216:219], v[38:41]
	v_mfma_f32_16x16x32_bf16 v[34:37], v[184:187], v[216:219], v[34:37]
	s_barrier
	s_add_i32 s22, s51, s25
	v_lshl_add_u64 v[172:173], v[172:173], 0, s[84:85]
	s_mov_b32 m0, s22
	ds_read_b128 v[188:191], v167 offset:49152
	ds_read_b128 v[192:195], v167 offset:50176
	ds_read_b128 v[196:199], v167 offset:51200
	ds_read_b128 v[200:203], v167 offset:52224
	ds_read_b128 v[204:207], v167 offset:53248
	ds_read_b128 v[208:211], v167 offset:54272
	ds_read_b128 v[212:215], v167 offset:55296
	ds_read_b128 v[216:219], v167 offset:56320
	global_load_lds_dwordx4 v[172:173], off
	s_add_i32 m0, s22, 0x2000
	s_add_u32 s22, s26, 0x18080
	v_lshl_add_u64 v[172:173], v[174:175], 0, s[84:85]
	s_addc_u32 s23, s27, 0
	s_add_i32 s26, s52, s25
	global_load_lds_dwordx4 v[172:173], off
	v_lshl_add_u64 v[172:173], s[22:23], 0, v[158:159]
	s_mov_b32 m0, s26
	s_nop 0
	global_load_lds_dwordx4 v[172:173], off
	v_lshl_add_u64 v[172:173], s[22:23], 0, v[154:155]
	s_add_i32 m0, s26, 0x2000
	s_nop 0
	global_load_lds_dwordx4 v[172:173], off
	v_lshl_add_u64 v[172:173], v[176:177], 0, s[84:85]
	s_mov_b32 m0, s41
	s_nop 0
	global_load_lds_dwordx4 v[172:173], off
	v_lshl_add_u64 v[172:173], v[220:221], 0, s[84:85]
	s_mov_b32 m0, s42
	s_nop 0
	global_load_lds_dwordx4 v[172:173], off
	s_waitcnt vmcnt(8)
	s_waitcnt lgkmcnt(0)
	s_barrier
	s_waitcnt lgkmcnt(0)
	v_mfma_f32_16x16x32_bf16 v[94:97], v[130:133], v[188:191], v[94:97]
	v_mfma_f32_16x16x32_bf16 v[90:93], v[138:141], v[188:191], v[90:93]
	v_mfma_f32_16x16x32_bf16 v[86:89], v[130:133], v[196:199], v[86:89]
	v_mfma_f32_16x16x32_bf16 v[82:85], v[138:141], v[196:199], v[82:85]
	v_mfma_f32_16x16x32_bf16 v[78:81], v[130:133], v[204:207], v[78:81]
	v_mfma_f32_16x16x32_bf16 v[74:77], v[138:141], v[204:207], v[74:77]
	v_mfma_f32_16x16x32_bf16 v[70:73], v[130:133], v[212:215], v[70:73]
	v_mfma_f32_16x16x32_bf16 v[66:69], v[138:141], v[212:215], v[66:69]
	v_mfma_f32_16x16x32_bf16 v[94:97], v[134:137], v[192:195], v[94:97]
	v_mfma_f32_16x16x32_bf16 v[90:93], v[142:145], v[192:195], v[90:93]
	v_mfma_f32_16x16x32_bf16 v[86:89], v[134:137], v[200:203], v[86:89]
	v_mfma_f32_16x16x32_bf16 v[82:85], v[142:145], v[200:203], v[82:85]
	v_mfma_f32_16x16x32_bf16 v[78:81], v[134:137], v[208:211], v[78:81]
	v_mfma_f32_16x16x32_bf16 v[74:77], v[142:145], v[208:211], v[74:77]
	v_mfma_f32_16x16x32_bf16 v[70:73], v[134:137], v[216:219], v[70:73]
	v_mfma_f32_16x16x32_bf16 v[66:69], v[142:145], v[216:219], v[66:69]
	v_mfma_f32_16x16x32_bf16 v[30:33], v[146:149], v[188:191], v[30:33]
	v_mfma_f32_16x16x32_bf16 v[26:29], v[168:171], v[188:191], v[26:29]
	v_mfma_f32_16x16x32_bf16 v[22:25], v[146:149], v[196:199], v[22:25]
	v_mfma_f32_16x16x32_bf16 v[18:21], v[168:171], v[196:199], v[18:21]
	v_mfma_f32_16x16x32_bf16 v[14:17], v[146:149], v[204:207], v[14:17]
	v_mfma_f32_16x16x32_bf16 v[8:11], v[168:171], v[204:207], v[8:11]
	v_mfma_f32_16x16x32_bf16 v[4:7], v[146:149], v[212:215], v[4:7]
	v_mfma_f32_16x16x32_bf16 v[0:3], v[168:171], v[212:215], v[0:3]
	v_mfma_f32_16x16x32_bf16 v[30:33], v[150:153], v[192:195], v[30:33]
	v_mfma_f32_16x16x32_bf16 v[26:29], v[184:187], v[192:195], v[26:29]
	v_mfma_f32_16x16x32_bf16 v[22:25], v[150:153], v[200:203], v[22:25]
	v_mfma_f32_16x16x32_bf16 v[18:21], v[184:187], v[200:203], v[18:21]
	v_mfma_f32_16x16x32_bf16 v[14:17], v[150:153], v[208:211], v[14:17]
	v_mfma_f32_16x16x32_bf16 v[8:11], v[184:187], v[208:211], v[8:11]
	v_mfma_f32_16x16x32_bf16 v[4:7], v[150:153], v[216:219], v[4:7]
	v_mfma_f32_16x16x32_bf16 v[0:3], v[184:187], v[216:219], v[0:3]
	s_barrier
	s_add_i32 s50, s50, 2
	s_add_u32 s48, s48, 0x100
	s_addc_u32 s49, s49, 0
	s_cmp_gt_u32 s50, 3
	s_mov_b64 s[22:23], s[6:7]
	s_cbranch_scc0 .LBB0_343
	s_and_b64 vcc, exec, s[10:11]
	s_cbranch_vccz .LBB0_346
	s_barrier

; #define PG8_STAGE(bufoff, gbase, voff) do { _Pragma("unroll") for (int _i = 0; _i < 2; ++_i) \
;         __builtin_amdgcn_global_load_lds((const unsigned*)((const char*)(gbase) + (voff)[_i]), (LAS unsigned*)(lds + (bufoff) + ldsw + _i * 8192), 16, 0, 0); } while (0)
; #define PG8_LDA(dst, b, h) do { _Pragma("unroll") for (int m = 0; m < 4; ++m) _Pragma("unroll") for (int k = 0; k < 2; ++k) dst[m][k] = *(const LAS bf16x8*)(lds + PG8_SA(b, h) + aoff + m * 2048 + k * 1024); } while (0)
; #define PG8_LDB(dst, b, h) do { _Pragma("unroll") for (int n = 0; n < 2; ++n) _Pragma("unroll") for (int k = 0; k < 2; ++k) dst[n][k] = *(const LAS bf16x8*)(lds + PG8_SB(b, h) + boff + n * 2048 + k * 1024); } while (0)
; #define PG8_MMA(ai, bj, At, Bt) do { __builtin_amdgcn_s_setprio(1); _Pragma("unroll") for (int m = 0; m < 4; ++m) _Pragma("unroll") for (int n = 0; n < 2; ++n) _Pragma("unroll") for (int k = 0; k < 2; ++k) \
;         acc[ai][bj][m][n] = __builtin_amdgcn_mfma_f32_16x16x32_bf16(Bt[n][k], At[m][k], acc[ai][bj][m][n], 0, 0, 0); __builtin_amdgcn_s_setprio(0); } while (0)
; #define PG8_WAIT_V(n) asm volatile("s_waitcnt vmcnt(" #n ")" ::: "memory")
; #define PG8_WAIT_L(n) asm volatile("s_waitcnt lgkmcnt(" #n ")" ::: "memory")
; #define PG8_BAR __builtin_amdgcn_s_barrier()
; #define PG8_SCHED __builtin_amdgcn_sched_barrier(0)
; template <class Epi>
; __device__ __forceinline__ void gemm_phase(LAS unsigned char* lds, const Gemm g, const StaticOrder& S, const Epi& E, int wave_s) {
;     ...
;             PG8_LDB(B0, 0, 0); PG8_LDB(B1, 0, 1); PG8_SCHED; PG8_LDA(At, 0, 0); PG8_STAGE(PG8_SA(1, 1), a1 + hstepA, voffA);
;             PG8_WAIT_V(8); PG8_WAIT_L(0); PG8_BAR; PG8_MMA(0, 0, At, B0); PG8_MMA(0, 1, At, B1); PG8_BAR; PG8_SCHED;
;             PG8_LDA(At, 0, 1); PG8_STAGE(PG8_SB(0, 0), b2, voffB); PG8_STAGE(PG8_SB(0, 1), b2 + hstepB, voffB); PG8_STAGE(PG8_SA(0, 0), a2, voffA);
;             PG8_WAIT_V(8); PG8_WAIT_L(0); PG8_BAR; PG8_MMA(1, 0, At, B0); PG8_MMA(1, 1, At, B1); PG8_BAR; PG8_SCHED;
;             PG8_LDB(B0, 1, 0); PG8_LDB(B1, 1, 1); PG8_SCHED; PG8_LDA(At, 1, 0); PG8_STAGE(PG8_SA(0, 1), a2 + hstepA, voffA);
.Lpp_lead_1:
	s_waitcnt lgkmcnt(4)
	s_barrier
	s_waitcnt lgkmcnt(4)
	v_mfma_f32_16x16x32_bf16 v[66:69], v[0:3], v[34:37], 0
	v_mfma_f32_16x16x32_bf16 v[70:73], v[8:11], v[34:37], 0
	v_mfma_f32_16x16x32_bf16 v[74:77], v[0:3], v[42:45], 0
	v_mfma_f32_16x16x32_bf16 v[78:81], v[8:11], v[42:45], 0
	v_mfma_f32_16x16x32_bf16 v[82:85], v[0:3], v[50:53], 0
	v_mfma_f32_16x16x32_bf16 v[86:89], v[8:11], v[50:53], 0
	v_mfma_f32_16x16x32_bf16 v[90:93], v[0:3], v[58:61], 0
	v_mfma_f32_16x16x32_bf16 v[94:97], v[8:11], v[58:61], 0
	v_mfma_f32_16x16x32_bf16 v[66:69], v[4:7], v[38:41], v[66:69]
	v_mfma_f32_16x16x32_bf16 v[70:73], v[14:17], v[38:41], v[70:73]
	v_mfma_f32_16x16x32_bf16 v[74:77], v[4:7], v[46:49], v[74:77]
	v_mfma_f32_16x16x32_bf16 v[78:81], v[14:17], v[46:49], v[78:81]
	v_mfma_f32_16x16x32_bf16 v[82:85], v[4:7], v[54:57], v[82:85]
	v_mfma_f32_16x16x32_bf16 v[86:89], v[14:17], v[54:57], v[86:89]
	v_mfma_f32_16x16x32_bf16 v[90:93], v[4:7], v[62:65], v[90:93]
	v_mfma_f32_16x16x32_bf16 v[94:97], v[14:17], v[62:65], v[94:97]
	s_waitcnt lgkmcnt(0)
	v_mfma_f32_16x16x32_bf16 v[98:101], v[18:21], v[34:37], 0
	v_mfma_f32_16x16x32_bf16 v[34:37], v[26:29], v[34:37], 0
	v_mfma_f32_16x16x32_bf16 v[98:101], v[22:25], v[38:41], v[98:101]
	v_mfma_f32_16x16x32_bf16 v[34:37], v[30:33], v[38:41], v[34:37]
	v_mfma_f32_16x16x32_bf16 v[38:41], v[18:21], v[42:45], 0
	v_mfma_f32_16x16x32_bf16 v[42:45], v[26:29], v[42:45], 0
	v_mfma_f32_16x16x32_bf16 v[38:41], v[22:25], v[46:49], v[38:41]
	v_mfma_f32_16x16x32_bf16 v[42:45], v[30:33], v[46:49], v[42:45]
	v_mfma_f32_16x16x32_bf16 v[46:49], v[18:21], v[50:53], 0
	v_mfma_f32_16x16x32_bf16 v[50:53], v[26:29], v[50:53], 0
	v_mfma_f32_16x16x32_bf16 v[46:49], v[22:25], v[54:57], v[46:49]
	v_mfma_f32_16x16x32_bf16 v[50:53], v[30:33], v[54:57], v[50:53]
	v_mfma_f32_16x16x32_bf16 v[54:57], v[18:21], v[58:61], 0
	v_mfma_f32_16x16x32_bf16 v[58:61], v[26:29], v[58:61], 0
	v_mfma_f32_16x16x32_bf16 v[54:57], v[22:25], v[62:65], v[54:57]
	v_mfma_f32_16x16x32_bf16 v[58:61], v[30:33], v[62:65], v[58:61]
	s_barrier
	s_add_i32 s45, s45, s30
	v_lshl_add_u64 v[172:173], s[22:23], 0, v[150:151]
	s_add_i32 s36, s45, 0x2000
	v_lshl_add_u64 v[130:131], v[172:173], 0, s[58:59]
	s_mov_b32 m0, s45
	v_lshl_add_u64 v[174:175], s[22:23], 0, v[146:147]
	s_add_u32 s48, s22, 0x10100
	ds_read_b128 v[62:65], v162 offset:16384
	ds_read_b128 v[102:105], v162 offset:17408
	ds_read_b128 v[106:109], v162 offset:18432
	ds_read_b128 v[110:113], v162 offset:19456
	ds_read_b128 v[114:117], v162 offset:20480
	ds_read_b128 v[118:121], v162 offset:21504
	ds_read_b128 v[122:125], v162 offset:22528
	ds_read_b128 v[126:129], v162 offset:23552
	global_load_lds_dwordx4 v[130:131], off
	v_lshl_add_u64 v[130:131], v[174:175], 0, s[58:59]
	s_mov_b32 m0, s36
	s_addc_u32 s49, s23, 0
	s_add_i32 s37, s44, s30
	global_load_lds_dwordx4 v[130:131], off
	v_lshl_add_u64 v[130:131], s[48:49], 0, v[150:151]
	s_mov_b32 m0, s37
	s_add_i32 s44, s37, 0x2000
	global_load_lds_dwordx4 v[130:131], off
	v_lshl_add_u64 v[130:131], s[48:49], 0, v[146:147]
	s_mov_b32 m0, s44
	v_lshl_add_u64 v[176:177], s[26:27], 0, v[152:153]
	global_load_lds_dwordx4 v[130:131], off
	v_lshl_add_u64 v[130:131], v[176:177], 0, s[58:59]
	s_mov_b32 m0, s31
	v_lshl_add_u64 v[214:215], s[26:27], 0, v[148:149]
	global_load_lds_dwordx4 v[130:131], off
	v_lshl_add_u64 v[130:131], v[214:215], 0, s[58:59]
	s_mov_b32 m0, s40
	s_nop 0
	global_load_lds_dwordx4 v[130:131], off
	s_waitcnt vmcnt(8)
	s_waitcnt lgkmcnt(0)
	s_barrier
	s_waitcnt lgkmcnt(0)
	v_mfma_f32_16x16x32_bf16 v[130:133], v[0:3], v[62:65], 0
	v_mfma_f32_16x16x32_bf16 v[138:141], v[0:3], v[106:109], 0
	v_mfma_f32_16x16x32_bf16 v[156:159], v[0:3], v[114:117], 0
	v_mfma_f32_16x16x32_bf16 v[0:3], v[0:3], v[122:125], 0
	v_mfma_f32_16x16x32_bf16 v[130:133], v[4:7], v[102:105], v[130:133]
	v_mfma_f32_16x16x32_bf16 v[138:141], v[4:7], v[110:113], v[138:141]
	v_mfma_f32_16x16x32_bf16 v[156:159], v[4:7], v[118:121], v[156:159]
	v_mfma_f32_16x16x32_bf16 v[0:3], v[4:7], v[126:129], v[0:3]
	v_mfma_f32_16x16x32_bf16 v[4:7], v[8:11], v[122:125], 0
	v_mfma_f32_16x16x32_bf16 v[134:137], v[8:11], v[62:65], 0
	v_mfma_f32_16x16x32_bf16 v[142:145], v[8:11], v[106:109], 0
	v_mfma_f32_16x16x32_bf16 v[164:167], v[8:11], v[114:117], 0
	v_mfma_f32_16x16x32_bf16 v[4:7], v[14:17], v[126:129], v[4:7]
	v_mfma_f32_16x16x32_bf16 v[134:137], v[14:17], v[102:105], v[134:137]
	v_mfma_f32_16x16x32_bf16 v[142:145], v[14:17], v[110:113], v[142:145]
	v_mfma_f32_16x16x32_bf16 v[164:167], v[14:17], v[118:121], v[164:167]
	v_mfma_f32_16x16x32_bf16 v[8:11], v[18:21], v[62:65], 0
	v_mfma_f32_16x16x32_bf16 v[14:17], v[26:29], v[62:65], 0
	v_mfma_f32_16x16x32_bf16 v[8:11], v[22:25], v[102:105], v[8:11]
	v_mfma_f32_16x16x32_bf16 v[14:17], v[30:33], v[102:105], v[14:17]
	v_mfma_f32_16x16x32_bf16 v[62:65], v[18:21], v[106:109], 0
	v_mfma_f32_16x16x32_bf16 v[102:105], v[26:29], v[106:109], 0
	v_mfma_f32_16x16x32_bf16 v[106:109], v[18:21], v[114:117], 0
	v_mfma_f32_16x16x32_bf16 v[18:21], v[18:21], v[122:125], 0
	v_mfma_f32_16x16x32_bf16 v[62:65], v[22:25], v[110:113], v[62:65]
	v_mfma_f32_16x16x32_bf16 v[102:105], v[30:33], v[110:113], v[102:105]
	v_mfma_f32_16x16x32_bf16 v[106:109], v[22:25], v[118:121], v[106:109]
	v_mfma_f32_16x16x32_bf16 v[110:113], v[26:29], v[114:117], 0
	v_mfma_f32_16x16x32_bf16 v[18:21], v[22:25], v[126:129], v[18:21]
	v_mfma_f32_16x16x32_bf16 v[22:25], v[26:29], v[122:125], 0
	v_mfma_f32_16x16x32_bf16 v[110:113], v[30:33], v[118:121], v[110:113]
	v_mfma_f32_16x16x32_bf16 v[22:25], v[30:33], v[126:129], v[22:25]
	s_barrier
	s_add_i32 s46, 0, 0x18000
	s_add_i32 s52, 0, 0x1c000
	v_add_u32_e32 v222, s46, v161
	v_add_u32_e32 v223, s52, v161
	ds_read_b128 v[26:29], v222
	ds_read_b128 v[30:33], v222 offset:1024
	ds_read_b128 v[114:117], v222 offset:2048
	ds_read_b128 v[118:121], v222 offset:3072
	ds_read_b128 v[182:185], v162 offset:32768
	ds_read_b128 v[186:189], v162 offset:33792
	ds_read_b128 v[190:193], v162 offset:34816
	ds_read_b128 v[194:197], v162 offset:35840
	ds_read_b128 v[198:201], v162 offset:36864
	ds_read_b128 v[202:205], v162 offset:37888
	ds_read_b128 v[206:209], v162 offset:38912
	ds_read_b128 v[210:213], v162 offset:39936
	ds_read_b128 v[122:125], v223
	ds_read_b128 v[126:129], v223 offset:1024
	ds_read_b128 v[168:171], v223 offset:2048
	ds_read_b128 v[178:181], v223 offset:3072
	s_add_u32 s48, s26, 0xc0100
	s_addc_u32 s49, s27, 0
	s_mov_b32 m0, s41
	v_lshl_add_u64 v[216:217], s[48:49], 0, v[152:153]
	global_load_lds_dwordx4 v[216:217], off
	v_lshl_add_u64 v[216:217], s[48:49], 0, v[148:149]
	s_mov_b32 m0, s42
	s_nop 0
	global_load_lds_dwordx4 v[216:217], off
	s_waitcnt vmcnt(8)
	s_cmp_lg_u64 s[6:7], 0
	s_cbranch_scc1 .Lpp_lead_2
	s_waitcnt lgkmcnt(0)
; #define PG8_STAGE(bufoff, gbase, voff) do { _Pragma("unroll") for (int _i = 0; _i < 2; ++_i) \
;         __builtin_amdgcn_global_load_lds((const unsigned*)((const char*)(gbase) + (voff)[_i]), (LAS unsigned*)(lds + (bufoff) + ldsw + _i * 8192), 16, 0, 0); } while (0)
; #define PG8_LDA(dst, b, h) do { _Pragma("unroll") for (int m = 0; m < 4; ++m) _Pragma("unroll") for (int k = 0; k < 2; ++k) dst[m][k] = *(const LAS bf16x8*)(lds + PG8_SA(b, h) + aoff + m * 2048 + k * 1024); } while (0)
; #define PG8_LDB(dst, b, h) do { _Pragma("unroll") for (int n = 0; n < 2; ++n) _Pragma("unroll") for (int k = 0; k < 2; ++k) dst[n][k] = *(const LAS bf16x8*)(lds + PG8_SB(b, h) + boff + n * 2048 + k * 1024); } while (0)
; #define PG8_MMA(ai, bj, At, Bt) do { __builtin_amdgcn_s_setprio(1); _Pragma("unroll") for (int m = 0; m < 4; ++m) _Pragma("unroll") for (int n = 0; n < 2; ++n) _Pragma("unroll") for (int k = 0; k < 2; ++k) \
;         acc[ai][bj][m][n] = __builtin_amdgcn_mfma_f32_16x16x32_bf16(Bt[n][k], At[m][k], acc[ai][bj][m][n], 0, 0, 0); __builtin_amdgcn_s_setprio(0); } while (0)
; #define PG8_WAIT_V(n) asm volatile("s_waitcnt vmcnt(" #n ")" ::: "memory")
; #define PG8_BAR __builtin_amdgcn_s_barrier()
; template <class Epi>
; __device__ __forceinline__ void gemm_phase(LAS unsigned char* lds, const Gemm g, const StaticOrder& S, const Epi& E, int wave_s) {
;     ...
;             PG8_LDB(B0, 0, 0); PG8_LDB(B1, 0, 1); PG8_SCHED; PG8_LDA(At, 0, 0); PG8_STAGE(PG8_SA(1, 1), a1 + hstepA, voffA);
;             PG8_WAIT_V(8); PG8_WAIT_L(0); PG8_BAR; PG8_MMA(0, 0, At, B0); PG8_MMA(0, 1, At, B1); PG8_BAR; PG8_SCHED;
;             PG8_LDA(At, 0, 1); PG8_STAGE(PG8_SB(0, 0), b2, voffB); PG8_STAGE(PG8_SB(0, 1), b2 + hstepB, voffB); PG8_STAGE(PG8_SA(0, 0), a2, voffA);
;             PG8_WAIT_V(8); PG8_WAIT_L(0); PG8_BAR; PG8_MMA(1, 0, At, B0); PG8_MMA(1, 1, At, B1); PG8_BAR; PG8_SCHED;
;             PG8_LDB(B0, 1, 0); PG8_LDB(B1, 1, 1); PG8_SCHED; PG8_LDA(At, 1, 0); PG8_STAGE(PG8_SA(0, 1), a2 + hstepA, voffA);
;             PG8_WAIT_V(8); PG8_WAIT_L(0); PG8_BAR; PG8_MMA(0, 0, At, B0); PG8_MMA(0, 1, At, B1); PG8_BAR; PG8_SCHED;
;             PG8_LDA(At, 1, 1); PG8_STAGE(PG8_SB(1, 0), b3, voffB); PG8_STAGE(PG8_SB(1, 1), b3 + hstepB, voffB); PG8_STAGE(PG8_SA(1, 0), a3, voffA);
;             PG8_WAIT_V(8); PG8_WAIT_L(0); PG8_BAR; PG8_MMA(1, 0, At, B0); PG8_MMA(1, 1, At, B1); PG8_BAR; PG8_SCHED;
.Lpp_lead_2:
	s_waitcnt lgkmcnt(4)
	s_barrier
	s_waitcnt lgkmcnt(4)
	v_mfma_f32_16x16x32_bf16 v[66:69], v[26:29], v[182:185], v[66:69]
	v_mfma_f32_16x16x32_bf16 v[70:73], v[114:117], v[182:185], v[70:73]
	v_mfma_f32_16x16x32_bf16 v[74:77], v[26:29], v[190:193], v[74:77]
	v_mfma_f32_16x16x32_bf16 v[78:81], v[114:117], v[190:193], v[78:81]
	v_mfma_f32_16x16x32_bf16 v[82:85], v[26:29], v[198:201], v[82:85]
	v_mfma_f32_16x16x32_bf16 v[86:89], v[114:117], v[198:201], v[86:89]
	v_mfma_f32_16x16x32_bf16 v[90:93], v[26:29], v[206:209], v[90:93]
	v_mfma_f32_16x16x32_bf16 v[94:97], v[114:117], v[206:209], v[94:97]
	v_mfma_f32_16x16x32_bf16 v[66:69], v[30:33], v[186:189], v[66:69]
	v_mfma_f32_16x16x32_bf16 v[70:73], v[118:121], v[186:189], v[70:73]
	v_mfma_f32_16x16x32_bf16 v[74:77], v[30:33], v[194:197], v[74:77]
	v_mfma_f32_16x16x32_bf16 v[78:81], v[118:121], v[194:197], v[78:81]
	v_mfma_f32_16x16x32_bf16 v[82:85], v[30:33], v[202:205], v[82:85]
	v_mfma_f32_16x16x32_bf16 v[86:89], v[118:121], v[202:205], v[86:89]
	v_mfma_f32_16x16x32_bf16 v[90:93], v[30:33], v[210:213], v[90:93]
	v_mfma_f32_16x16x32_bf16 v[94:97], v[118:121], v[210:213], v[94:97]
	s_waitcnt lgkmcnt(0)
	v_mfma_f32_16x16x32_bf16 v[98:101], v[122:125], v[182:185], v[98:101]
	v_mfma_f32_16x16x32_bf16 v[34:37], v[168:171], v[182:185], v[34:37]
	v_mfma_f32_16x16x32_bf16 v[38:41], v[122:125], v[190:193], v[38:41]
	v_mfma_f32_16x16x32_bf16 v[42:45], v[168:171], v[190:193], v[42:45]
	v_mfma_f32_16x16x32_bf16 v[46:49], v[122:125], v[198:201], v[46:49]
	v_mfma_f32_16x16x32_bf16 v[50:53], v[168:171], v[198:201], v[50:53]
	v_mfma_f32_16x16x32_bf16 v[54:57], v[122:125], v[206:209], v[54:57]
	v_mfma_f32_16x16x32_bf16 v[58:61], v[168:171], v[206:209], v[58:61]
	v_mfma_f32_16x16x32_bf16 v[98:101], v[126:129], v[186:189], v[98:101]
	v_mfma_f32_16x16x32_bf16 v[34:37], v[178:181], v[186:189], v[34:37]
	v_mfma_f32_16x16x32_bf16 v[38:41], v[126:129], v[194:197], v[38:41]
	v_mfma_f32_16x16x32_bf16 v[42:45], v[178:181], v[194:197], v[42:45]
	v_mfma_f32_16x16x32_bf16 v[46:49], v[126:129], v[202:205], v[46:49]
	v_mfma_f32_16x16x32_bf16 v[50:53], v[178:181], v[202:205], v[50:53]
	v_mfma_f32_16x16x32_bf16 v[54:57], v[126:129], v[210:213], v[54:57]
	v_mfma_f32_16x16x32_bf16 v[58:61], v[178:181], v[210:213], v[58:61]
	s_barrier
	s_add_i32 s48, s46, s30
	s_add_i32 s46, s48, 0x2000
	v_lshl_add_u64 v[172:173], v[172:173], 0, s[64:65]
	s_mov_b32 m0, s48
	s_add_u32 s50, s22, 0x10180
	ds_read_b128 v[182:185], v162 offset:49152
	ds_read_b128 v[186:189], v162 offset:50176
	ds_read_b128 v[190:193], v162 offset:51200
	ds_read_b128 v[194:197], v162 offset:52224
	ds_read_b128 v[198:201], v162 offset:53248
	ds_read_b128 v[202:205], v162 offset:54272
	ds_read_b128 v[206:209], v162 offset:55296
	ds_read_b128 v[210:213], v162 offset:56320
	global_load_lds_dwordx4 v[172:173], off
	v_lshl_add_u64 v[172:173], v[174:175], 0, s[64:65]
	s_mov_b32 m0, s46
	s_addc_u32 s51, s23, 0
	s_add_i32 s22, s52, s30
	global_load_lds_dwordx4 v[172:173], off
	v_lshl_add_u64 v[172:173], s[50:51], 0, v[150:151]
	s_mov_b32 m0, s22
	s_add_i32 s23, s22, 0x2000
	global_load_lds_dwordx4 v[172:173], off
	v_lshl_add_u64 v[172:173], s[50:51], 0, v[146:147]
	s_mov_b32 m0, s23
	s_nop 0
	global_load_lds_dwordx4 v[172:173], off
	v_lshl_add_u64 v[172:173], v[176:177], 0, s[64:65]
	s_mov_b32 m0, s43
	s_nop 0
	global_load_lds_dwordx4 v[172:173], off
	v_lshl_add_u64 v[172:173], v[214:215], 0, s[64:65]
	s_mov_b32 m0, s69
	s_nop 0
	global_load_lds_dwordx4 v[172:173], off
	s_waitcnt vmcnt(8)
	s_waitcnt lgkmcnt(0)
	s_barrier
	s_waitcnt lgkmcnt(0)
	v_mfma_f32_16x16x32_bf16 v[0:3], v[26:29], v[206:209], v[0:3]
	v_mfma_f32_16x16x32_bf16 v[4:7], v[114:117], v[206:209], v[4:7]
	v_mfma_f32_16x16x32_bf16 v[130:133], v[26:29], v[182:185], v[130:133]
	v_mfma_f32_16x16x32_bf16 v[134:137], v[114:117], v[182:185], v[134:137]
	v_mfma_f32_16x16x32_bf16 v[138:141], v[26:29], v[190:193], v[138:141]
	v_mfma_f32_16x16x32_bf16 v[142:145], v[114:117], v[190:193], v[142:145]
	v_mfma_f32_16x16x32_bf16 v[156:159], v[26:29], v[198:201], v[156:159]
	v_mfma_f32_16x16x32_bf16 v[164:167], v[114:117], v[198:201], v[164:167]
	v_mfma_f32_16x16x32_bf16 v[0:3], v[30:33], v[210:213], v[0:3]
	v_mfma_f32_16x16x32_bf16 v[4:7], v[118:121], v[210:213], v[4:7]
	v_mfma_f32_16x16x32_bf16 v[130:133], v[30:33], v[186:189], v[130:133]
	v_mfma_f32_16x16x32_bf16 v[134:137], v[118:121], v[186:189], v[134:137]
	v_mfma_f32_16x16x32_bf16 v[138:141], v[30:33], v[194:197], v[138:141]
	v_mfma_f32_16x16x32_bf16 v[142:145], v[118:121], v[194:197], v[142:145]
	v_mfma_f32_16x16x32_bf16 v[156:159], v[30:33], v[202:205], v[156:159]
	v_mfma_f32_16x16x32_bf16 v[164:167], v[118:121], v[202:205], v[164:167]
	v_mfma_f32_16x16x32_bf16 v[8:11], v[122:125], v[182:185], v[8:11]
	v_mfma_f32_16x16x32_bf16 v[14:17], v[168:171], v[182:185], v[14:17]
	v_mfma_f32_16x16x32_bf16 v[26:29], v[122:125], v[190:193], v[62:65]
	v_mfma_f32_16x16x32_bf16 v[30:33], v[168:171], v[190:193], v[102:105]
	v_mfma_f32_16x16x32_bf16 v[62:65], v[122:125], v[198:201], v[106:109]
	v_mfma_f32_16x16x32_bf16 v[102:105], v[168:171], v[198:201], v[110:113]
	v_mfma_f32_16x16x32_bf16 v[18:21], v[122:125], v[206:209], v[18:21]
	v_mfma_f32_16x16x32_bf16 v[22:25], v[168:171], v[206:209], v[22:25]
	v_mfma_f32_16x16x32_bf16 v[8:11], v[126:129], v[186:189], v[8:11]
	v_mfma_f32_16x16x32_bf16 v[14:17], v[178:181], v[186:189], v[14:17]
	v_mfma_f32_16x16x32_bf16 v[26:29], v[126:129], v[194:197], v[26:29]
	v_mfma_f32_16x16x32_bf16 v[30:33], v[178:181], v[194:197], v[30:33]
	v_mfma_f32_16x16x32_bf16 v[62:65], v[126:129], v[202:205], v[62:65]
	v_mfma_f32_16x16x32_bf16 v[102:105], v[178:181], v[202:205], v[102:105]
	v_mfma_f32_16x16x32_bf16 v[18:21], v[126:129], v[210:213], v[18:21]
	v_mfma_f32_16x16x32_bf16 v[22:25], v[178:181], v[210:213], v[22:25]
	s_barrier
	ds_read_b128 v[106:109], v163
	ds_read_b128 v[110:113], v163 offset:1024
	ds_read_b128 v[114:117], v163 offset:2048
	ds_read_b128 v[118:121], v163 offset:3072
	ds_read_b128 v[182:185], v162
	ds_read_b128 v[186:189], v162 offset:1024
	ds_read_b128 v[190:193], v162 offset:2048
	ds_read_b128 v[194:197], v162 offset:3072
	ds_read_b128 v[198:201], v162 offset:4096
	ds_read_b128 v[202:205], v162 offset:5120
	ds_read_b128 v[206:209], v162 offset:6144
	ds_read_b128 v[210:213], v162 offset:7168
	ds_read_b128 v[122:125], v218
	ds_read_b128 v[126:129], v218 offset:1024
	ds_read_b128 v[168:171], v218 offset:2048
	ds_read_b128 v[178:181], v218 offset:3072
	s_add_u32 s26, s26, 0xc0180
	s_addc_u32 s27, s27, 0
	s_mov_b32 m0, s47
	v_lshl_add_u64 v[172:173], s[26:27], 0, v[152:153]
	global_load_lds_dwordx4 v[172:173], off
	v_lshl_add_u64 v[172:173], s[26:27], 0, v[148:149]
	s_mov_b32 m0, s11
	s_nop 0
	global_load_lds_dwordx4 v[172:173], off
	s_waitcnt vmcnt(8)
	s_cmp_lg_u64 s[6:7], 0
	s_cbranch_scc1 .Lpp_lead_3
	s_waitcnt lgkmcnt(0)
; #define PG8_STAGE(bufoff, gbase, voff) do { _Pragma("unroll") for (int _i = 0; _i < 2; ++_i) \
;         __builtin_amdgcn_global_load_lds((const unsigned*)((const char*)(gbase) + (voff)[_i]), (LAS unsigned*)(lds + (bufoff) + ldsw + _i * 8192), 16, 0, 0); } while (0)
; #define PG8_LDA(dst, b, h) do { _Pragma("unroll") for (int m = 0; m < 4; ++m) _Pragma("unroll") for (int k = 0; k < 2; ++k) dst[m][k] = *(const LAS bf16x8*)(lds + PG8_SA(b, h) + aoff + m * 2048 + k * 1024); } while (0)
; #define PG8_LDB(dst, b, h) do { _Pragma("unroll") for (int n = 0; n < 2; ++n) _Pragma("unroll") for (int k = 0; k < 2; ++k) dst[n][k] = *(const LAS bf16x8*)(lds + PG8_SB(b, h) + boff + n * 2048 + k * 1024); } while (0)
; #define PG8_MMA(ai, bj, At, Bt) do { __builtin_amdgcn_s_setprio(1); _Pragma("unroll") for (int m = 0; m < 4; ++m) _Pragma("unroll") for (int n = 0; n < 2; ++n) _Pragma("unroll") for (int k = 0; k < 2; ++k) \
;         acc[ai][bj][m][n] = __builtin_amdgcn_mfma_f32_16x16x32_bf16(Bt[n][k], At[m][k], acc[ai][bj][m][n], 0, 0, 0); __builtin_amdgcn_s_setprio(0); } while (0)
; #define PG8_WAIT_V(n) asm volatile("s_waitcnt vmcnt(" #n ")" ::: "memory")
; #define PG8_WAIT_L(n) asm volatile("s_waitcnt lgkmcnt(" #n ")" ::: "memory")
; #define PG8_BAR __builtin_amdgcn_s_barrier()
; #define PG8_SCHED __builtin_amdgcn_sched_barrier(0)
; template <class Epi>
; __device__ __forceinline__ void gemm_phase(LAS unsigned char* lds, const Gemm g, const StaticOrder& S, const Epi& E, int wave_s) {
;     ...
;             const char* a2 = last ? nA : cA + (size_t)(t + 2) * kstep; const char* b2 = last ? nB : cB + (size_t)(t + 2) * kstep;
;             const char* a3 = a2 + kstep; const char* b3 = b2 + kstep;
;             PG8_LDB(B0, 0, 0); PG8_LDB(B1, 0, 1); PG8_SCHED; PG8_LDA(At, 0, 0); PG8_STAGE(PG8_SA(1, 1), a1 + hstepA, voffA);
;             PG8_WAIT_V(8); PG8_WAIT_L(0); PG8_BAR; PG8_MMA(0, 0, At, B0); PG8_MMA(0, 1, At, B1); PG8_BAR; PG8_SCHED;
;             PG8_LDA(At, 0, 1); PG8_STAGE(PG8_SB(0, 0), b2, voffB); PG8_STAGE(PG8_SB(0, 1), b2 + hstepB, voffB); PG8_STAGE(PG8_SA(0, 0), a2, voffA);
;             PG8_WAIT_V(8); PG8_WAIT_L(0); PG8_BAR; PG8_MMA(1, 0, At, B0); PG8_MMA(1, 1, At, B1); PG8_BAR; PG8_SCHED;
;             PG8_LDB(B0, 1, 0); PG8_LDB(B1, 1, 1); PG8_SCHED; PG8_LDA(At, 1, 0); PG8_STAGE(PG8_SA(0, 1), a2 + hstepA, voffA);
.Lpp_lead_3:
	s_waitcnt lgkmcnt(4)
	s_barrier
	s_waitcnt lgkmcnt(4)
	v_mfma_f32_16x16x32_bf16 v[90:93], v[106:109], v[206:209], v[90:93]
	v_mfma_f32_16x16x32_bf16 v[66:69], v[106:109], v[182:185], v[66:69]
	v_mfma_f32_16x16x32_bf16 v[70:73], v[114:117], v[182:185], v[70:73]
	v_mfma_f32_16x16x32_bf16 v[74:77], v[106:109], v[190:193], v[74:77]
	v_mfma_f32_16x16x32_bf16 v[78:81], v[114:117], v[190:193], v[78:81]
	v_mfma_f32_16x16x32_bf16 v[82:85], v[106:109], v[198:201], v[82:85]
	v_mfma_f32_16x16x32_bf16 v[86:89], v[114:117], v[198:201], v[86:89]
	v_mfma_f32_16x16x32_bf16 v[214:217], v[110:113], v[210:213], v[90:93]
	v_mfma_f32_16x16x32_bf16 v[90:93], v[114:117], v[206:209], v[94:97]
	v_mfma_f32_16x16x32_bf16 v[66:69], v[110:113], v[186:189], v[66:69]
	v_mfma_f32_16x16x32_bf16 v[70:73], v[118:121], v[186:189], v[70:73]
	v_mfma_f32_16x16x32_bf16 v[74:77], v[110:113], v[194:197], v[74:77]
	v_mfma_f32_16x16x32_bf16 v[78:81], v[118:121], v[194:197], v[78:81]
	v_mfma_f32_16x16x32_bf16 v[82:85], v[110:113], v[202:205], v[82:85]
	v_mfma_f32_16x16x32_bf16 v[86:89], v[118:121], v[202:205], v[86:89]
	v_mfma_f32_16x16x32_bf16 v[94:97], v[118:121], v[210:213], v[90:93]
	s_waitcnt lgkmcnt(0)
	v_mfma_f32_16x16x32_bf16 v[34:37], v[168:171], v[182:185], v[34:37]
	v_mfma_f32_16x16x32_bf16 v[38:41], v[122:125], v[190:193], v[38:41]
	v_mfma_f32_16x16x32_bf16 v[42:45], v[168:171], v[190:193], v[42:45]
	v_mfma_f32_16x16x32_bf16 v[46:49], v[122:125], v[198:201], v[46:49]
	v_mfma_f32_16x16x32_bf16 v[50:53], v[168:171], v[198:201], v[50:53]
	v_mfma_f32_16x16x32_bf16 v[54:57], v[122:125], v[206:209], v[54:57]
	v_mfma_f32_16x16x32_bf16 v[58:61], v[168:171], v[206:209], v[58:61]
	v_mfma_f32_16x16x32_bf16 v[90:93], v[122:125], v[182:185], v[98:101]
	v_mfma_f32_16x16x32_bf16 v[34:37], v[178:181], v[186:189], v[34:37]
	v_mfma_f32_16x16x32_bf16 v[38:41], v[126:129], v[194:197], v[38:41]
	v_mfma_f32_16x16x32_bf16 v[42:45], v[178:181], v[194:197], v[42:45]
	v_mfma_f32_16x16x32_bf16 v[46:49], v[126:129], v[202:205], v[46:49]
	v_mfma_f32_16x16x32_bf16 v[50:53], v[178:181], v[202:205], v[50:53]
	v_mfma_f32_16x16x32_bf16 v[54:57], v[126:129], v[210:213], v[54:57]
	v_mfma_f32_16x16x32_bf16 v[58:61], v[178:181], v[210:213], v[58:61]
	v_mfma_f32_16x16x32_bf16 v[218:221], v[126:129], v[186:189], v[90:93]
	s_barrier
	s_mov_b32 m0, s45
	v_lshl_add_u64 v[176:177], s[2:3], 0, v[150:151]
	s_add_u32 s26, s2, 0x10000
	ds_read_b128 v[90:93], v162 offset:16384
	ds_read_b128 v[98:101], v162 offset:17408
	ds_read_b128 v[182:185], v162 offset:18432
	ds_read_b128 v[186:189], v162 offset:19456
	ds_read_b128 v[190:193], v162 offset:20480
	ds_read_b128 v[194:197], v162 offset:21504
	ds_read_b128 v[198:201], v162 offset:22528
	ds_read_b128 v[202:205], v162 offset:23552
	global_load_lds_dwordx4 v[176:177], off
	v_lshl_add_u64 v[234:235], s[2:3], 0, v[146:147]
	s_mov_b32 m0, s36
	s_addc_u32 s27, s3, 0
	global_load_lds_dwordx4 v[234:235], off
	v_lshl_add_u64 v[172:173], s[26:27], 0, v[150:151]
	s_mov_b32 m0, s37
	v_lshl_add_u64 v[240:241], s[12:13], 0, v[152:153]
	global_load_lds_dwordx4 v[172:173], off
	v_lshl_add_u64 v[172:173], s[26:27], 0, v[146:147]
	s_mov_b32 m0, s44
	v_lshl_add_u64 v[250:251], s[12:13], 0, v[148:149]
	global_load_lds_dwordx4 v[172:173], off
	s_mov_b32 m0, s31
	s_nop 0
	global_load_lds_dwordx4 v[240:241], off
	s_mov_b32 m0, s40
	s_nop 0
	global_load_lds_dwordx4 v[250:251], off
	s_waitcnt vmcnt(8)
	s_waitcnt lgkmcnt(0)
	s_barrier
	s_waitcnt lgkmcnt(0)
	v_mfma_f32_16x16x32_bf16 v[0:3], v[106:109], v[198:201], v[0:3]
	v_mfma_f32_16x16x32_bf16 v[4:7], v[114:117], v[198:201], v[4:7]
	v_mfma_f32_16x16x32_bf16 v[130:133], v[106:109], v[90:93], v[130:133]
	v_mfma_f32_16x16x32_bf16 v[134:137], v[114:117], v[90:93], v[134:137]
	v_mfma_f32_16x16x32_bf16 v[138:141], v[106:109], v[182:185], v[138:141]
	v_mfma_f32_16x16x32_bf16 v[142:145], v[114:117], v[182:185], v[142:145]
	v_mfma_f32_16x16x32_bf16 v[156:159], v[106:109], v[190:193], v[156:159]
	v_mfma_f32_16x16x32_bf16 v[164:167], v[114:117], v[190:193], v[164:167]
	v_mfma_f32_16x16x32_bf16 v[0:3], v[110:113], v[202:205], v[0:3]
	v_mfma_f32_16x16x32_bf16 v[4:7], v[118:121], v[202:205], v[4:7]
	v_mfma_f32_16x16x32_bf16 v[130:133], v[110:113], v[98:101], v[130:133]
	v_mfma_f32_16x16x32_bf16 v[134:137], v[118:121], v[98:101], v[134:137]
	v_mfma_f32_16x16x32_bf16 v[138:141], v[110:113], v[186:189], v[138:141]
	v_mfma_f32_16x16x32_bf16 v[142:145], v[118:121], v[186:189], v[142:145]
	v_mfma_f32_16x16x32_bf16 v[156:159], v[110:113], v[194:197], v[156:159]
	v_mfma_f32_16x16x32_bf16 v[164:167], v[118:121], v[194:197], v[164:167]
	v_mfma_f32_16x16x32_bf16 v[8:11], v[122:125], v[90:93], v[8:11]
	v_mfma_f32_16x16x32_bf16 v[206:209], v[126:129], v[98:101], v[8:11]
	v_mfma_f32_16x16x32_bf16 v[8:11], v[168:171], v[90:93], v[14:17]
	v_mfma_f32_16x16x32_bf16 v[14:17], v[178:181], v[98:101], v[8:11]
	v_mfma_f32_16x16x32_bf16 v[8:11], v[122:125], v[182:185], v[26:29]
	v_mfma_f32_16x16x32_bf16 v[210:213], v[126:129], v[186:189], v[8:11]
	v_mfma_f32_16x16x32_bf16 v[8:11], v[168:171], v[182:185], v[30:33]
	v_mfma_f32_16x16x32_bf16 v[30:33], v[178:181], v[186:189], v[8:11]
	v_mfma_f32_16x16x32_bf16 v[8:11], v[122:125], v[190:193], v[62:65]
	v_mfma_f32_16x16x32_bf16 v[182:185], v[126:129], v[194:197], v[8:11]
	v_mfma_f32_16x16x32_bf16 v[8:11], v[168:171], v[190:193], v[102:105]
	v_mfma_f32_16x16x32_bf16 v[186:189], v[178:181], v[194:197], v[8:11]
	v_mfma_f32_16x16x32_bf16 v[8:11], v[122:125], v[198:201], v[18:21]
	v_mfma_f32_16x16x32_bf16 v[190:193], v[126:129], v[202:205], v[8:11]
	v_mfma_f32_16x16x32_bf16 v[8:11], v[168:171], v[198:201], v[22:25]
	v_mfma_f32_16x16x32_bf16 v[168:171], v[178:181], v[202:205], v[8:11]
	s_barrier
	s_nop 4
	ds_read_b128 v[8:11], v222
	ds_read_b128 v[22:25], v222 offset:1024
	ds_read_b128 v[62:65], v222 offset:2048
	ds_read_b128 v[178:181], v222 offset:3072
	ds_read_b128 v[18:21], v162 offset:32768
	ds_read_b128 v[26:29], v162 offset:33792
	ds_read_b128 v[102:105], v162 offset:34816
	ds_read_b128 v[226:229], v162 offset:35840
	ds_read_b128 v[230:233], v162 offset:36864
	ds_read_b128 v[242:245], v162 offset:37888
	ds_read_b128 v[246:249], v162 offset:38912
	ds_read_b128 v[172:175], v162 offset:39936
	ds_read_b128 v[194:197], v223
	ds_read_b128 v[198:201], v223 offset:1024
	ds_read_b128 v[202:205], v223 offset:2048
	ds_read_b128 v[222:225], v223 offset:3072
	s_add_u32 s26, s12, 0xc0000
	s_addc_u32 s27, s13, 0
	s_mov_b32 m0, s41
	v_lshl_add_u64 v[90:91], s[26:27], 0, v[152:153]
	global_load_lds_dwordx4 v[90:91], off
	v_lshl_add_u64 v[90:91], s[26:27], 0, v[148:149]
	s_mov_b32 m0, s42
	s_nop 0
	global_load_lds_dwordx4 v[90:91], off
	s_waitcnt vmcnt(8)
	s_cmp_lg_u64 s[6:7], 0
	s_cbranch_scc1 .Lpp_lead_4
	s_waitcnt lgkmcnt(0)
; #define PG8_STAGE(bufoff, gbase, voff) do { _Pragma("unroll") for (int _i = 0; _i < 2; ++_i) \
;         __builtin_amdgcn_global_load_lds((const unsigned*)((const char*)(gbase) + (voff)[_i]), (LAS unsigned*)(lds + (bufoff) + ldsw + _i * 8192), 16, 0, 0); } while (0)
; #define PG8_LDA(dst, b, h) do { _Pragma("unroll") for (int m = 0; m < 4; ++m) _Pragma("unroll") for (int k = 0; k < 2; ++k) dst[m][k] = *(const LAS bf16x8*)(lds + PG8_SA(b, h) + aoff + m * 2048 + k * 1024); } while (0)
; #define PG8_LDB(dst, b, h) do { _Pragma("unroll") for (int n = 0; n < 2; ++n) _Pragma("unroll") for (int k = 0; k < 2; ++k) dst[n][k] = *(const LAS bf16x8*)(lds + PG8_SB(b, h) + boff + n * 2048 + k * 1024); } while (0)
; #define PG8_MMA(ai, bj, At, Bt) do { __builtin_amdgcn_s_setprio(1); _Pragma("unroll") for (int m = 0; m < 4; ++m) _Pragma("unroll") for (int n = 0; n < 2; ++n) _Pragma("unroll") for (int k = 0; k < 2; ++k) \
;         acc[ai][bj][m][n] = __builtin_amdgcn_mfma_f32_16x16x32_bf16(Bt[n][k], At[m][k], acc[ai][bj][m][n], 0, 0, 0); __builtin_amdgcn_s_setprio(0); } while (0)
; #define PG8_WAIT_V(n) asm volatile("s_waitcnt vmcnt(" #n ")" ::: "memory")
; #define PG8_WAIT_L(n) asm volatile("s_waitcnt lgkmcnt(" #n ")" ::: "memory")
; #define PG8_BAR __builtin_amdgcn_s_barrier()
; #define PG8_SCHED __builtin_amdgcn_sched_barrier(0)
; template <class Epi>
; __device__ __forceinline__ void gemm_phase(LAS unsigned char* lds, const Gemm g, const StaticOrder& S, const Epi& E, int wave_s) {
;     ...
;             PG8_LDB(B0, 1, 0); PG8_LDB(B1, 1, 1); PG8_SCHED; PG8_LDA(At, 1, 0); PG8_STAGE(PG8_SA(0, 1), a2 + hstepA, voffA);
;             PG8_WAIT_V(8); PG8_WAIT_L(0); PG8_BAR; PG8_MMA(0, 0, At, B0); PG8_MMA(0, 1, At, B1); PG8_BAR; PG8_SCHED;
;             PG8_LDA(At, 1, 1); PG8_STAGE(PG8_SB(1, 0), b3, voffB); PG8_STAGE(PG8_SB(1, 1), b3 + hstepB, voffB); PG8_STAGE(PG8_SA(1, 0), a3, voffA);
;             PG8_WAIT_V(8); PG8_WAIT_L(0); PG8_BAR; PG8_MMA(1, 0, At, B0); PG8_MMA(1, 1, At, B1); PG8_BAR; PG8_SCHED;
;         }
;         if (wr == 0) PG8_BAR;
.Lpp_lead_4:
	s_waitcnt lgkmcnt(4)
	s_barrier
	s_waitcnt lgkmcnt(4)
	v_mfma_f32_16x16x32_bf16 v[66:69], v[8:11], v[18:21], v[66:69]
	v_mfma_f32_16x16x32_bf16 v[122:125], v[22:25], v[26:29], v[66:69]
	v_mfma_f32_16x16x32_bf16 v[66:69], v[62:65], v[18:21], v[70:73]
	v_mfma_f32_16x16x32_bf16 v[114:117], v[178:181], v[26:29], v[66:69]
	v_mfma_f32_16x16x32_bf16 v[66:69], v[8:11], v[102:105], v[74:77]
	v_mfma_f32_16x16x32_bf16 v[106:109], v[22:25], v[226:229], v[66:69]
	v_mfma_f32_16x16x32_bf16 v[66:69], v[62:65], v[102:105], v[78:81]
	v_mfma_f32_16x16x32_bf16 v[98:101], v[178:181], v[226:229], v[66:69]
	v_mfma_f32_16x16x32_bf16 v[66:69], v[8:11], v[230:233], v[82:85]
	v_mfma_f32_16x16x32_bf16 v[90:93], v[22:25], v[242:245], v[66:69]
	v_mfma_f32_16x16x32_bf16 v[66:69], v[62:65], v[230:233], v[86:89]
	v_mfma_f32_16x16x32_bf16 v[82:85], v[178:181], v[242:245], v[66:69]
	v_mfma_f32_16x16x32_bf16 v[66:69], v[8:11], v[246:249], v[214:217]
	v_mfma_f32_16x16x32_bf16 v[74:77], v[22:25], v[172:175], v[66:69]
	v_mfma_f32_16x16x32_bf16 v[66:69], v[62:65], v[246:249], v[94:97]
	v_mfma_f32_16x16x32_bf16 v[66:69], v[178:181], v[172:175], v[66:69]
	s_waitcnt lgkmcnt(0)
	v_mfma_f32_16x16x32_bf16 v[70:73], v[194:197], v[18:21], v[218:221]
	v_mfma_f32_16x16x32_bf16 v[18:21], v[202:205], v[18:21], v[34:37]
	v_mfma_f32_16x16x32_bf16 v[118:121], v[222:225], v[26:29], v[18:21]
	v_mfma_f32_16x16x32_bf16 v[18:21], v[194:197], v[102:105], v[38:41]
	v_mfma_f32_16x16x32_bf16 v[110:113], v[198:201], v[226:229], v[18:21]
	v_mfma_f32_16x16x32_bf16 v[18:21], v[202:205], v[102:105], v[42:45]
	v_mfma_f32_16x16x32_bf16 v[102:105], v[222:225], v[226:229], v[18:21]
	v_mfma_f32_16x16x32_bf16 v[18:21], v[194:197], v[230:233], v[46:49]
	v_mfma_f32_16x16x32_bf16 v[94:97], v[198:201], v[242:245], v[18:21]
	v_mfma_f32_16x16x32_bf16 v[18:21], v[202:205], v[230:233], v[50:53]
	v_mfma_f32_16x16x32_bf16 v[86:89], v[222:225], v[242:245], v[18:21]
	v_mfma_f32_16x16x32_bf16 v[18:21], v[194:197], v[246:249], v[54:57]
	v_mfma_f32_16x16x32_bf16 v[78:81], v[198:201], v[172:175], v[18:21]
	v_mfma_f32_16x16x32_bf16 v[18:21], v[202:205], v[246:249], v[58:61]
	v_mfma_f32_16x16x32_bf16 v[126:129], v[198:201], v[26:29], v[70:73]
	v_mfma_f32_16x16x32_bf16 v[70:73], v[222:225], v[172:175], v[18:21]
	s_barrier
	s_mov_b32 m0, s48
	s_nop 2
	v_lshl_add_u64 v[18:19], v[176:177], 0, s[84:85]
	s_add_u32 s2, s2, 0x10080
	ds_read_b128 v[38:41], v162 offset:49152
	ds_read_b128 v[46:49], v162 offset:50176
	ds_read_b128 v[172:175], v162 offset:51200
	ds_read_b128 v[214:217], v162 offset:52224
	ds_read_b128 v[218:221], v162 offset:53248
	ds_read_b128 v[226:229], v162 offset:54272
	ds_read_b128 v[230:233], v162 offset:55296
	ds_read_b128 v[242:245], v162 offset:56320
	global_load_lds_dwordx4 v[18:19], off
	v_lshl_add_u64 v[18:19], v[234:235], 0, s[84:85]
	s_mov_b32 m0, s46
	s_addc_u32 s3, s3, 0
	global_load_lds_dwordx4 v[18:19], off
	v_lshl_add_u64 v[18:19], s[2:3], 0, v[150:151]
	s_mov_b32 m0, s22
	s_nop 0
	global_load_lds_dwordx4 v[18:19], off
	v_lshl_add_u64 v[18:19], s[2:3], 0, v[146:147]
	s_mov_b32 m0, s23
	s_nop 0
	global_load_lds_dwordx4 v[18:19], off
	v_lshl_add_u64 v[18:19], v[240:241], 0, s[84:85]
	s_mov_b32 m0, s43
	s_nop 0
	global_load_lds_dwordx4 v[18:19], off
	v_lshl_add_u64 v[18:19], v[250:251], 0, s[84:85]
	s_mov_b32 m0, s69
	s_nop 0
	global_load_lds_dwordx4 v[18:19], off
	s_waitcnt vmcnt(8)
	s_waitcnt lgkmcnt(0)
	s_barrier
	s_waitcnt lgkmcnt(0)
	v_mfma_f32_16x16x32_bf16 v[18:21], v[8:11], v[38:41], v[130:133]
	v_mfma_f32_16x16x32_bf16 v[58:61], v[22:25], v[46:49], v[18:21]
	v_mfma_f32_16x16x32_bf16 v[18:21], v[62:65], v[38:41], v[134:137]
	v_mfma_f32_16x16x32_bf16 v[50:53], v[178:181], v[46:49], v[18:21]
	v_mfma_f32_16x16x32_bf16 v[18:21], v[8:11], v[172:175], v[138:141]
	v_mfma_f32_16x16x32_bf16 v[42:45], v[22:25], v[214:217], v[18:21]
	v_mfma_f32_16x16x32_bf16 v[18:21], v[62:65], v[172:175], v[142:145]
	v_mfma_f32_16x16x32_bf16 v[34:37], v[178:181], v[214:217], v[18:21]
	v_mfma_f32_16x16x32_bf16 v[18:21], v[8:11], v[218:221], v[156:159]
	v_mfma_f32_16x16x32_bf16 v[0:3], v[8:11], v[230:233], v[0:3]
	v_mfma_f32_16x16x32_bf16 v[26:29], v[22:25], v[226:229], v[18:21]
	v_mfma_f32_16x16x32_bf16 v[18:21], v[62:65], v[218:221], v[164:167]
	v_mfma_f32_16x16x32_bf16 v[8:11], v[22:25], v[242:245], v[0:3]
	v_mfma_f32_16x16x32_bf16 v[0:3], v[62:65], v[230:233], v[4:7]
	v_mfma_f32_16x16x32_bf16 v[18:21], v[178:181], v[226:229], v[18:21]
	v_mfma_f32_16x16x32_bf16 v[0:3], v[178:181], v[242:245], v[0:3]
	v_mfma_f32_16x16x32_bf16 v[4:7], v[194:197], v[38:41], v[206:209]
	v_mfma_f32_16x16x32_bf16 v[62:65], v[198:201], v[46:49], v[4:7]
	v_mfma_f32_16x16x32_bf16 v[4:7], v[202:205], v[38:41], v[14:17]
	v_mfma_f32_16x16x32_bf16 v[54:57], v[222:225], v[46:49], v[4:7]
	v_mfma_f32_16x16x32_bf16 v[4:7], v[194:197], v[172:175], v[210:213]
	v_mfma_f32_16x16x32_bf16 v[46:49], v[198:201], v[214:217], v[4:7]
	v_mfma_f32_16x16x32_bf16 v[4:7], v[202:205], v[172:175], v[30:33]
	v_mfma_f32_16x16x32_bf16 v[38:41], v[222:225], v[214:217], v[4:7]
	v_mfma_f32_16x16x32_bf16 v[4:7], v[194:197], v[218:221], v[182:185]
	v_mfma_f32_16x16x32_bf16 v[30:33], v[198:201], v[226:229], v[4:7]
	v_mfma_f32_16x16x32_bf16 v[4:7], v[202:205], v[218:221], v[186:189]
	v_mfma_f32_16x16x32_bf16 v[22:25], v[222:225], v[226:229], v[4:7]
	v_mfma_f32_16x16x32_bf16 v[4:7], v[194:197], v[230:233], v[190:193]
	v_mfma_f32_16x16x32_bf16 v[14:17], v[198:201], v[242:245], v[4:7]
	v_mfma_f32_16x16x32_bf16 v[4:7], v[202:205], v[230:233], v[168:171]
	v_mfma_f32_16x16x32_bf16 v[4:7], v[222:225], v[242:245], v[4:7]
	s_barrier
	s_andn2_b64 vcc, exec, s[6:7]
	s_cbranch_vccnz .LBB0_466
	s_barrier

; #define PG8_STAGE(bufoff, gbase, voff) do { _Pragma("unroll") for (int _i = 0; _i < 2; ++_i) \
;         __builtin_amdgcn_global_load_lds((const unsigned*)((const char*)(gbase) + (voff)[_i]), (LAS unsigned*)(lds + (bufoff) + ldsw + _i * 8192), 16, 0, 0); } while (0)
; #define PG8_LDA(dst, b, h) do { _Pragma("unroll") for (int m = 0; m < 4; ++m) _Pragma("unroll") for (int k = 0; k < 2; ++k) dst[m][k] = *(const LAS bf16x8*)(lds + PG8_SA(b, h) + aoff + m * 2048 + k * 1024); } while (0)
; #define PG8_LDB(dst, b, h) do { _Pragma("unroll") for (int n = 0; n < 2; ++n) _Pragma("unroll") for (int k = 0; k < 2; ++k) dst[n][k] = *(const LAS bf16x8*)(lds + PG8_SB(b, h) + boff + n * 2048 + k * 1024); } while (0)
; #define PG8_MMA(ai, bj, At, Bt) do { __builtin_amdgcn_s_setprio(1); _Pragma("unroll") for (int m = 0; m < 4; ++m) _Pragma("unroll") for (int n = 0; n < 2; ++n) _Pragma("unroll") for (int k = 0; k < 2; ++k) \
;         acc[ai][bj][m][n] = __builtin_amdgcn_mfma_f32_16x16x32_bf16(Bt[n][k], At[m][k], acc[ai][bj][m][n], 0, 0, 0); __builtin_amdgcn_s_setprio(0); } while (0)
; #define PG8_WAIT_V(n) asm volatile("s_waitcnt vmcnt(" #n ")" ::: "memory")
; #define PG8_WAIT_L(n) asm volatile("s_waitcnt lgkmcnt(" #n ")" ::: "memory")
; #define PG8_BAR __builtin_amdgcn_s_barrier()
; #define PG8_SCHED __builtin_amdgcn_sched_barrier(0)
; template <class Epi>
; __device__ __forceinline__ void gemm_phase(LAS unsigned char* lds, const Gemm g, const StaticOrder& S, const Epi& E, int wave_s) {
;     ...
;             PG8_LDB(B0, 0, 0); PG8_LDB(B1, 0, 1); PG8_SCHED; PG8_LDA(At, 0, 0); PG8_STAGE(PG8_SA(1, 1), a1 + hstepA, voffA);
;             PG8_WAIT_V(8); PG8_WAIT_L(0); PG8_BAR; PG8_MMA(0, 0, At, B0); PG8_MMA(0, 1, At, B1); PG8_BAR; PG8_SCHED;
;             PG8_LDA(At, 0, 1); PG8_STAGE(PG8_SB(0, 0), b2, voffB); PG8_STAGE(PG8_SB(0, 1), b2 + hstepB, voffB); PG8_STAGE(PG8_SA(0, 0), a2, voffA);
;             PG8_WAIT_V(8); PG8_WAIT_L(0); PG8_BAR; PG8_MMA(1, 0, At, B0); PG8_MMA(1, 1, At, B1); PG8_BAR; PG8_SCHED;
;             PG8_LDB(B0, 1, 0); PG8_LDB(B1, 1, 1); PG8_SCHED; PG8_LDA(At, 1, 0); PG8_STAGE(PG8_SA(0, 1), a2 + hstepA, voffA);
.Lpp_lead_9:
	s_waitcnt lgkmcnt(4)
	s_barrier
	s_waitcnt lgkmcnt(4)
	v_mfma_f32_16x16x32_bf16 v[106:109], v[130:133], v[186:189], v[106:109]
	v_mfma_f32_16x16x32_bf16 v[114:117], v[152:155], v[186:189], v[114:117]
	v_mfma_f32_16x16x32_bf16 v[98:101], v[130:133], v[194:197], v[98:101]
	v_mfma_f32_16x16x32_bf16 v[110:113], v[152:155], v[194:197], v[110:113]
	v_mfma_f32_16x16x32_bf16 v[94:97], v[130:133], v[202:205], v[94:97]
	v_mfma_f32_16x16x32_bf16 v[102:105], v[152:155], v[202:205], v[102:105]
	v_mfma_f32_16x16x32_bf16 v[90:93], v[130:133], v[212:215], v[90:93]
	v_mfma_f32_16x16x32_bf16 v[126:129], v[152:155], v[212:215], v[126:129]
	v_mfma_f32_16x16x32_bf16 v[106:109], v[134:137], v[190:193], v[106:109]
	v_mfma_f32_16x16x32_bf16 v[114:117], v[156:159], v[190:193], v[114:117]
	v_mfma_f32_16x16x32_bf16 v[98:101], v[134:137], v[198:201], v[98:101]
	v_mfma_f32_16x16x32_bf16 v[110:113], v[156:159], v[198:201], v[110:113]
	v_mfma_f32_16x16x32_bf16 v[94:97], v[134:137], v[208:211], v[94:97]
	v_mfma_f32_16x16x32_bf16 v[102:105], v[156:159], v[208:211], v[102:105]
	v_mfma_f32_16x16x32_bf16 v[90:93], v[134:137], v[222:225], v[90:93]
	v_mfma_f32_16x16x32_bf16 v[126:129], v[156:159], v[222:225], v[126:129]
	s_waitcnt lgkmcnt(0)
	v_mfma_f32_16x16x32_bf16 v[62:65], v[160:163], v[186:189], v[62:65]
	v_mfma_f32_16x16x32_bf16 v[34:37], v[178:181], v[186:189], v[34:37]
	v_mfma_f32_16x16x32_bf16 v[58:61], v[160:163], v[194:197], v[58:61]
	v_mfma_f32_16x16x32_bf16 v[30:33], v[178:181], v[194:197], v[30:33]
	v_mfma_f32_16x16x32_bf16 v[54:57], v[160:163], v[202:205], v[54:57]
	v_mfma_f32_16x16x32_bf16 v[26:29], v[178:181], v[202:205], v[26:29]
	v_mfma_f32_16x16x32_bf16 v[50:53], v[160:163], v[212:215], v[50:53]
	v_mfma_f32_16x16x32_bf16 v[22:25], v[178:181], v[212:215], v[22:25]
	v_mfma_f32_16x16x32_bf16 v[62:65], v[170:173], v[190:193], v[62:65]
	v_mfma_f32_16x16x32_bf16 v[34:37], v[182:185], v[190:193], v[34:37]
	v_mfma_f32_16x16x32_bf16 v[58:61], v[170:173], v[198:201], v[58:61]
	v_mfma_f32_16x16x32_bf16 v[30:33], v[182:185], v[198:201], v[30:33]
	v_mfma_f32_16x16x32_bf16 v[54:57], v[170:173], v[208:211], v[54:57]
	v_mfma_f32_16x16x32_bf16 v[26:29], v[182:185], v[208:211], v[26:29]
	v_mfma_f32_16x16x32_bf16 v[50:53], v[170:173], v[222:225], v[50:53]
	v_mfma_f32_16x16x32_bf16 v[22:25], v[182:185], v[222:225], v[22:25]
	s_barrier
	s_add_i32 s58, s58, s36
	v_lshl_add_u64 v[164:165], s[40:41], 0, v[12:13]
	s_mov_b32 m0, s58
	ds_read_b128 v[186:189], v247 offset:16384
	ds_read_b128 v[190:193], v247 offset:17408
	ds_read_b128 v[194:197], v247 offset:18432
	ds_read_b128 v[198:201], v247 offset:19456
	ds_read_b128 v[202:205], v247 offset:20480
	ds_read_b128 v[208:211], v247 offset:21504
	ds_read_b128 v[212:215], v247 offset:22528
	ds_read_b128 v[222:225], v247 offset:23552
	global_load_lds_dwordx4 v[164:165], off
	s_add_i32 m0, s58, 0x2000
	s_add_u32 s58, s40, 0x40000
	v_lshl_add_u64 v[174:175], s[40:41], 0, v[138:139]
	s_addc_u32 s59, s41, 0
	s_add_i32 s70, s70, s36
	global_load_lds_dwordx4 v[174:175], off
	v_lshl_add_u64 v[176:177], s[58:59], 0, v[12:13]
	s_mov_b32 m0, s70
	v_lshl_add_u64 v[240:241], s[42:43], 0, v[140:141]
	global_load_lds_dwordx4 v[176:177], off
	v_lshl_add_u64 v[176:177], s[58:59], 0, v[138:139]
	s_add_i32 m0, s70, 0x2000
	s_nop 0
	global_load_lds_dwordx4 v[176:177], off
	v_lshl_add_u64 v[176:177], s[42:43], 0, v[142:143]
	s_mov_b32 m0, s37
	s_nop 0
	global_load_lds_dwordx4 v[176:177], off
	s_mov_b32 m0, s44
	s_nop 0
	global_load_lds_dwordx4 v[240:241], off
	s_waitcnt vmcnt(8)
	s_waitcnt lgkmcnt(0)
	s_barrier
	s_waitcnt lgkmcnt(0)
	v_mfma_f32_16x16x32_bf16 v[86:89], v[130:133], v[186:189], v[86:89]
	v_mfma_f32_16x16x32_bf16 v[122:125], v[152:155], v[186:189], v[122:125]
	v_mfma_f32_16x16x32_bf16 v[82:85], v[130:133], v[194:197], v[82:85]
	v_mfma_f32_16x16x32_bf16 v[118:121], v[152:155], v[194:197], v[118:121]
	v_mfma_f32_16x16x32_bf16 v[78:81], v[130:133], v[202:205], v[78:81]
	v_mfma_f32_16x16x32_bf16 v[70:73], v[152:155], v[202:205], v[70:73]
	v_mfma_f32_16x16x32_bf16 v[74:77], v[130:133], v[212:215], v[74:77]
	v_mfma_f32_16x16x32_bf16 v[66:69], v[152:155], v[212:215], v[66:69]
	v_mfma_f32_16x16x32_bf16 v[86:89], v[134:137], v[190:193], v[86:89]
	v_mfma_f32_16x16x32_bf16 v[122:125], v[156:159], v[190:193], v[122:125]
	v_mfma_f32_16x16x32_bf16 v[82:85], v[134:137], v[198:201], v[82:85]
	v_mfma_f32_16x16x32_bf16 v[118:121], v[156:159], v[198:201], v[118:121]
	v_mfma_f32_16x16x32_bf16 v[78:81], v[134:137], v[208:211], v[78:81]
	v_mfma_f32_16x16x32_bf16 v[70:73], v[156:159], v[208:211], v[70:73]
	v_mfma_f32_16x16x32_bf16 v[74:77], v[134:137], v[222:225], v[74:77]
	v_mfma_f32_16x16x32_bf16 v[66:69], v[156:159], v[222:225], v[66:69]
	v_mfma_f32_16x16x32_bf16 v[46:49], v[160:163], v[186:189], v[46:49]
	v_mfma_f32_16x16x32_bf16 v[14:17], v[178:181], v[186:189], v[14:17]
	v_mfma_f32_16x16x32_bf16 v[42:45], v[160:163], v[194:197], v[42:45]
	v_mfma_f32_16x16x32_bf16 v[8:11], v[178:181], v[194:197], v[8:11]
	v_mfma_f32_16x16x32_bf16 v[38:41], v[160:163], v[202:205], v[38:41]
	v_mfma_f32_16x16x32_bf16 v[4:7], v[178:181], v[202:205], v[4:7]
	v_mfma_f32_16x16x32_bf16 v[18:21], v[160:163], v[212:215], v[18:21]
	v_mfma_f32_16x16x32_bf16 v[0:3], v[178:181], v[212:215], v[0:3]
	v_mfma_f32_16x16x32_bf16 v[46:49], v[170:173], v[190:193], v[46:49]
	v_mfma_f32_16x16x32_bf16 v[14:17], v[182:185], v[190:193], v[14:17]
	v_mfma_f32_16x16x32_bf16 v[42:45], v[170:173], v[198:201], v[42:45]
	v_mfma_f32_16x16x32_bf16 v[8:11], v[182:185], v[198:201], v[8:11]
	v_mfma_f32_16x16x32_bf16 v[38:41], v[170:173], v[208:211], v[38:41]
	v_mfma_f32_16x16x32_bf16 v[4:7], v[182:185], v[208:211], v[4:7]
	v_mfma_f32_16x16x32_bf16 v[18:21], v[170:173], v[222:225], v[18:21]
	v_mfma_f32_16x16x32_bf16 v[0:3], v[182:185], v[222:225], v[0:3]
	s_barrier
	s_add_i32 s58, 0, 0x18000
	s_add_i32 s59, 0, 0x1c000
	v_add_u32_e32 v156, s58, v167
	v_add_u32_e32 v182, s59, v167
	ds_read_b128 v[130:133], v156
	ds_read_b128 v[134:137], v156 offset:1024
	ds_read_b128 v[152:155], v156 offset:2048
	ds_read_b128 v[156:159], v156 offset:3072
	ds_read_b128 v[186:189], v247 offset:32768
	ds_read_b128 v[190:193], v247 offset:33792
	ds_read_b128 v[194:197], v247 offset:34816
	ds_read_b128 v[198:201], v247 offset:35840
	ds_read_b128 v[202:205], v247 offset:36864
	ds_read_b128 v[208:211], v247 offset:37888
	ds_read_b128 v[212:215], v247 offset:38912
	ds_read_b128 v[222:225], v247 offset:39936
	ds_read_b128 v[160:163], v182
	ds_read_b128 v[170:173], v182 offset:1024
	ds_read_b128 v[178:181], v182 offset:2048
	ds_read_b128 v[182:185], v182 offset:3072
	s_add_u32 s42, s42, 0x40000
	s_addc_u32 s43, s43, 0
	s_mov_b32 m0, s45
	v_lshl_add_u64 v[250:251], s[42:43], 0, v[142:143]
	global_load_lds_dwordx4 v[250:251], off
	v_lshl_add_u64 v[250:251], s[42:43], 0, v[140:141]
	s_mov_b32 m0, s46
	s_nop 0
	global_load_lds_dwordx4 v[250:251], off
	s_waitcnt vmcnt(8)
	s_cmp_lg_u64 s[22:23], 0
	s_cbranch_scc1 .Lpp_lead_10
	s_waitcnt lgkmcnt(0)
; #define PG8_STAGE(bufoff, gbase, voff) do { _Pragma("unroll") for (int _i = 0; _i < 2; ++_i) \
;         __builtin_amdgcn_global_load_lds((const unsigned*)((const char*)(gbase) + (voff)[_i]), (LAS unsigned*)(lds + (bufoff) + ldsw + _i * 8192), 16, 0, 0); } while (0)
; #define PG8_LDA(dst, b, h) do { _Pragma("unroll") for (int m = 0; m < 4; ++m) _Pragma("unroll") for (int k = 0; k < 2; ++k) dst[m][k] = *(const LAS bf16x8*)(lds + PG8_SA(b, h) + aoff + m * 2048 + k * 1024); } while (0)
; #define PG8_LDB(dst, b, h) do { _Pragma("unroll") for (int n = 0; n < 2; ++n) _Pragma("unroll") for (int k = 0; k < 2; ++k) dst[n][k] = *(const LAS bf16x8*)(lds + PG8_SB(b, h) + boff + n * 2048 + k * 1024); } while (0)
; #define PG8_MMA(ai, bj, At, Bt) do { __builtin_amdgcn_s_setprio(1); _Pragma("unroll") for (int m = 0; m < 4; ++m) _Pragma("unroll") for (int n = 0; n < 2; ++n) _Pragma("unroll") for (int k = 0; k < 2; ++k) \
;         acc[ai][bj][m][n] = __builtin_amdgcn_mfma_f32_16x16x32_bf16(Bt[n][k], At[m][k], acc[ai][bj][m][n], 0, 0, 0); __builtin_amdgcn_s_setprio(0); } while (0)
; #define PG8_WAIT_V(n) asm volatile("s_waitcnt vmcnt(" #n ")" ::: "memory")
; #define PG8_WAIT_L(n) asm volatile("s_waitcnt lgkmcnt(" #n ")" ::: "memory")
; #define PG8_BAR __builtin_amdgcn_s_barrier()
; #define PG8_SCHED __builtin_amdgcn_sched_barrier(0)
; template <class Epi>
; __device__ __forceinline__ void gemm_phase(LAS unsigned char* lds, const Gemm g, const StaticOrder& S, const Epi& E, int wave_s) {
;     ...
;             PG8_LDB(B0, 1, 0); PG8_LDB(B1, 1, 1); PG8_SCHED; PG8_LDA(At, 1, 0); PG8_STAGE(PG8_SA(0, 1), a2 + hstepA, voffA);
;             PG8_WAIT_V(8); PG8_WAIT_L(0); PG8_BAR; PG8_MMA(0, 0, At, B0); PG8_MMA(0, 1, At, B1); PG8_BAR; PG8_SCHED;
;             PG8_LDA(At, 1, 1); PG8_STAGE(PG8_SB(1, 0), b3, voffB); PG8_STAGE(PG8_SB(1, 1), b3 + hstepB, voffB); PG8_STAGE(PG8_SA(1, 0), a3, voffA);
;             PG8_WAIT_V(8); PG8_WAIT_L(0); PG8_BAR; PG8_MMA(1, 0, At, B0); PG8_MMA(1, 1, At, B1); PG8_BAR; PG8_SCHED;
;         }
;         if (wr == 0) PG8_BAR;
.Lpp_lead_10:
	s_waitcnt lgkmcnt(4)
	s_barrier
	s_waitcnt lgkmcnt(4)
	v_mfma_f32_16x16x32_bf16 v[106:109], v[130:133], v[186:189], v[106:109]
	v_mfma_f32_16x16x32_bf16 v[114:117], v[152:155], v[186:189], v[114:117]
	v_mfma_f32_16x16x32_bf16 v[98:101], v[130:133], v[194:197], v[98:101]
	v_mfma_f32_16x16x32_bf16 v[110:113], v[152:155], v[194:197], v[110:113]
	v_mfma_f32_16x16x32_bf16 v[94:97], v[130:133], v[202:205], v[94:97]
	v_mfma_f32_16x16x32_bf16 v[102:105], v[152:155], v[202:205], v[102:105]
	v_mfma_f32_16x16x32_bf16 v[90:93], v[130:133], v[212:215], v[90:93]
	v_mfma_f32_16x16x32_bf16 v[126:129], v[152:155], v[212:215], v[126:129]
	v_mfma_f32_16x16x32_bf16 v[106:109], v[134:137], v[190:193], v[106:109]
	v_mfma_f32_16x16x32_bf16 v[114:117], v[156:159], v[190:193], v[114:117]
	v_mfma_f32_16x16x32_bf16 v[98:101], v[134:137], v[198:201], v[98:101]
	v_mfma_f32_16x16x32_bf16 v[110:113], v[156:159], v[198:201], v[110:113]
	v_mfma_f32_16x16x32_bf16 v[94:97], v[134:137], v[208:211], v[94:97]
	v_mfma_f32_16x16x32_bf16 v[102:105], v[156:159], v[208:211], v[102:105]
	v_mfma_f32_16x16x32_bf16 v[90:93], v[134:137], v[222:225], v[90:93]
	v_mfma_f32_16x16x32_bf16 v[126:129], v[156:159], v[222:225], v[126:129]
	s_waitcnt lgkmcnt(0)
	v_mfma_f32_16x16x32_bf16 v[62:65], v[160:163], v[186:189], v[62:65]
	v_mfma_f32_16x16x32_bf16 v[34:37], v[178:181], v[186:189], v[34:37]
	v_mfma_f32_16x16x32_bf16 v[58:61], v[160:163], v[194:197], v[58:61]
	v_mfma_f32_16x16x32_bf16 v[30:33], v[178:181], v[194:197], v[30:33]
	v_mfma_f32_16x16x32_bf16 v[54:57], v[160:163], v[202:205], v[54:57]
	v_mfma_f32_16x16x32_bf16 v[26:29], v[178:181], v[202:205], v[26:29]
	v_mfma_f32_16x16x32_bf16 v[50:53], v[160:163], v[212:215], v[50:53]
	v_mfma_f32_16x16x32_bf16 v[22:25], v[178:181], v[212:215], v[22:25]
	v_mfma_f32_16x16x32_bf16 v[62:65], v[170:173], v[190:193], v[62:65]
	v_mfma_f32_16x16x32_bf16 v[34:37], v[182:185], v[190:193], v[34:37]
	v_mfma_f32_16x16x32_bf16 v[58:61], v[170:173], v[198:201], v[58:61]
	v_mfma_f32_16x16x32_bf16 v[30:33], v[182:185], v[198:201], v[30:33]
	v_mfma_f32_16x16x32_bf16 v[54:57], v[170:173], v[208:211], v[54:57]
	v_mfma_f32_16x16x32_bf16 v[26:29], v[182:185], v[208:211], v[26:29]
	v_mfma_f32_16x16x32_bf16 v[50:53], v[170:173], v[222:225], v[50:53]
	v_mfma_f32_16x16x32_bf16 v[22:25], v[182:185], v[222:225], v[22:25]
	s_barrier
	s_add_i32 s42, s58, s36
	v_lshl_add_u64 v[164:165], v[164:165], 0, s[84:85]
	s_mov_b32 m0, s42
	ds_read_b128 v[186:189], v247 offset:49152
	ds_read_b128 v[190:193], v247 offset:50176
	ds_read_b128 v[194:197], v247 offset:51200
	ds_read_b128 v[198:201], v247 offset:52224
	ds_read_b128 v[202:205], v247 offset:53248
	ds_read_b128 v[208:211], v247 offset:54272
	ds_read_b128 v[212:215], v247 offset:55296
	ds_read_b128 v[222:225], v247 offset:56320
	global_load_lds_dwordx4 v[164:165], off
	s_add_i32 m0, s42, 0x2000
	s_add_u32 s40, s40, 0x40080
	v_lshl_add_u64 v[164:165], v[174:175], 0, s[84:85]
	s_addc_u32 s41, s41, 0
	s_add_i32 s42, s59, s36
	global_load_lds_dwordx4 v[164:165], off
	v_lshl_add_u64 v[164:165], s[40:41], 0, v[12:13]
	s_mov_b32 m0, s42
	s_nop 0
	global_load_lds_dwordx4 v[164:165], off
	v_lshl_add_u64 v[164:165], s[40:41], 0, v[138:139]
	s_add_i32 m0, s42, 0x2000
	s_nop 0
	global_load_lds_dwordx4 v[164:165], off
	v_lshl_add_u64 v[164:165], v[176:177], 0, s[84:85]
	s_mov_b32 m0, s50
	s_nop 0
	global_load_lds_dwordx4 v[164:165], off
	v_lshl_add_u64 v[164:165], v[240:241], 0, s[84:85]
	s_mov_b32 m0, s51
	s_nop 0
	global_load_lds_dwordx4 v[164:165], off
	s_waitcnt vmcnt(8)
	s_waitcnt lgkmcnt(0)
	s_barrier
	s_waitcnt lgkmcnt(0)
	v_mfma_f32_16x16x32_bf16 v[86:89], v[130:133], v[186:189], v[86:89]
	v_mfma_f32_16x16x32_bf16 v[122:125], v[152:155], v[186:189], v[122:125]
	v_mfma_f32_16x16x32_bf16 v[82:85], v[130:133], v[194:197], v[82:85]
	v_mfma_f32_16x16x32_bf16 v[118:121], v[152:155], v[194:197], v[118:121]
	v_mfma_f32_16x16x32_bf16 v[78:81], v[130:133], v[202:205], v[78:81]
	v_mfma_f32_16x16x32_bf16 v[70:73], v[152:155], v[202:205], v[70:73]
	v_mfma_f32_16x16x32_bf16 v[74:77], v[130:133], v[212:215], v[74:77]
	v_mfma_f32_16x16x32_bf16 v[66:69], v[152:155], v[212:215], v[66:69]
	v_mfma_f32_16x16x32_bf16 v[86:89], v[134:137], v[190:193], v[86:89]
	v_mfma_f32_16x16x32_bf16 v[122:125], v[156:159], v[190:193], v[122:125]
	v_mfma_f32_16x16x32_bf16 v[82:85], v[134:137], v[198:201], v[82:85]
	v_mfma_f32_16x16x32_bf16 v[118:121], v[156:159], v[198:201], v[118:121]
	v_mfma_f32_16x16x32_bf16 v[78:81], v[134:137], v[208:211], v[78:81]
	v_mfma_f32_16x16x32_bf16 v[70:73], v[156:159], v[208:211], v[70:73]
	v_mfma_f32_16x16x32_bf16 v[74:77], v[134:137], v[222:225], v[74:77]
	v_mfma_f32_16x16x32_bf16 v[66:69], v[156:159], v[222:225], v[66:69]
	v_mfma_f32_16x16x32_bf16 v[46:49], v[160:163], v[186:189], v[46:49]
	v_mfma_f32_16x16x32_bf16 v[14:17], v[178:181], v[186:189], v[14:17]
	v_mfma_f32_16x16x32_bf16 v[42:45], v[160:163], v[194:197], v[42:45]
	v_mfma_f32_16x16x32_bf16 v[8:11], v[178:181], v[194:197], v[8:11]
	v_mfma_f32_16x16x32_bf16 v[38:41], v[160:163], v[202:205], v[38:41]
	v_mfma_f32_16x16x32_bf16 v[4:7], v[178:181], v[202:205], v[4:7]
	v_mfma_f32_16x16x32_bf16 v[18:21], v[160:163], v[212:215], v[18:21]
	v_mfma_f32_16x16x32_bf16 v[0:3], v[178:181], v[212:215], v[0:3]
	v_mfma_f32_16x16x32_bf16 v[46:49], v[170:173], v[190:193], v[46:49]
	v_mfma_f32_16x16x32_bf16 v[14:17], v[182:185], v[190:193], v[14:17]
	v_mfma_f32_16x16x32_bf16 v[42:45], v[170:173], v[198:201], v[42:45]
	v_mfma_f32_16x16x32_bf16 v[8:11], v[182:185], v[198:201], v[8:11]
	v_mfma_f32_16x16x32_bf16 v[38:41], v[170:173], v[208:211], v[38:41]
	v_mfma_f32_16x16x32_bf16 v[4:7], v[182:185], v[208:211], v[4:7]
	v_mfma_f32_16x16x32_bf16 v[18:21], v[170:173], v[222:225], v[18:21]
	v_mfma_f32_16x16x32_bf16 v[0:3], v[182:185], v[222:225], v[0:3]
	s_barrier
	s_add_i32 s83, s83, 2
	s_add_u32 s8, s8, 0x100
	s_addc_u32 s9, s9, 0
	s_add_u32 s68, s68, 0x100
	s_addc_u32 s69, s69, 0
	s_cmp_gt_u32 s83, 13
	s_cbranch_scc0 .LBB0_916
	s_and_b64 vcc, exec, s[22:23]
	s_cbranch_vccz .LBB0_919
	s_barrier

; #define PG8_STAGE(bufoff, gbase, voff) do { _Pragma("unroll") for (int _i = 0; _i < 2; ++_i) \
;         __builtin_amdgcn_global_load_lds((const unsigned*)((const char*)(gbase) + (voff)[_i]), (LAS unsigned*)(lds + (bufoff) + ldsw + _i * 8192), 16, 0, 0); } while (0)
; #define PG8_LDA(dst, b, h) do { _Pragma("unroll") for (int m = 0; m < 4; ++m) _Pragma("unroll") for (int k = 0; k < 2; ++k) dst[m][k] = *(const LAS bf16x8*)(lds + PG8_SA(b, h) + aoff + m * 2048 + k * 1024); } while (0)
; #define PG8_LDB(dst, b, h) do { _Pragma("unroll") for (int n = 0; n < 2; ++n) _Pragma("unroll") for (int k = 0; k < 2; ++k) dst[n][k] = *(const LAS bf16x8*)(lds + PG8_SB(b, h) + boff + n * 2048 + k * 1024); } while (0)
; #define PG8_MMA(ai, bj, At, Bt) do { __builtin_amdgcn_s_setprio(1); _Pragma("unroll") for (int m = 0; m < 4; ++m) _Pragma("unroll") for (int n = 0; n < 2; ++n) _Pragma("unroll") for (int k = 0; k < 2; ++k) \
;         acc[ai][bj][m][n] = __builtin_amdgcn_mfma_f32_16x16x32_bf16(Bt[n][k], At[m][k], acc[ai][bj][m][n], 0, 0, 0); __builtin_amdgcn_s_setprio(0); } while (0)
; #define PG8_WAIT_V(n) asm volatile("s_waitcnt vmcnt(" #n ")" ::: "memory")
; #define PG8_WAIT_L(n) asm volatile("s_waitcnt lgkmcnt(" #n ")" ::: "memory")
; #define PG8_BAR __builtin_amdgcn_s_barrier()
; #define PG8_SCHED __builtin_amdgcn_sched_barrier(0)
; template <class Epi>
; __device__ __forceinline__ void gemm_phase(LAS unsigned char* lds, const Gemm g, const StaticOrder& S, const Epi& E, int wave_s) {
;     ...
;             PG8_LDB(B0, 0, 0); PG8_LDB(B1, 0, 1); PG8_SCHED; PG8_LDA(At, 0, 0); PG8_STAGE(PG8_SA(1, 1), a1 + hstepA, voffA);
;             PG8_WAIT_V(8); PG8_WAIT_L(0); PG8_BAR; PG8_MMA(0, 0, At, B0); PG8_MMA(0, 1, At, B1); PG8_BAR; PG8_SCHED;
;             PG8_LDA(At, 0, 1); PG8_STAGE(PG8_SB(0, 0), b2, voffB); PG8_STAGE(PG8_SB(0, 1), b2 + hstepB, voffB); PG8_STAGE(PG8_SA(0, 0), a2, voffA);
;             PG8_WAIT_V(8); PG8_WAIT_L(0); PG8_BAR; PG8_MMA(1, 0, At, B0); PG8_MMA(1, 1, At, B1); PG8_BAR; PG8_SCHED;
;             PG8_LDB(B0, 1, 0); PG8_LDB(B1, 1, 1); PG8_SCHED; PG8_LDA(At, 1, 0); PG8_STAGE(PG8_SA(0, 1), a2 + hstepA, voffA);
.Lpp_lead_11:
	s_waitcnt lgkmcnt(4)
	s_barrier
	s_waitcnt lgkmcnt(4)
	v_mfma_f32_16x16x32_bf16 v[126:129], v[146:149], v[182:185], v[126:129]
	v_mfma_f32_16x16x32_bf16 v[122:125], v[154:157], v[182:185], v[122:125]
	v_mfma_f32_16x16x32_bf16 v[118:121], v[146:149], v[190:193], v[118:121]
	v_mfma_f32_16x16x32_bf16 v[114:117], v[154:157], v[190:193], v[114:117]
	v_mfma_f32_16x16x32_bf16 v[102:105], v[146:149], v[198:201], v[102:105]
	v_mfma_f32_16x16x32_bf16 v[98:101], v[154:157], v[198:201], v[98:101]
	v_mfma_f32_16x16x32_bf16 v[86:89], v[146:149], v[206:209], v[86:89]
	v_mfma_f32_16x16x32_bf16 v[82:85], v[154:157], v[206:209], v[82:85]
	v_mfma_f32_16x16x32_bf16 v[126:129], v[150:153], v[186:189], v[126:129]
	v_mfma_f32_16x16x32_bf16 v[122:125], v[158:161], v[186:189], v[122:125]
	v_mfma_f32_16x16x32_bf16 v[118:121], v[150:153], v[194:197], v[118:121]
	v_mfma_f32_16x16x32_bf16 v[114:117], v[158:161], v[194:197], v[114:117]
	v_mfma_f32_16x16x32_bf16 v[102:105], v[150:153], v[202:205], v[102:105]
	v_mfma_f32_16x16x32_bf16 v[98:101], v[158:161], v[202:205], v[98:101]
	v_mfma_f32_16x16x32_bf16 v[86:89], v[150:153], v[210:213], v[86:89]
	v_mfma_f32_16x16x32_bf16 v[82:85], v[158:161], v[210:213], v[82:85]
	s_waitcnt lgkmcnt(0)
	v_mfma_f32_16x16x32_bf16 v[110:113], v[162:165], v[182:185], v[110:113]
	v_mfma_f32_16x16x32_bf16 v[106:109], v[170:173], v[182:185], v[106:109]
	v_mfma_f32_16x16x32_bf16 v[94:97], v[162:165], v[190:193], v[94:97]
	v_mfma_f32_16x16x32_bf16 v[90:93], v[170:173], v[190:193], v[90:93]
	v_mfma_f32_16x16x32_bf16 v[78:81], v[162:165], v[198:201], v[78:81]
	v_mfma_f32_16x16x32_bf16 v[74:77], v[170:173], v[198:201], v[74:77]
	v_mfma_f32_16x16x32_bf16 v[70:73], v[162:165], v[206:209], v[70:73]
	v_mfma_f32_16x16x32_bf16 v[66:69], v[170:173], v[206:209], v[66:69]
	v_mfma_f32_16x16x32_bf16 v[110:113], v[166:169], v[186:189], v[110:113]
	v_mfma_f32_16x16x32_bf16 v[106:109], v[178:181], v[186:189], v[106:109]
	v_mfma_f32_16x16x32_bf16 v[94:97], v[166:169], v[194:197], v[94:97]
	v_mfma_f32_16x16x32_bf16 v[90:93], v[178:181], v[194:197], v[90:93]
	v_mfma_f32_16x16x32_bf16 v[78:81], v[166:169], v[202:205], v[78:81]
	v_mfma_f32_16x16x32_bf16 v[74:77], v[178:181], v[202:205], v[74:77]
	v_mfma_f32_16x16x32_bf16 v[70:73], v[166:169], v[210:213], v[70:73]
	v_mfma_f32_16x16x32_bf16 v[66:69], v[178:181], v[210:213], v[66:69]
	s_barrier
	s_add_i32 s53, s53, s36
	v_lshl_add_u64 v[174:175], s[26:27], 0, v[134:135]
	s_mov_b32 m0, s53
	ds_read_b128 v[182:185], v144 offset:16384
	ds_read_b128 v[186:189], v144 offset:17408
	ds_read_b128 v[190:193], v144 offset:18432
	ds_read_b128 v[194:197], v144 offset:19456
	ds_read_b128 v[198:201], v144 offset:20480
	ds_read_b128 v[202:205], v144 offset:21504
	ds_read_b128 v[206:209], v144 offset:22528
	ds_read_b128 v[210:213], v144 offset:23552
	global_load_lds_dwordx4 v[174:175], off
	s_add_i32 m0, s53, 0x2000
	s_add_u32 s58, s26, 0x40000
	v_lshl_add_u64 v[176:177], s[26:27], 0, v[130:131]
	s_addc_u32 s59, s27, 0
	s_add_i32 s53, s54, s36
	global_load_lds_dwordx4 v[176:177], off
	v_lshl_add_u64 v[214:215], s[58:59], 0, v[134:135]
	s_mov_b32 m0, s53
	v_lshl_add_u64 v[216:217], s[30:31], 0, v[132:133]
	global_load_lds_dwordx4 v[214:215], off
	v_lshl_add_u64 v[214:215], s[58:59], 0, v[130:131]
	s_add_i32 m0, s53, 0x2000
	s_nop 0
	global_load_lds_dwordx4 v[214:215], off
	v_lshl_add_u64 v[214:215], s[30:31], 0, v[136:137]
	s_mov_b32 m0, s37
	s_nop 0
	global_load_lds_dwordx4 v[214:215], off
	s_mov_b32 m0, s40
	s_nop 0
	global_load_lds_dwordx4 v[216:217], off
	s_waitcnt vmcnt(8)
	s_waitcnt lgkmcnt(0)
	s_barrier
	s_waitcnt lgkmcnt(0)
	v_mfma_f32_16x16x32_bf16 v[62:65], v[146:149], v[182:185], v[62:65]
	v_mfma_f32_16x16x32_bf16 v[58:61], v[154:157], v[182:185], v[58:61]
	v_mfma_f32_16x16x32_bf16 v[54:57], v[146:149], v[190:193], v[54:57]
	v_mfma_f32_16x16x32_bf16 v[50:53], v[154:157], v[190:193], v[50:53]
	v_mfma_f32_16x16x32_bf16 v[38:41], v[146:149], v[198:201], v[38:41]
	v_mfma_f32_16x16x32_bf16 v[34:37], v[154:157], v[198:201], v[34:37]
	v_mfma_f32_16x16x32_bf16 v[22:25], v[146:149], v[206:209], v[22:25]
	v_mfma_f32_16x16x32_bf16 v[18:21], v[154:157], v[206:209], v[18:21]
	v_mfma_f32_16x16x32_bf16 v[62:65], v[150:153], v[186:189], v[62:65]
	v_mfma_f32_16x16x32_bf16 v[58:61], v[158:161], v[186:189], v[58:61]
	v_mfma_f32_16x16x32_bf16 v[54:57], v[150:153], v[194:197], v[54:57]
	v_mfma_f32_16x16x32_bf16 v[50:53], v[158:161], v[194:197], v[50:53]
	v_mfma_f32_16x16x32_bf16 v[38:41], v[150:153], v[202:205], v[38:41]
	v_mfma_f32_16x16x32_bf16 v[34:37], v[158:161], v[202:205], v[34:37]
	v_mfma_f32_16x16x32_bf16 v[22:25], v[150:153], v[210:213], v[22:25]
	v_mfma_f32_16x16x32_bf16 v[18:21], v[158:161], v[210:213], v[18:21]
	v_mfma_f32_16x16x32_bf16 v[46:49], v[162:165], v[182:185], v[46:49]
	v_mfma_f32_16x16x32_bf16 v[42:45], v[170:173], v[182:185], v[42:45]
	v_mfma_f32_16x16x32_bf16 v[30:33], v[162:165], v[190:193], v[30:33]
	v_mfma_f32_16x16x32_bf16 v[26:29], v[170:173], v[190:193], v[26:29]
	v_mfma_f32_16x16x32_bf16 v[14:17], v[162:165], v[198:201], v[14:17]
	v_mfma_f32_16x16x32_bf16 v[8:11], v[170:173], v[198:201], v[8:11]
	v_mfma_f32_16x16x32_bf16 v[4:7], v[162:165], v[206:209], v[4:7]
	v_mfma_f32_16x16x32_bf16 v[0:3], v[170:173], v[206:209], v[0:3]
	v_mfma_f32_16x16x32_bf16 v[46:49], v[166:169], v[186:189], v[46:49]
	v_mfma_f32_16x16x32_bf16 v[42:45], v[178:181], v[186:189], v[42:45]
	v_mfma_f32_16x16x32_bf16 v[30:33], v[166:169], v[194:197], v[30:33]
	v_mfma_f32_16x16x32_bf16 v[26:29], v[178:181], v[194:197], v[26:29]
	v_mfma_f32_16x16x32_bf16 v[14:17], v[166:169], v[202:205], v[14:17]
	v_mfma_f32_16x16x32_bf16 v[8:11], v[178:181], v[202:205], v[8:11]
	v_mfma_f32_16x16x32_bf16 v[4:7], v[166:169], v[210:213], v[4:7]
	v_mfma_f32_16x16x32_bf16 v[0:3], v[178:181], v[210:213], v[0:3]
	s_barrier
	s_add_i32 s53, 0, 0x18000
	v_add_u32_e32 v145, s53, v143
	s_add_i32 s54, 0, 0x1c000
	ds_read_b128 v[146:149], v145
	ds_read_b128 v[150:153], v145 offset:1024
	ds_read_b128 v[154:157], v145 offset:2048
	ds_read_b128 v[158:161], v145 offset:3072
	v_add_u32_e32 v145, s54, v143
	ds_read_b128 v[182:185], v144 offset:32768
	ds_read_b128 v[186:189], v144 offset:33792
	ds_read_b128 v[190:193], v144 offset:34816
	ds_read_b128 v[194:197], v144 offset:35840
	ds_read_b128 v[198:201], v144 offset:36864
	ds_read_b128 v[202:205], v144 offset:37888
	ds_read_b128 v[206:209], v144 offset:38912
	ds_read_b128 v[210:213], v144 offset:39936
	ds_read_b128 v[162:165], v145
	ds_read_b128 v[166:169], v145 offset:1024
	ds_read_b128 v[170:173], v145 offset:2048
	ds_read_b128 v[178:181], v145 offset:3072
	s_add_u32 s30, s30, 0x40000
	s_addc_u32 s31, s31, 0
	s_mov_b32 m0, s41
	v_lshl_add_u64 v[218:219], s[30:31], 0, v[136:137]
	global_load_lds_dwordx4 v[218:219], off
	v_lshl_add_u64 v[218:219], s[30:31], 0, v[132:133]
	s_mov_b32 m0, s42
	s_nop 0
	global_load_lds_dwordx4 v[218:219], off
	s_waitcnt vmcnt(8)
	s_cmp_lg_u64 s[6:7], 0
	s_cbranch_scc1 .Lpp_lead_12
	s_waitcnt lgkmcnt(0)
; #define PG8_STAGE(bufoff, gbase, voff) do { _Pragma("unroll") for (int _i = 0; _i < 2; ++_i) \
;         __builtin_amdgcn_global_load_lds((const unsigned*)((const char*)(gbase) + (voff)[_i]), (LAS unsigned*)(lds + (bufoff) + ldsw + _i * 8192), 16, 0, 0); } while (0)
; #define PG8_LDA(dst, b, h) do { _Pragma("unroll") for (int m = 0; m < 4; ++m) _Pragma("unroll") for (int k = 0; k < 2; ++k) dst[m][k] = *(const LAS bf16x8*)(lds + PG8_SA(b, h) + aoff + m * 2048 + k * 1024); } while (0)
; #define PG8_LDB(dst, b, h) do { _Pragma("unroll") for (int n = 0; n < 2; ++n) _Pragma("unroll") for (int k = 0; k < 2; ++k) dst[n][k] = *(const LAS bf16x8*)(lds + PG8_SB(b, h) + boff + n * 2048 + k * 1024); } while (0)
; #define PG8_MMA(ai, bj, At, Bt) do { __builtin_amdgcn_s_setprio(1); _Pragma("unroll") for (int m = 0; m < 4; ++m) _Pragma("unroll") for (int n = 0; n < 2; ++n) _Pragma("unroll") for (int k = 0; k < 2; ++k) \
;         acc[ai][bj][m][n] = __builtin_amdgcn_mfma_f32_16x16x32_bf16(Bt[n][k], At[m][k], acc[ai][bj][m][n], 0, 0, 0); __builtin_amdgcn_s_setprio(0); } while (0)
; #define PG8_WAIT_V(n) asm volatile("s_waitcnt vmcnt(" #n ")" ::: "memory")
; #define PG8_WAIT_L(n) asm volatile("s_waitcnt lgkmcnt(" #n ")" ::: "memory")
; #define PG8_BAR __builtin_amdgcn_s_barrier()
; #define PG8_SCHED __builtin_amdgcn_sched_barrier(0)
; template <class Epi>
; __device__ __forceinline__ void gemm_phase(LAS unsigned char* lds, const Gemm g, const StaticOrder& S, const Epi& E, int wave_s) {
;     ...
;             PG8_LDB(B0, 1, 0); PG8_LDB(B1, 1, 1); PG8_SCHED; PG8_LDA(At, 1, 0); PG8_STAGE(PG8_SA(0, 1), a2 + hstepA, voffA);
;             PG8_WAIT_V(8); PG8_WAIT_L(0); PG8_BAR; PG8_MMA(0, 0, At, B0); PG8_MMA(0, 1, At, B1); PG8_BAR; PG8_SCHED;
;             PG8_LDA(At, 1, 1); PG8_STAGE(PG8_SB(1, 0), b3, voffB); PG8_STAGE(PG8_SB(1, 1), b3 + hstepB, voffB); PG8_STAGE(PG8_SA(1, 0), a3, voffA);
;             PG8_WAIT_V(8); PG8_WAIT_L(0); PG8_BAR; PG8_MMA(1, 0, At, B0); PG8_MMA(1, 1, At, B1); PG8_BAR; PG8_SCHED;
;         }
;         if (wr == 0) PG8_BAR;
.Lpp_lead_12:
	s_waitcnt lgkmcnt(4)
	s_barrier
	s_waitcnt lgkmcnt(4)
	v_mfma_f32_16x16x32_bf16 v[126:129], v[146:149], v[182:185], v[126:129]
	v_mfma_f32_16x16x32_bf16 v[122:125], v[154:157], v[182:185], v[122:125]
	v_mfma_f32_16x16x32_bf16 v[118:121], v[146:149], v[190:193], v[118:121]
	v_mfma_f32_16x16x32_bf16 v[114:117], v[154:157], v[190:193], v[114:117]
	v_mfma_f32_16x16x32_bf16 v[102:105], v[146:149], v[198:201], v[102:105]
	v_mfma_f32_16x16x32_bf16 v[98:101], v[154:157], v[198:201], v[98:101]
	v_mfma_f32_16x16x32_bf16 v[86:89], v[146:149], v[206:209], v[86:89]
	v_mfma_f32_16x16x32_bf16 v[82:85], v[154:157], v[206:209], v[82:85]
	v_mfma_f32_16x16x32_bf16 v[126:129], v[150:153], v[186:189], v[126:129]
	v_mfma_f32_16x16x32_bf16 v[122:125], v[158:161], v[186:189], v[122:125]
	v_mfma_f32_16x16x32_bf16 v[118:121], v[150:153], v[194:197], v[118:121]
	v_mfma_f32_16x16x32_bf16 v[114:117], v[158:161], v[194:197], v[114:117]
	v_mfma_f32_16x16x32_bf16 v[102:105], v[150:153], v[202:205], v[102:105]
	v_mfma_f32_16x16x32_bf16 v[98:101], v[158:161], v[202:205], v[98:101]
	v_mfma_f32_16x16x32_bf16 v[86:89], v[150:153], v[210:213], v[86:89]
	v_mfma_f32_16x16x32_bf16 v[82:85], v[158:161], v[210:213], v[82:85]
	s_waitcnt lgkmcnt(0)
	v_mfma_f32_16x16x32_bf16 v[110:113], v[162:165], v[182:185], v[110:113]
	v_mfma_f32_16x16x32_bf16 v[106:109], v[170:173], v[182:185], v[106:109]
	v_mfma_f32_16x16x32_bf16 v[94:97], v[162:165], v[190:193], v[94:97]
	v_mfma_f32_16x16x32_bf16 v[90:93], v[170:173], v[190:193], v[90:93]
	v_mfma_f32_16x16x32_bf16 v[78:81], v[162:165], v[198:201], v[78:81]
	v_mfma_f32_16x16x32_bf16 v[74:77], v[170:173], v[198:201], v[74:77]
	v_mfma_f32_16x16x32_bf16 v[70:73], v[162:165], v[206:209], v[70:73]
	v_mfma_f32_16x16x32_bf16 v[66:69], v[170:173], v[206:209], v[66:69]
	v_mfma_f32_16x16x32_bf16 v[110:113], v[166:169], v[186:189], v[110:113]
	v_mfma_f32_16x16x32_bf16 v[106:109], v[178:181], v[186:189], v[106:109]
	v_mfma_f32_16x16x32_bf16 v[94:97], v[166:169], v[194:197], v[94:97]
	v_mfma_f32_16x16x32_bf16 v[90:93], v[178:181], v[194:197], v[90:93]
	v_mfma_f32_16x16x32_bf16 v[78:81], v[166:169], v[202:205], v[78:81]
	v_mfma_f32_16x16x32_bf16 v[74:77], v[178:181], v[202:205], v[74:77]
	v_mfma_f32_16x16x32_bf16 v[70:73], v[166:169], v[210:213], v[70:73]
	v_mfma_f32_16x16x32_bf16 v[66:69], v[178:181], v[210:213], v[66:69]
	s_barrier
	s_add_i32 s30, s53, s36
	v_lshl_add_u64 v[174:175], v[174:175], 0, s[84:85]
	s_mov_b32 m0, s30
	ds_read_b128 v[182:185], v144 offset:49152
	ds_read_b128 v[186:189], v144 offset:50176
	ds_read_b128 v[190:193], v144 offset:51200
	ds_read_b128 v[194:197], v144 offset:52224
	ds_read_b128 v[198:201], v144 offset:53248
	ds_read_b128 v[202:205], v144 offset:54272
	ds_read_b128 v[206:209], v144 offset:55296
	ds_read_b128 v[210:213], v144 offset:56320
	global_load_lds_dwordx4 v[174:175], off
	s_add_i32 m0, s30, 0x2000
	s_add_u32 s26, s26, 0x40080
	v_lshl_add_u64 v[174:175], v[176:177], 0, s[84:85]
	s_addc_u32 s27, s27, 0
	s_add_i32 s30, s54, s36
	global_load_lds_dwordx4 v[174:175], off
	v_lshl_add_u64 v[174:175], s[26:27], 0, v[134:135]
	s_mov_b32 m0, s30
	s_nop 0
	global_load_lds_dwordx4 v[174:175], off
	v_lshl_add_u64 v[174:175], s[26:27], 0, v[130:131]
	s_add_i32 m0, s30, 0x2000
	s_nop 0
	global_load_lds_dwordx4 v[174:175], off
	v_lshl_add_u64 v[174:175], v[214:215], 0, s[84:85]
	s_mov_b32 m0, s43
	s_nop 0
	global_load_lds_dwordx4 v[174:175], off
	v_lshl_add_u64 v[174:175], v[216:217], 0, s[84:85]
	s_mov_b32 m0, s44
	s_nop 0
	global_load_lds_dwordx4 v[174:175], off
	s_waitcnt vmcnt(8)
	s_waitcnt lgkmcnt(0)
	s_barrier
	s_waitcnt lgkmcnt(0)
	v_mfma_f32_16x16x32_bf16 v[62:65], v[146:149], v[182:185], v[62:65]
	v_mfma_f32_16x16x32_bf16 v[58:61], v[154:157], v[182:185], v[58:61]
	v_mfma_f32_16x16x32_bf16 v[54:57], v[146:149], v[190:193], v[54:57]
	v_mfma_f32_16x16x32_bf16 v[50:53], v[154:157], v[190:193], v[50:53]
	v_mfma_f32_16x16x32_bf16 v[38:41], v[146:149], v[198:201], v[38:41]
	v_mfma_f32_16x16x32_bf16 v[34:37], v[154:157], v[198:201], v[34:37]
	v_mfma_f32_16x16x32_bf16 v[22:25], v[146:149], v[206:209], v[22:25]
	v_mfma_f32_16x16x32_bf16 v[18:21], v[154:157], v[206:209], v[18:21]
	v_mfma_f32_16x16x32_bf16 v[62:65], v[150:153], v[186:189], v[62:65]
	v_mfma_f32_16x16x32_bf16 v[58:61], v[158:161], v[186:189], v[58:61]
	v_mfma_f32_16x16x32_bf16 v[54:57], v[150:153], v[194:197], v[54:57]
	v_mfma_f32_16x16x32_bf16 v[50:53], v[158:161], v[194:197], v[50:53]
	v_mfma_f32_16x16x32_bf16 v[38:41], v[150:153], v[202:205], v[38:41]
	v_mfma_f32_16x16x32_bf16 v[34:37], v[158:161], v[202:205], v[34:37]
	v_mfma_f32_16x16x32_bf16 v[22:25], v[150:153], v[210:213], v[22:25]
	v_mfma_f32_16x16x32_bf16 v[18:21], v[158:161], v[210:213], v[18:21]
	v_mfma_f32_16x16x32_bf16 v[46:49], v[162:165], v[182:185], v[46:49]
	v_mfma_f32_16x16x32_bf16 v[42:45], v[170:173], v[182:185], v[42:45]
	v_mfma_f32_16x16x32_bf16 v[30:33], v[162:165], v[190:193], v[30:33]
	v_mfma_f32_16x16x32_bf16 v[26:29], v[170:173], v[190:193], v[26:29]
	v_mfma_f32_16x16x32_bf16 v[14:17], v[162:165], v[198:201], v[14:17]
	v_mfma_f32_16x16x32_bf16 v[8:11], v[170:173], v[198:201], v[8:11]
	v_mfma_f32_16x16x32_bf16 v[4:7], v[162:165], v[206:209], v[4:7]
	v_mfma_f32_16x16x32_bf16 v[0:3], v[170:173], v[206:209], v[0:3]
	v_mfma_f32_16x16x32_bf16 v[46:49], v[166:169], v[186:189], v[46:49]
	v_mfma_f32_16x16x32_bf16 v[42:45], v[178:181], v[186:189], v[42:45]
	v_mfma_f32_16x16x32_bf16 v[30:33], v[166:169], v[194:197], v[30:33]
	v_mfma_f32_16x16x32_bf16 v[26:29], v[178:181], v[194:197], v[26:29]
	v_mfma_f32_16x16x32_bf16 v[14:17], v[166:169], v[202:205], v[14:17]
	v_mfma_f32_16x16x32_bf16 v[8:11], v[178:181], v[202:205], v[8:11]
	v_mfma_f32_16x16x32_bf16 v[4:7], v[166:169], v[210:213], v[4:7]
	v_mfma_f32_16x16x32_bf16 v[0:3], v[178:181], v[210:213], v[0:3]
	s_barrier
	s_add_i32 s52, s52, 2
	s_add_u32 s22, s22, 0x100
	s_addc_u32 s23, s23, 0
	s_add_u32 s50, s50, 0x100
	s_addc_u32 s51, s51, 0
	s_cmp_gt_u32 s52, 13
	s_cbranch_scc0 .LBB0_1044
	s_and_b64 vcc, exec, s[6:7]
	s_cbranch_vccz .LBB0_1047
	s_barrier

; #define PG8_STAGE(bufoff, gbase, voff) do { _Pragma("unroll") for (int _i = 0; _i < 2; ++_i) \
;         __builtin_amdgcn_global_load_lds((const unsigned*)((const char*)(gbase) + (voff)[_i]), (LAS unsigned*)(lds + (bufoff) + ldsw + _i * 8192), 16, 0, 0); } while (0)
; #define PG8_LDA(dst, b, h) do { _Pragma("unroll") for (int m = 0; m < 4; ++m) _Pragma("unroll") for (int k = 0; k < 2; ++k) dst[m][k] = *(const LAS bf16x8*)(lds + PG8_SA(b, h) + aoff + m * 2048 + k * 1024); } while (0)
; #define PG8_LDB(dst, b, h) do { _Pragma("unroll") for (int n = 0; n < 2; ++n) _Pragma("unroll") for (int k = 0; k < 2; ++k) dst[n][k] = *(const LAS bf16x8*)(lds + PG8_SB(b, h) + boff + n * 2048 + k * 1024); } while (0)
; #define PG8_MMA(ai, bj, At, Bt) do { __builtin_amdgcn_s_setprio(1); _Pragma("unroll") for (int m = 0; m < 4; ++m) _Pragma("unroll") for (int n = 0; n < 2; ++n) _Pragma("unroll") for (int k = 0; k < 2; ++k) \
;         acc[ai][bj][m][n] = __builtin_amdgcn_mfma_f32_16x16x32_bf16(Bt[n][k], At[m][k], acc[ai][bj][m][n], 0, 0, 0); __builtin_amdgcn_s_setprio(0); } while (0)
; #define PG8_WAIT_V(n) asm volatile("s_waitcnt vmcnt(" #n ")" ::: "memory")
; #define PG8_WAIT_L(n) asm volatile("s_waitcnt lgkmcnt(" #n ")" ::: "memory")
; #define PG8_BAR __builtin_amdgcn_s_barrier()
; #define PG8_SCHED __builtin_amdgcn_sched_barrier(0)
; template <class Epi>
; __device__ __forceinline__ void gemm_phase(LAS unsigned char* lds, const Gemm g, const StaticOrder& S, const Epi& E, int wave_s) {
;     ...
;             PG8_LDB(B0, 0, 0); PG8_LDB(B1, 0, 1); PG8_SCHED; PG8_LDA(At, 0, 0); PG8_STAGE(PG8_SA(1, 1), a1 + hstepA, voffA);
;             PG8_WAIT_V(8); PG8_WAIT_L(0); PG8_BAR; PG8_MMA(0, 0, At, B0); PG8_MMA(0, 1, At, B1); PG8_BAR; PG8_SCHED;
;             PG8_LDA(At, 0, 1); PG8_STAGE(PG8_SB(0, 0), b2, voffB); PG8_STAGE(PG8_SB(0, 1), b2 + hstepB, voffB); PG8_STAGE(PG8_SA(0, 0), a2, voffA);
;             PG8_WAIT_V(8); PG8_WAIT_L(0); PG8_BAR; PG8_MMA(1, 0, At, B0); PG8_MMA(1, 1, At, B1); PG8_BAR; PG8_SCHED;
;             PG8_LDB(B0, 1, 0); PG8_LDB(B1, 1, 1); PG8_SCHED; PG8_LDA(At, 1, 0); PG8_STAGE(PG8_SA(0, 1), a2 + hstepA, voffA);
.Lpp_lead_13:
	s_waitcnt lgkmcnt(4)
	s_barrier
	s_waitcnt lgkmcnt(4)
	v_mfma_f32_16x16x32_bf16 v[158:161], v[122:125], v[162:165], v[158:161]
	v_mfma_f32_16x16x32_bf16 v[154:157], v[130:133], v[162:165], v[154:157]
	v_mfma_f32_16x16x32_bf16 v[118:121], v[122:125], v[170:173], v[118:121]
	v_mfma_f32_16x16x32_bf16 v[114:117], v[130:133], v[170:173], v[114:117]
	v_mfma_f32_16x16x32_bf16 v[110:113], v[122:125], v[194:197], v[110:113]
	v_mfma_f32_16x16x32_bf16 v[106:109], v[130:133], v[194:197], v[106:109]
	v_mfma_f32_16x16x32_bf16 v[102:105], v[122:125], v[202:205], v[102:105]
	v_mfma_f32_16x16x32_bf16 v[98:101], v[130:133], v[202:205], v[98:101]
	v_mfma_f32_16x16x32_bf16 v[158:161], v[126:129], v[166:169], v[158:161]
	v_mfma_f32_16x16x32_bf16 v[154:157], v[134:137], v[166:169], v[154:157]
	v_mfma_f32_16x16x32_bf16 v[118:121], v[126:129], v[190:193], v[118:121]
	v_mfma_f32_16x16x32_bf16 v[114:117], v[134:137], v[190:193], v[114:117]
	v_mfma_f32_16x16x32_bf16 v[110:113], v[126:129], v[198:201], v[110:113]
	v_mfma_f32_16x16x32_bf16 v[106:109], v[134:137], v[198:201], v[106:109]
	v_mfma_f32_16x16x32_bf16 v[102:105], v[126:129], v[206:209], v[102:105]
	v_mfma_f32_16x16x32_bf16 v[98:101], v[134:137], v[206:209], v[98:101]
	s_waitcnt lgkmcnt(0)
	v_mfma_f32_16x16x32_bf16 v[94:97], v[138:141], v[162:165], v[94:97]
	v_mfma_f32_16x16x32_bf16 v[90:93], v[146:149], v[162:165], v[90:93]
	v_mfma_f32_16x16x32_bf16 v[86:89], v[138:141], v[170:173], v[86:89]
	v_mfma_f32_16x16x32_bf16 v[82:85], v[146:149], v[170:173], v[82:85]
	v_mfma_f32_16x16x32_bf16 v[78:81], v[138:141], v[194:197], v[78:81]
	v_mfma_f32_16x16x32_bf16 v[74:77], v[146:149], v[194:197], v[74:77]
	v_mfma_f32_16x16x32_bf16 v[38:41], v[138:141], v[202:205], v[38:41]
	v_mfma_f32_16x16x32_bf16 v[34:37], v[146:149], v[202:205], v[34:37]
	v_mfma_f32_16x16x32_bf16 v[94:97], v[142:145], v[166:169], v[94:97]
	v_mfma_f32_16x16x32_bf16 v[90:93], v[150:153], v[166:169], v[90:93]
	v_mfma_f32_16x16x32_bf16 v[86:89], v[142:145], v[190:193], v[86:89]
	v_mfma_f32_16x16x32_bf16 v[82:85], v[150:153], v[190:193], v[82:85]
	v_mfma_f32_16x16x32_bf16 v[78:81], v[142:145], v[198:201], v[78:81]
	v_mfma_f32_16x16x32_bf16 v[74:77], v[150:153], v[198:201], v[74:77]
	v_mfma_f32_16x16x32_bf16 v[38:41], v[142:145], v[206:209], v[38:41]
	v_mfma_f32_16x16x32_bf16 v[34:37], v[150:153], v[206:209], v[34:37]
	s_barrier
	s_add_i32 s47, s47, s20
	v_lshl_add_u64 v[174:175], s[6:7], 0, v[182:183]
	s_mov_b32 m0, s47
	ds_read_b128 v[162:165], v245 offset:16384
	ds_read_b128 v[166:169], v245 offset:17408
	ds_read_b128 v[170:173], v245 offset:18432
	ds_read_b128 v[190:193], v245 offset:19456
	ds_read_b128 v[194:197], v245 offset:20480
	ds_read_b128 v[198:201], v245 offset:21504
	ds_read_b128 v[202:205], v245 offset:22528
	ds_read_b128 v[206:209], v245 offset:23552
	global_load_lds_dwordx4 v[174:175], off
	s_add_i32 m0, s47, 0x2000
	s_add_u32 s48, s6, 0x40000
	v_lshl_add_u64 v[176:177], s[6:7], 0, v[178:179]
	s_addc_u32 s49, s7, 0
	s_add_i32 s47, s50, s20
	global_load_lds_dwordx4 v[176:177], off
	v_lshl_add_u64 v[210:211], s[48:49], 0, v[182:183]
	s_mov_b32 m0, s47
	v_lshl_add_u64 v[212:213], s[8:9], 0, v[180:181]
	global_load_lds_dwordx4 v[210:211], off
	v_lshl_add_u64 v[210:211], s[48:49], 0, v[178:179]
	s_add_i32 m0, s47, 0x2000
	s_nop 0
	global_load_lds_dwordx4 v[210:211], off
	v_lshl_add_u64 v[210:211], s[8:9], 0, v[184:185]
	s_mov_b32 m0, s42
	s_nop 0
	global_load_lds_dwordx4 v[210:211], off
	s_mov_b32 m0, s43
	s_nop 0
	global_load_lds_dwordx4 v[212:213], off
	s_waitcnt vmcnt(8)
	s_waitcnt lgkmcnt(0)
	s_barrier
	s_waitcnt lgkmcnt(0)
	v_mfma_f32_16x16x32_bf16 v[70:73], v[122:125], v[162:165], v[70:73]
	v_mfma_f32_16x16x32_bf16 v[66:69], v[130:133], v[162:165], v[66:69]
	v_mfma_f32_16x16x32_bf16 v[62:65], v[122:125], v[170:173], v[62:65]
	v_mfma_f32_16x16x32_bf16 v[58:61], v[130:133], v[170:173], v[58:61]
	v_mfma_f32_16x16x32_bf16 v[54:57], v[122:125], v[194:197], v[54:57]
	v_mfma_f32_16x16x32_bf16 v[50:53], v[130:133], v[194:197], v[50:53]
	v_mfma_f32_16x16x32_bf16 v[46:49], v[122:125], v[202:205], v[46:49]
	v_mfma_f32_16x16x32_bf16 v[42:45], v[130:133], v[202:205], v[42:45]
	v_mfma_f32_16x16x32_bf16 v[70:73], v[126:129], v[166:169], v[70:73]
	v_mfma_f32_16x16x32_bf16 v[66:69], v[134:137], v[166:169], v[66:69]
	v_mfma_f32_16x16x32_bf16 v[62:65], v[126:129], v[190:193], v[62:65]
	v_mfma_f32_16x16x32_bf16 v[58:61], v[134:137], v[190:193], v[58:61]
	v_mfma_f32_16x16x32_bf16 v[54:57], v[126:129], v[198:201], v[54:57]
	v_mfma_f32_16x16x32_bf16 v[50:53], v[134:137], v[198:201], v[50:53]
	v_mfma_f32_16x16x32_bf16 v[46:49], v[126:129], v[206:209], v[46:49]
	v_mfma_f32_16x16x32_bf16 v[42:45], v[134:137], v[206:209], v[42:45]
	v_mfma_f32_16x16x32_bf16 v[30:33], v[138:141], v[162:165], v[30:33]
	v_mfma_f32_16x16x32_bf16 v[26:29], v[146:149], v[162:165], v[26:29]
	v_mfma_f32_16x16x32_bf16 v[22:25], v[138:141], v[170:173], v[22:25]
	v_mfma_f32_16x16x32_bf16 v[18:21], v[146:149], v[170:173], v[18:21]
	v_mfma_f32_16x16x32_bf16 v[14:17], v[138:141], v[194:197], v[14:17]
	v_mfma_f32_16x16x32_bf16 v[8:11], v[146:149], v[194:197], v[8:11]
	v_mfma_f32_16x16x32_bf16 v[4:7], v[138:141], v[202:205], v[4:7]
	v_mfma_f32_16x16x32_bf16 v[0:3], v[146:149], v[202:205], v[0:3]
	v_mfma_f32_16x16x32_bf16 v[30:33], v[142:145], v[166:169], v[30:33]
	v_mfma_f32_16x16x32_bf16 v[26:29], v[150:153], v[166:169], v[26:29]
	v_mfma_f32_16x16x32_bf16 v[22:25], v[142:145], v[190:193], v[22:25]
	v_mfma_f32_16x16x32_bf16 v[18:21], v[150:153], v[190:193], v[18:21]
	v_mfma_f32_16x16x32_bf16 v[14:17], v[142:145], v[198:201], v[14:17]
	v_mfma_f32_16x16x32_bf16 v[8:11], v[150:153], v[198:201], v[8:11]
	v_mfma_f32_16x16x32_bf16 v[4:7], v[142:145], v[206:209], v[4:7]
	v_mfma_f32_16x16x32_bf16 v[0:3], v[150:153], v[206:209], v[0:3]
	s_barrier
	s_add_i32 s47, 0, 0x18000
	v_add_u32_e32 v12, s47, v243
	s_add_i32 s48, 0, 0x1c000
	ds_read_b128 v[122:125], v12
	ds_read_b128 v[126:129], v12 offset:1024
	ds_read_b128 v[130:133], v12 offset:2048
	ds_read_b128 v[134:137], v12 offset:3072
	v_add_u32_e32 v12, s48, v243
	ds_read_b128 v[162:165], v245 offset:32768
	ds_read_b128 v[166:169], v245 offset:33792
	ds_read_b128 v[170:173], v245 offset:34816
	ds_read_b128 v[190:193], v245 offset:35840
	ds_read_b128 v[194:197], v245 offset:36864
	ds_read_b128 v[198:201], v245 offset:37888
	ds_read_b128 v[202:205], v245 offset:38912
	ds_read_b128 v[206:209], v245 offset:39936
	ds_read_b128 v[138:141], v12
	ds_read_b128 v[142:145], v12 offset:1024
	ds_read_b128 v[146:149], v12 offset:2048
	ds_read_b128 v[150:153], v12 offset:3072
	s_add_u32 s8, s8, 0x40000
	s_addc_u32 s9, s9, 0
	s_mov_b32 m0, s82
	v_lshl_add_u64 v[214:215], s[8:9], 0, v[184:185]
	global_load_lds_dwordx4 v[214:215], off
	v_lshl_add_u64 v[214:215], s[8:9], 0, v[180:181]
	s_mov_b32 m0, s83
	s_nop 0
	global_load_lds_dwordx4 v[214:215], off
	s_waitcnt vmcnt(8)
	s_cmp_lg_u64 s[0:1], 0
	s_cbranch_scc1 .Lpp_lead_14
	s_waitcnt lgkmcnt(0)
; #define PG8_STAGE(bufoff, gbase, voff) do { _Pragma("unroll") for (int _i = 0; _i < 2; ++_i) \
;         __builtin_amdgcn_global_load_lds((const unsigned*)((const char*)(gbase) + (voff)[_i]), (LAS unsigned*)(lds + (bufoff) + ldsw + _i * 8192), 16, 0, 0); } while (0)
; #define PG8_LDA(dst, b, h) do { _Pragma("unroll") for (int m = 0; m < 4; ++m) _Pragma("unroll") for (int k = 0; k < 2; ++k) dst[m][k] = *(const LAS bf16x8*)(lds + PG8_SA(b, h) + aoff + m * 2048 + k * 1024); } while (0)
; #define PG8_LDB(dst, b, h) do { _Pragma("unroll") for (int n = 0; n < 2; ++n) _Pragma("unroll") for (int k = 0; k < 2; ++k) dst[n][k] = *(const LAS bf16x8*)(lds + PG8_SB(b, h) + boff + n * 2048 + k * 1024); } while (0)
; #define PG8_MMA(ai, bj, At, Bt) do { __builtin_amdgcn_s_setprio(1); _Pragma("unroll") for (int m = 0; m < 4; ++m) _Pragma("unroll") for (int n = 0; n < 2; ++n) _Pragma("unroll") for (int k = 0; k < 2; ++k) \
;         acc[ai][bj][m][n] = __builtin_amdgcn_mfma_f32_16x16x32_bf16(Bt[n][k], At[m][k], acc[ai][bj][m][n], 0, 0, 0); __builtin_amdgcn_s_setprio(0); } while (0)
; #define PG8_WAIT_V(n) asm volatile("s_waitcnt vmcnt(" #n ")" ::: "memory")
; #define PG8_WAIT_L(n) asm volatile("s_waitcnt lgkmcnt(" #n ")" ::: "memory")
; #define PG8_BAR __builtin_amdgcn_s_barrier()
; #define PG8_SCHED __builtin_amdgcn_sched_barrier(0)
; template <class Epi>
; __device__ __forceinline__ void gemm_phase(LAS unsigned char* lds, const Gemm g, const StaticOrder& S, const Epi& E, int wave_s) {
;     ...
;             PG8_LDB(B0, 1, 0); PG8_LDB(B1, 1, 1); PG8_SCHED; PG8_LDA(At, 1, 0); PG8_STAGE(PG8_SA(0, 1), a2 + hstepA, voffA);
;             PG8_WAIT_V(8); PG8_WAIT_L(0); PG8_BAR; PG8_MMA(0, 0, At, B0); PG8_MMA(0, 1, At, B1); PG8_BAR; PG8_SCHED;
;             PG8_LDA(At, 1, 1); PG8_STAGE(PG8_SB(1, 0), b3, voffB); PG8_STAGE(PG8_SB(1, 1), b3 + hstepB, voffB); PG8_STAGE(PG8_SA(1, 0), a3, voffA);
;             PG8_WAIT_V(8); PG8_WAIT_L(0); PG8_BAR; PG8_MMA(1, 0, At, B0); PG8_MMA(1, 1, At, B1); PG8_BAR; PG8_SCHED;
;         }
;         if (wr == 0) PG8_BAR;
.Lpp_lead_14:
	s_waitcnt lgkmcnt(4)
	s_barrier
	s_waitcnt lgkmcnt(4)
	v_mfma_f32_16x16x32_bf16 v[158:161], v[122:125], v[162:165], v[158:161]
	v_mfma_f32_16x16x32_bf16 v[154:157], v[130:133], v[162:165], v[154:157]
	v_mfma_f32_16x16x32_bf16 v[118:121], v[122:125], v[170:173], v[118:121]
	v_mfma_f32_16x16x32_bf16 v[114:117], v[130:133], v[170:173], v[114:117]
	v_mfma_f32_16x16x32_bf16 v[110:113], v[122:125], v[194:197], v[110:113]
	v_mfma_f32_16x16x32_bf16 v[106:109], v[130:133], v[194:197], v[106:109]
	v_mfma_f32_16x16x32_bf16 v[102:105], v[122:125], v[202:205], v[102:105]
	v_mfma_f32_16x16x32_bf16 v[98:101], v[130:133], v[202:205], v[98:101]
	v_mfma_f32_16x16x32_bf16 v[158:161], v[126:129], v[166:169], v[158:161]
	v_mfma_f32_16x16x32_bf16 v[154:157], v[134:137], v[166:169], v[154:157]
	v_mfma_f32_16x16x32_bf16 v[118:121], v[126:129], v[190:193], v[118:121]
	v_mfma_f32_16x16x32_bf16 v[114:117], v[134:137], v[190:193], v[114:117]
	v_mfma_f32_16x16x32_bf16 v[110:113], v[126:129], v[198:201], v[110:113]
	v_mfma_f32_16x16x32_bf16 v[106:109], v[134:137], v[198:201], v[106:109]
	v_mfma_f32_16x16x32_bf16 v[102:105], v[126:129], v[206:209], v[102:105]
	v_mfma_f32_16x16x32_bf16 v[98:101], v[134:137], v[206:209], v[98:101]
	s_waitcnt lgkmcnt(0)
	v_mfma_f32_16x16x32_bf16 v[94:97], v[138:141], v[162:165], v[94:97]
	v_mfma_f32_16x16x32_bf16 v[90:93], v[146:149], v[162:165], v[90:93]
	v_mfma_f32_16x16x32_bf16 v[86:89], v[138:141], v[170:173], v[86:89]
	v_mfma_f32_16x16x32_bf16 v[82:85], v[146:149], v[170:173], v[82:85]
	v_mfma_f32_16x16x32_bf16 v[78:81], v[138:141], v[194:197], v[78:81]
	v_mfma_f32_16x16x32_bf16 v[74:77], v[146:149], v[194:197], v[74:77]
	v_mfma_f32_16x16x32_bf16 v[38:41], v[138:141], v[202:205], v[38:41]
	v_mfma_f32_16x16x32_bf16 v[34:37], v[146:149], v[202:205], v[34:37]
	v_mfma_f32_16x16x32_bf16 v[94:97], v[142:145], v[166:169], v[94:97]
	v_mfma_f32_16x16x32_bf16 v[90:93], v[150:153], v[166:169], v[90:93]
	v_mfma_f32_16x16x32_bf16 v[86:89], v[142:145], v[190:193], v[86:89]
	v_mfma_f32_16x16x32_bf16 v[82:85], v[150:153], v[190:193], v[82:85]
	v_mfma_f32_16x16x32_bf16 v[78:81], v[142:145], v[198:201], v[78:81]
	v_mfma_f32_16x16x32_bf16 v[74:77], v[150:153], v[198:201], v[74:77]
	v_mfma_f32_16x16x32_bf16 v[38:41], v[142:145], v[206:209], v[38:41]
	v_mfma_f32_16x16x32_bf16 v[34:37], v[150:153], v[206:209], v[34:37]
	s_barrier
	s_add_i32 s8, s47, s20
	v_lshl_add_u64 v[174:175], v[174:175], 0, s[84:85]
	s_mov_b32 m0, s8
	ds_read_b128 v[162:165], v245 offset:49152
	ds_read_b128 v[166:169], v245 offset:50176
	ds_read_b128 v[170:173], v245 offset:51200
	ds_read_b128 v[190:193], v245 offset:52224
	ds_read_b128 v[194:197], v245 offset:53248
	ds_read_b128 v[198:201], v245 offset:54272
	ds_read_b128 v[202:205], v245 offset:55296
	ds_read_b128 v[206:209], v245 offset:56320
	global_load_lds_dwordx4 v[174:175], off
	s_add_i32 m0, s8, 0x2000
	s_add_u32 s6, s6, 0x40080
	v_lshl_add_u64 v[174:175], v[176:177], 0, s[84:85]
	s_addc_u32 s7, s7, 0
	s_add_i32 s8, s48, s20
	global_load_lds_dwordx4 v[174:175], off
	v_lshl_add_u64 v[174:175], s[6:7], 0, v[182:183]
	s_mov_b32 m0, s8
	s_nop 0
	global_load_lds_dwordx4 v[174:175], off
	v_lshl_add_u64 v[174:175], s[6:7], 0, v[178:179]
	s_add_i32 m0, s8, 0x2000
	s_nop 0
	global_load_lds_dwordx4 v[174:175], off
	v_lshl_add_u64 v[174:175], v[210:211], 0, s[84:85]
	s_mov_b32 m0, s96
	s_nop 0
	global_load_lds_dwordx4 v[174:175], off
	v_lshl_add_u64 v[174:175], v[212:213], 0, s[84:85]
	s_mov_b32 m0, s97
	s_nop 0
	global_load_lds_dwordx4 v[174:175], off
	s_waitcnt vmcnt(8)
	s_waitcnt lgkmcnt(0)
	s_barrier
	s_waitcnt lgkmcnt(0)
	v_mfma_f32_16x16x32_bf16 v[70:73], v[122:125], v[162:165], v[70:73]
	v_mfma_f32_16x16x32_bf16 v[66:69], v[130:133], v[162:165], v[66:69]
	v_mfma_f32_16x16x32_bf16 v[62:65], v[122:125], v[170:173], v[62:65]
	v_mfma_f32_16x16x32_bf16 v[58:61], v[130:133], v[170:173], v[58:61]
	v_mfma_f32_16x16x32_bf16 v[54:57], v[122:125], v[194:197], v[54:57]
	v_mfma_f32_16x16x32_bf16 v[50:53], v[130:133], v[194:197], v[50:53]
	v_mfma_f32_16x16x32_bf16 v[46:49], v[122:125], v[202:205], v[46:49]
	v_mfma_f32_16x16x32_bf16 v[42:45], v[130:133], v[202:205], v[42:45]
	v_mfma_f32_16x16x32_bf16 v[70:73], v[126:129], v[166:169], v[70:73]
	v_mfma_f32_16x16x32_bf16 v[66:69], v[134:137], v[166:169], v[66:69]
	v_mfma_f32_16x16x32_bf16 v[62:65], v[126:129], v[190:193], v[62:65]
	v_mfma_f32_16x16x32_bf16 v[58:61], v[134:137], v[190:193], v[58:61]
	v_mfma_f32_16x16x32_bf16 v[54:57], v[126:129], v[198:201], v[54:57]
	v_mfma_f32_16x16x32_bf16 v[50:53], v[134:137], v[198:201], v[50:53]
	v_mfma_f32_16x16x32_bf16 v[46:49], v[126:129], v[206:209], v[46:49]
	v_mfma_f32_16x16x32_bf16 v[42:45], v[134:137], v[206:209], v[42:45]
	v_mfma_f32_16x16x32_bf16 v[30:33], v[138:141], v[162:165], v[30:33]
	v_mfma_f32_16x16x32_bf16 v[26:29], v[146:149], v[162:165], v[26:29]
	v_mfma_f32_16x16x32_bf16 v[22:25], v[138:141], v[170:173], v[22:25]
	v_mfma_f32_16x16x32_bf16 v[18:21], v[146:149], v[170:173], v[18:21]
	v_mfma_f32_16x16x32_bf16 v[14:17], v[138:141], v[194:197], v[14:17]
	v_mfma_f32_16x16x32_bf16 v[8:11], v[146:149], v[194:197], v[8:11]
	v_mfma_f32_16x16x32_bf16 v[4:7], v[138:141], v[202:205], v[4:7]
	v_mfma_f32_16x16x32_bf16 v[0:3], v[146:149], v[202:205], v[0:3]
	v_mfma_f32_16x16x32_bf16 v[30:33], v[142:145], v[166:169], v[30:33]
	v_mfma_f32_16x16x32_bf16 v[26:29], v[150:153], v[166:169], v[26:29]
	v_mfma_f32_16x16x32_bf16 v[22:25], v[142:145], v[190:193], v[22:25]
	v_mfma_f32_16x16x32_bf16 v[18:21], v[150:153], v[190:193], v[18:21]
	v_mfma_f32_16x16x32_bf16 v[14:17], v[142:145], v[198:201], v[14:17]
	v_mfma_f32_16x16x32_bf16 v[8:11], v[150:153], v[198:201], v[8:11]
	v_mfma_f32_16x16x32_bf16 v[4:7], v[142:145], v[206:209], v[4:7]
	v_mfma_f32_16x16x32_bf16 v[0:3], v[150:153], v[206:209], v[0:3]
	s_barrier
	s_add_i32 s46, s46, 2
	s_add_u32 s4, s4, 0x100
	s_addc_u32 s5, s5, 0
	s_add_u32 s44, s44, 0x100
	s_addc_u32 s45, s45, 0
	s_cmp_gt_u32 s46, 13
	s_cbranch_scc0 .LBB0_1112
	s_and_b64 vcc, exec, s[0:1]
	s_cbranch_vccz .LBB0_1115
	s_barrier

; #define PG8_STAGE(bufoff, gbase, voff) do { _Pragma("unroll") for (int _i = 0; _i < 2; ++_i) \
;         __builtin_amdgcn_global_load_lds((const unsigned*)((const char*)(gbase) + (voff)[_i]), (LAS unsigned*)(lds + (bufoff) + ldsw + _i * 8192), 16, 0, 0); } while (0)
; #define PG8_LDA(dst, b, h) do { _Pragma("unroll") for (int m = 0; m < 4; ++m) _Pragma("unroll") for (int k = 0; k < 2; ++k) dst[m][k] = *(const LAS bf16x8*)(lds + PG8_SA(b, h) + aoff + m * 2048 + k * 1024); } while (0)
; #define PG8_LDB(dst, b, h) do { _Pragma("unroll") for (int n = 0; n < 2; ++n) _Pragma("unroll") for (int k = 0; k < 2; ++k) dst[n][k] = *(const LAS bf16x8*)(lds + PG8_SB(b, h) + boff + n * 2048 + k * 1024); } while (0)
; #define PG8_MMA(ai, bj, At, Bt) do { __builtin_amdgcn_s_setprio(1); _Pragma("unroll") for (int m = 0; m < 4; ++m) _Pragma("unroll") for (int n = 0; n < 2; ++n) _Pragma("unroll") for (int k = 0; k < 2; ++k) \
;         acc[ai][bj][m][n] = __builtin_amdgcn_mfma_f32_16x16x32_bf16(Bt[n][k], At[m][k], acc[ai][bj][m][n], 0, 0, 0); __builtin_amdgcn_s_setprio(0); } while (0)
; #define PG8_WAIT_V(n) asm volatile("s_waitcnt vmcnt(" #n ")" ::: "memory")
; #define PG8_WAIT_L(n) asm volatile("s_waitcnt lgkmcnt(" #n ")" ::: "memory")
; #define PG8_BAR __builtin_amdgcn_s_barrier()
; #define PG8_SCHED __builtin_amdgcn_sched_barrier(0)
; template <class Epi>
; __device__ __forceinline__ void gemm_phase(LAS unsigned char* lds, const Gemm g, const StaticOrder& S, const Epi& E, int wave_s) {
;     ...
;             PG8_LDB(B0, 0, 0); PG8_LDB(B1, 0, 1); PG8_SCHED; PG8_LDA(At, 0, 0); PG8_STAGE(PG8_SA(1, 1), a1 + hstepA, voffA);
;             PG8_WAIT_V(8); PG8_WAIT_L(0); PG8_BAR; PG8_MMA(0, 0, At, B0); PG8_MMA(0, 1, At, B1); PG8_BAR; PG8_SCHED;
;             PG8_LDA(At, 0, 1); PG8_STAGE(PG8_SB(0, 0), b2, voffB); PG8_STAGE(PG8_SB(0, 1), b2 + hstepB, voffB); PG8_STAGE(PG8_SA(0, 0), a2, voffA);
;             PG8_WAIT_V(8); PG8_WAIT_L(0); PG8_BAR; PG8_MMA(1, 0, At, B0); PG8_MMA(1, 1, At, B1); PG8_BAR; PG8_SCHED;
;             PG8_LDB(B0, 1, 0); PG8_LDB(B1, 1, 1); PG8_SCHED; PG8_LDA(At, 1, 0); PG8_STAGE(PG8_SA(0, 1), a2 + hstepA, voffA);
.Lpp_lead_15:
	s_waitcnt lgkmcnt(4)
	s_barrier
	s_waitcnt lgkmcnt(4)
	v_mfma_f32_16x16x32_bf16 v[78:81], v[130:133], v[186:189], v[78:81]
	v_mfma_f32_16x16x32_bf16 v[106:109], v[138:141], v[186:189], v[106:109]
	v_mfma_f32_16x16x32_bf16 v[74:77], v[130:133], v[194:197], v[74:77]
	v_mfma_f32_16x16x32_bf16 v[98:101], v[138:141], v[194:197], v[98:101]
	v_mfma_f32_16x16x32_bf16 v[70:73], v[130:133], v[210:213], v[70:73]
	v_mfma_f32_16x16x32_bf16 v[86:89], v[138:141], v[210:213], v[86:89]
	v_mfma_f32_16x16x32_bf16 v[62:65], v[130:133], v[232:235], v[62:65]
	v_mfma_f32_16x16x32_bf16 v[122:125], v[138:141], v[232:235], v[122:125]
	v_mfma_f32_16x16x32_bf16 v[78:81], v[134:137], v[190:193], v[78:81]
	v_mfma_f32_16x16x32_bf16 v[106:109], v[142:145], v[190:193], v[106:109]
	v_mfma_f32_16x16x32_bf16 v[74:77], v[134:137], v[198:201], v[74:77]
	v_mfma_f32_16x16x32_bf16 v[98:101], v[142:145], v[198:201], v[98:101]
	v_mfma_f32_16x16x32_bf16 v[70:73], v[134:137], v[214:217], v[70:73]
	v_mfma_f32_16x16x32_bf16 v[86:89], v[142:145], v[214:217], v[86:89]
	v_mfma_f32_16x16x32_bf16 v[62:65], v[134:137], v[174:177], v[62:65]
	v_mfma_f32_16x16x32_bf16 v[122:125], v[142:145], v[174:177], v[122:125]
	s_waitcnt lgkmcnt(0)
	v_mfma_f32_16x16x32_bf16 v[102:105], v[146:149], v[186:189], v[102:105]
	v_mfma_f32_16x16x32_bf16 v[34:37], v[178:181], v[186:189], v[34:37]
	v_mfma_f32_16x16x32_bf16 v[94:97], v[146:149], v[194:197], v[94:97]
	v_mfma_f32_16x16x32_bf16 v[30:33], v[178:181], v[194:197], v[30:33]
	v_mfma_f32_16x16x32_bf16 v[90:93], v[146:149], v[210:213], v[90:93]
	v_mfma_f32_16x16x32_bf16 v[26:29], v[178:181], v[210:213], v[26:29]
	v_mfma_f32_16x16x32_bf16 v[82:85], v[146:149], v[232:235], v[82:85]
	v_mfma_f32_16x16x32_bf16 v[22:25], v[178:181], v[232:235], v[22:25]
	v_mfma_f32_16x16x32_bf16 v[102:105], v[170:173], v[190:193], v[102:105]
	v_mfma_f32_16x16x32_bf16 v[34:37], v[182:185], v[190:193], v[34:37]
	v_mfma_f32_16x16x32_bf16 v[94:97], v[170:173], v[198:201], v[94:97]
	v_mfma_f32_16x16x32_bf16 v[30:33], v[182:185], v[198:201], v[30:33]
	v_mfma_f32_16x16x32_bf16 v[90:93], v[170:173], v[214:217], v[90:93]
	v_mfma_f32_16x16x32_bf16 v[26:29], v[182:185], v[214:217], v[26:29]
	v_mfma_f32_16x16x32_bf16 v[82:85], v[170:173], v[174:177], v[82:85]
	v_mfma_f32_16x16x32_bf16 v[22:25], v[182:185], v[174:177], v[22:25]
	s_barrier
	s_add_i32 s54, s54, s65
	v_lshl_add_u64 v[164:165], s[8:9], 0, v[12:13]
	s_mov_b32 m0, s54
	ds_read_b128 v[174:177], v167 offset:16384
	ds_read_b128 v[186:189], v167 offset:17408
	ds_read_b128 v[190:193], v167 offset:18432
	ds_read_b128 v[194:197], v167 offset:19456
	ds_read_b128 v[198:201], v167 offset:20480
	ds_read_b128 v[210:213], v167 offset:21504
	ds_read_b128 v[214:217], v167 offset:22528
	ds_read_b128 v[232:235], v167 offset:23552
	global_load_lds_dwordx4 v[164:165], off
	s_add_i32 m0, s54, 0x2000
	s_add_u32 s58, s8, 0xb0000
	v_lshl_add_u64 v[202:203], s[8:9], 0, v[150:151]
	s_addc_u32 s59, s9, 0
	s_add_i32 s54, s70, s65
	global_load_lds_dwordx4 v[202:203], off
	v_lshl_add_u64 v[206:207], s[58:59], 0, v[12:13]
	s_mov_b32 m0, s54
	v_lshl_add_u64 v[218:219], vcc, 0, v[152:153]
	global_load_lds_dwordx4 v[206:207], off
	v_lshl_add_u64 v[206:207], s[58:59], 0, v[150:151]
	s_add_i32 m0, s54, 0x2000
	s_nop 0
	global_load_lds_dwordx4 v[206:207], off
	v_lshl_add_u64 v[206:207], vcc, 0, v[154:155]
	s_mov_b32 m0, s52
	s_nop 0
	global_load_lds_dwordx4 v[206:207], off
	s_mov_b32 m0, s53
	s_nop 0
	global_load_lds_dwordx4 v[218:219], off
	s_waitcnt vmcnt(8)
	s_waitcnt lgkmcnt(0)
	s_barrier
	s_waitcnt lgkmcnt(0)
	v_mfma_f32_16x16x32_bf16 v[58:61], v[130:133], v[174:177], v[58:61]
	v_mfma_f32_16x16x32_bf16 v[118:121], v[138:141], v[174:177], v[118:121]
	v_mfma_f32_16x16x32_bf16 v[54:57], v[130:133], v[190:193], v[54:57]
	v_mfma_f32_16x16x32_bf16 v[126:129], v[138:141], v[190:193], v[126:129]
	v_mfma_f32_16x16x32_bf16 v[50:53], v[130:133], v[198:201], v[50:53]
	v_mfma_f32_16x16x32_bf16 v[114:117], v[138:141], v[198:201], v[114:117]
	v_mfma_f32_16x16x32_bf16 v[46:49], v[130:133], v[214:217], v[46:49]
	v_mfma_f32_16x16x32_bf16 v[110:113], v[138:141], v[214:217], v[110:113]
	v_mfma_f32_16x16x32_bf16 v[58:61], v[134:137], v[186:189], v[58:61]
	v_mfma_f32_16x16x32_bf16 v[118:121], v[142:145], v[186:189], v[118:121]
	v_mfma_f32_16x16x32_bf16 v[54:57], v[134:137], v[194:197], v[54:57]
	v_mfma_f32_16x16x32_bf16 v[126:129], v[142:145], v[194:197], v[126:129]
	v_mfma_f32_16x16x32_bf16 v[50:53], v[134:137], v[210:213], v[50:53]
	v_mfma_f32_16x16x32_bf16 v[114:117], v[142:145], v[210:213], v[114:117]
	v_mfma_f32_16x16x32_bf16 v[46:49], v[134:137], v[232:235], v[46:49]
	v_mfma_f32_16x16x32_bf16 v[110:113], v[142:145], v[232:235], v[110:113]
	v_mfma_f32_16x16x32_bf16 v[66:69], v[146:149], v[174:177], v[66:69]
	v_mfma_f32_16x16x32_bf16 v[14:17], v[178:181], v[174:177], v[14:17]
	v_mfma_f32_16x16x32_bf16 v[42:45], v[146:149], v[190:193], v[42:45]
	v_mfma_f32_16x16x32_bf16 v[8:11], v[178:181], v[190:193], v[8:11]
	v_mfma_f32_16x16x32_bf16 v[38:41], v[146:149], v[198:201], v[38:41]
	v_mfma_f32_16x16x32_bf16 v[4:7], v[178:181], v[198:201], v[4:7]
	v_mfma_f32_16x16x32_bf16 v[18:21], v[146:149], v[214:217], v[18:21]
	v_mfma_f32_16x16x32_bf16 v[0:3], v[178:181], v[214:217], v[0:3]
	v_mfma_f32_16x16x32_bf16 v[66:69], v[170:173], v[186:189], v[66:69]
	v_mfma_f32_16x16x32_bf16 v[14:17], v[182:185], v[186:189], v[14:17]
	v_mfma_f32_16x16x32_bf16 v[42:45], v[170:173], v[194:197], v[42:45]
	v_mfma_f32_16x16x32_bf16 v[8:11], v[182:185], v[194:197], v[8:11]
	v_mfma_f32_16x16x32_bf16 v[38:41], v[170:173], v[210:213], v[38:41]
	v_mfma_f32_16x16x32_bf16 v[4:7], v[182:185], v[210:213], v[4:7]
	v_mfma_f32_16x16x32_bf16 v[18:21], v[170:173], v[232:235], v[18:21]
	v_mfma_f32_16x16x32_bf16 v[0:3], v[182:185], v[232:235], v[0:3]
	s_barrier
	s_add_i32 s54, 0, 0x18000
	s_add_i32 s70, 0, 0x1c000
	v_add_u32_e32 v142, s54, v209
	v_add_u32_e32 v169, s70, v209
	ds_read_b128 v[130:133], v142
	ds_read_b128 v[134:137], v142 offset:1024
	ds_read_b128 v[138:141], v142 offset:2048
	ds_read_b128 v[142:145], v142 offset:3072
	ds_read_b128 v[182:185], v167 offset:32768
	ds_read_b128 v[186:189], v167 offset:33792
	ds_read_b128 v[190:193], v167 offset:34816
	ds_read_b128 v[194:197], v167 offset:35840
	ds_read_b128 v[198:201], v167 offset:36864
	ds_read_b128 v[210:213], v167 offset:37888
	ds_read_b128 v[214:217], v167 offset:38912
	ds_read_b128 v[232:235], v167 offset:39936
	ds_read_b128 v[146:149], v169
	ds_read_b128 v[170:173], v169 offset:1024
	ds_read_b128 v[174:177], v169 offset:2048
	ds_read_b128 v[178:181], v169 offset:3072
	s_add_u32 s58, vcc_lo, 0xb0000
	s_addc_u32 s59, vcc_hi, 0
	s_mov_b32 m0, s35
	v_lshl_add_u64 v[224:225], s[58:59], 0, v[154:155]
	global_load_lds_dwordx4 v[224:225], off
	v_lshl_add_u64 v[224:225], s[58:59], 0, v[152:153]
	s_mov_b32 m0, s18
	s_nop 0
	global_load_lds_dwordx4 v[224:225], off
	s_waitcnt vmcnt(8)
	s_cmp_lg_u64 s[26:27], 0
	s_cbranch_scc1 .Lpp_lead_16
	s_waitcnt lgkmcnt(0)
; #define PG8_STAGE(bufoff, gbase, voff) do { _Pragma("unroll") for (int _i = 0; _i < 2; ++_i) \
;         __builtin_amdgcn_global_load_lds((const unsigned*)((const char*)(gbase) + (voff)[_i]), (LAS unsigned*)(lds + (bufoff) + ldsw + _i * 8192), 16, 0, 0); } while (0)
; #define PG8_LDA(dst, b, h) do { _Pragma("unroll") for (int m = 0; m < 4; ++m) _Pragma("unroll") for (int k = 0; k < 2; ++k) dst[m][k] = *(const LAS bf16x8*)(lds + PG8_SA(b, h) + aoff + m * 2048 + k * 1024); } while (0)
; #define PG8_LDB(dst, b, h) do { _Pragma("unroll") for (int n = 0; n < 2; ++n) _Pragma("unroll") for (int k = 0; k < 2; ++k) dst[n][k] = *(const LAS bf16x8*)(lds + PG8_SB(b, h) + boff + n * 2048 + k * 1024); } while (0)
; #define PG8_MMA(ai, bj, At, Bt) do { __builtin_amdgcn_s_setprio(1); _Pragma("unroll") for (int m = 0; m < 4; ++m) _Pragma("unroll") for (int n = 0; n < 2; ++n) _Pragma("unroll") for (int k = 0; k < 2; ++k) \
;         acc[ai][bj][m][n] = __builtin_amdgcn_mfma_f32_16x16x32_bf16(Bt[n][k], At[m][k], acc[ai][bj][m][n], 0, 0, 0); __builtin_amdgcn_s_setprio(0); } while (0)
; #define PG8_WAIT_V(n) asm volatile("s_waitcnt vmcnt(" #n ")" ::: "memory")
; #define PG8_WAIT_L(n) asm volatile("s_waitcnt lgkmcnt(" #n ")" ::: "memory")
; #define PG8_BAR __builtin_amdgcn_s_barrier()
; #define PG8_SCHED __builtin_amdgcn_sched_barrier(0)
; template <class Epi>
; __device__ __forceinline__ void gemm_phase(LAS unsigned char* lds, const Gemm g, const StaticOrder& S, const Epi& E, int wave_s) {
;     ...
;             PG8_LDB(B0, 1, 0); PG8_LDB(B1, 1, 1); PG8_SCHED; PG8_LDA(At, 1, 0); PG8_STAGE(PG8_SA(0, 1), a2 + hstepA, voffA);
;             PG8_WAIT_V(8); PG8_WAIT_L(0); PG8_BAR; PG8_MMA(0, 0, At, B0); PG8_MMA(0, 1, At, B1); PG8_BAR; PG8_SCHED;
;             PG8_LDA(At, 1, 1); PG8_STAGE(PG8_SB(1, 0), b3, voffB); PG8_STAGE(PG8_SB(1, 1), b3 + hstepB, voffB); PG8_STAGE(PG8_SA(1, 0), a3, voffA);
;             PG8_WAIT_V(8); PG8_WAIT_L(0); PG8_BAR; PG8_MMA(1, 0, At, B0); PG8_MMA(1, 1, At, B1); PG8_BAR; PG8_SCHED;
;         }
;         if (wr == 0) PG8_BAR;
.Lpp_lead_16:
	s_waitcnt lgkmcnt(4)
	s_barrier
	s_waitcnt lgkmcnt(4)
	v_mfma_f32_16x16x32_bf16 v[78:81], v[130:133], v[182:185], v[78:81]
	v_mfma_f32_16x16x32_bf16 v[106:109], v[138:141], v[182:185], v[106:109]
	v_mfma_f32_16x16x32_bf16 v[74:77], v[130:133], v[190:193], v[74:77]
	v_mfma_f32_16x16x32_bf16 v[98:101], v[138:141], v[190:193], v[98:101]
	v_mfma_f32_16x16x32_bf16 v[70:73], v[130:133], v[198:201], v[70:73]
	v_mfma_f32_16x16x32_bf16 v[86:89], v[138:141], v[198:201], v[86:89]
	v_mfma_f32_16x16x32_bf16 v[62:65], v[130:133], v[214:217], v[62:65]
	v_mfma_f32_16x16x32_bf16 v[122:125], v[138:141], v[214:217], v[122:125]
	v_mfma_f32_16x16x32_bf16 v[78:81], v[134:137], v[186:189], v[78:81]
	v_mfma_f32_16x16x32_bf16 v[106:109], v[142:145], v[186:189], v[106:109]
	v_mfma_f32_16x16x32_bf16 v[74:77], v[134:137], v[194:197], v[74:77]
	v_mfma_f32_16x16x32_bf16 v[98:101], v[142:145], v[194:197], v[98:101]
	v_mfma_f32_16x16x32_bf16 v[70:73], v[134:137], v[210:213], v[70:73]
	v_mfma_f32_16x16x32_bf16 v[86:89], v[142:145], v[210:213], v[86:89]
	v_mfma_f32_16x16x32_bf16 v[62:65], v[134:137], v[232:235], v[62:65]
	v_mfma_f32_16x16x32_bf16 v[122:125], v[142:145], v[232:235], v[122:125]
	s_waitcnt lgkmcnt(0)
	v_mfma_f32_16x16x32_bf16 v[102:105], v[146:149], v[182:185], v[102:105]
	v_mfma_f32_16x16x32_bf16 v[34:37], v[174:177], v[182:185], v[34:37]
	v_mfma_f32_16x16x32_bf16 v[94:97], v[146:149], v[190:193], v[94:97]
	v_mfma_f32_16x16x32_bf16 v[30:33], v[174:177], v[190:193], v[30:33]
	v_mfma_f32_16x16x32_bf16 v[90:93], v[146:149], v[198:201], v[90:93]
	v_mfma_f32_16x16x32_bf16 v[26:29], v[174:177], v[198:201], v[26:29]
	v_mfma_f32_16x16x32_bf16 v[82:85], v[146:149], v[214:217], v[82:85]
	v_mfma_f32_16x16x32_bf16 v[22:25], v[174:177], v[214:217], v[22:25]
	v_mfma_f32_16x16x32_bf16 v[102:105], v[170:173], v[186:189], v[102:105]
	v_mfma_f32_16x16x32_bf16 v[34:37], v[178:181], v[186:189], v[34:37]
	v_mfma_f32_16x16x32_bf16 v[94:97], v[170:173], v[194:197], v[94:97]
	v_mfma_f32_16x16x32_bf16 v[30:33], v[178:181], v[194:197], v[30:33]
	v_mfma_f32_16x16x32_bf16 v[90:93], v[170:173], v[210:213], v[90:93]
	v_mfma_f32_16x16x32_bf16 v[26:29], v[178:181], v[210:213], v[26:29]
	v_mfma_f32_16x16x32_bf16 v[82:85], v[170:173], v[232:235], v[82:85]
	v_mfma_f32_16x16x32_bf16 v[22:25], v[178:181], v[232:235], v[22:25]
	s_barrier
	s_add_i32 s54, s54, s65
	v_lshl_add_u64 v[164:165], v[164:165], 0, s[84:85]
	s_mov_b32 m0, s54
	ds_read_b128 v[182:185], v167 offset:49152
	ds_read_b128 v[186:189], v167 offset:50176
	ds_read_b128 v[190:193], v167 offset:51200
	ds_read_b128 v[194:197], v167 offset:52224
	ds_read_b128 v[198:201], v167 offset:53248
	ds_read_b128 v[210:213], v167 offset:54272
	ds_read_b128 v[214:217], v167 offset:55296
	ds_read_b128 v[232:235], v167 offset:56320
	global_load_lds_dwordx4 v[164:165], off
	s_add_i32 m0, s54, 0x2000
	s_add_u32 s8, s8, 0xb0080
	v_lshl_add_u64 v[164:165], v[202:203], 0, s[84:85]
	s_addc_u32 s9, s9, 0
	s_add_i32 s54, s70, s65
	global_load_lds_dwordx4 v[164:165], off
	v_lshl_add_u64 v[164:165], s[8:9], 0, v[12:13]
	s_mov_b32 m0, s54
	s_nop 0
	global_load_lds_dwordx4 v[164:165], off
	v_lshl_add_u64 v[164:165], s[8:9], 0, v[150:151]
	s_add_i32 m0, s54, 0x2000
	s_nop 0
	global_load_lds_dwordx4 v[164:165], off
	v_lshl_add_u64 v[164:165], v[206:207], 0, s[84:85]
	s_mov_b32 m0, s45
	s_nop 0
	global_load_lds_dwordx4 v[164:165], off
	v_lshl_add_u64 v[164:165], v[218:219], 0, s[84:85]
	s_mov_b32 m0, s46
	s_nop 0
	global_load_lds_dwordx4 v[164:165], off
	s_waitcnt vmcnt(8)
	s_waitcnt lgkmcnt(0)
	s_barrier
	s_waitcnt lgkmcnt(0)
	v_mfma_f32_16x16x32_bf16 v[58:61], v[130:133], v[182:185], v[58:61]
	v_mfma_f32_16x16x32_bf16 v[118:121], v[138:141], v[182:185], v[118:121]
	v_mfma_f32_16x16x32_bf16 v[54:57], v[130:133], v[190:193], v[54:57]
	v_mfma_f32_16x16x32_bf16 v[126:129], v[138:141], v[190:193], v[126:129]
	v_mfma_f32_16x16x32_bf16 v[50:53], v[130:133], v[198:201], v[50:53]
	v_mfma_f32_16x16x32_bf16 v[114:117], v[138:141], v[198:201], v[114:117]
	v_mfma_f32_16x16x32_bf16 v[46:49], v[130:133], v[214:217], v[46:49]
	v_mfma_f32_16x16x32_bf16 v[110:113], v[138:141], v[214:217], v[110:113]
	v_mfma_f32_16x16x32_bf16 v[58:61], v[134:137], v[186:189], v[58:61]
	v_mfma_f32_16x16x32_bf16 v[118:121], v[142:145], v[186:189], v[118:121]
	v_mfma_f32_16x16x32_bf16 v[54:57], v[134:137], v[194:197], v[54:57]
	v_mfma_f32_16x16x32_bf16 v[126:129], v[142:145], v[194:197], v[126:129]
	v_mfma_f32_16x16x32_bf16 v[50:53], v[134:137], v[210:213], v[50:53]
	v_mfma_f32_16x16x32_bf16 v[114:117], v[142:145], v[210:213], v[114:117]
	v_mfma_f32_16x16x32_bf16 v[46:49], v[134:137], v[232:235], v[46:49]
	v_mfma_f32_16x16x32_bf16 v[110:113], v[142:145], v[232:235], v[110:113]
	v_mfma_f32_16x16x32_bf16 v[66:69], v[146:149], v[182:185], v[66:69]
	v_mfma_f32_16x16x32_bf16 v[14:17], v[174:177], v[182:185], v[14:17]
	v_mfma_f32_16x16x32_bf16 v[42:45], v[146:149], v[190:193], v[42:45]
	v_mfma_f32_16x16x32_bf16 v[8:11], v[174:177], v[190:193], v[8:11]
	v_mfma_f32_16x16x32_bf16 v[38:41], v[146:149], v[198:201], v[38:41]
	v_mfma_f32_16x16x32_bf16 v[4:7], v[174:177], v[198:201], v[4:7]
	v_mfma_f32_16x16x32_bf16 v[18:21], v[146:149], v[214:217], v[18:21]
	v_mfma_f32_16x16x32_bf16 v[0:3], v[174:177], v[214:217], v[0:3]
	v_mfma_f32_16x16x32_bf16 v[66:69], v[170:173], v[186:189], v[66:69]
	v_mfma_f32_16x16x32_bf16 v[14:17], v[178:181], v[186:189], v[14:17]
	v_mfma_f32_16x16x32_bf16 v[42:45], v[170:173], v[194:197], v[42:45]
	v_mfma_f32_16x16x32_bf16 v[8:11], v[178:181], v[194:197], v[8:11]
	v_mfma_f32_16x16x32_bf16 v[38:41], v[170:173], v[210:213], v[38:41]
	v_mfma_f32_16x16x32_bf16 v[4:7], v[178:181], v[210:213], v[4:7]
	v_mfma_f32_16x16x32_bf16 v[18:21], v[170:173], v[232:235], v[18:21]
	v_mfma_f32_16x16x32_bf16 v[0:3], v[178:181], v[232:235], v[0:3]
	s_barrier
	s_add_i32 s51, s51, 2
	s_add_u32 s49, s49, 0x100
	s_addc_u32 s50, s50, 0
	s_cmp_gt_u32 s51, 41
	s_mov_b64 s[94:95], s[6:7]
	s_cbranch_scc0 .LBB0_1188
	s_and_b64 vcc, exec, s[26:27]
	s_cbranch_vccz .LBB0_1191
	s_barrier
